# saddr-form LDS-DMA in all GEMM K-loops (drops 64-bit VALU address adds)
# speedup vs baseline: 1.0045x; 1.0045x over previous
.LBB0_422:
	ds_read_b128 v[146:149], v154
	ds_read_b128 v[158:161], v154 offset:1024
	ds_read_b128 v[162:165], v154 offset:2048
	ds_read_b128 v[166:169], v154 offset:3072
	ds_read_b128 v[170:173], v155
	ds_read_b128 v[178:181], v155 offset:1024
	ds_read_b128 v[182:185], v155 offset:2048
	ds_read_b128 v[186:189], v155 offset:3072
	s_add_u32 s30, s28, 0xfc000
	s_addc_u32 s31, s29, 0
	s_cmp_eq_u32 s53, 60
	s_cselect_b32 s36, s21, s30
	s_cselect_b32 s37, s9, s31
	s_cselect_b32 s34, s50, s51
	s_cselect_b32 s35, s19, s52
	s_add_u32 s30, s36, 0x100000
	s_addc_u32 s31, s37, 0
	s_add_i32 m0, s1, 0xc000
	ds_read_b128 v[190:193], v156
	ds_read_b128 v[194:197], v156 offset:1024
	ds_read_b128 v[198:201], v156 offset:2048
	ds_read_b128 v[202:205], v156 offset:3072
	ds_read_b128 v[206:209], v156 offset:4096
	ds_read_b128 v[210:213], v156 offset:5120
	ds_read_b128 v[214:217], v156 offset:6144
	ds_read_b128 v[218:221], v156 offset:7168
	global_load_lds_dwordx4 v138, s[28:29]
	s_add_i32 m0, s1, 0xe000
	s_nop 0
	global_load_lds_dwordx4 v140, s[28:29]
	s_waitcnt vmcnt(8)
	s_waitcnt lgkmcnt(0)
	s_barrier
	s_setprio 1
	s_waitcnt lgkmcnt(0)
	v_mfma_f32_16x16x32_bf16 v[126:129], v[146:149], v[190:193], v[126:129]
	v_mfma_f32_16x16x32_bf16 v[122:125], v[162:165], v[190:193], v[122:125]
	v_mfma_f32_16x16x32_bf16 v[110:113], v[146:149], v[198:201], v[110:113]
	v_mfma_f32_16x16x32_bf16 v[106:109], v[162:165], v[198:201], v[106:109]
	v_mfma_f32_16x16x32_bf16 v[94:97], v[146:149], v[206:209], v[94:97]
	v_mfma_f32_16x16x32_bf16 v[90:93], v[162:165], v[206:209], v[90:93]
	v_mfma_f32_16x16x32_bf16 v[78:81], v[146:149], v[214:217], v[78:81]
	v_mfma_f32_16x16x32_bf16 v[74:77], v[162:165], v[214:217], v[74:77]
	v_mfma_f32_16x16x32_bf16 v[126:129], v[158:161], v[194:197], v[126:129]
	v_mfma_f32_16x16x32_bf16 v[122:125], v[166:169], v[194:197], v[122:125]
	v_mfma_f32_16x16x32_bf16 v[110:113], v[158:161], v[202:205], v[110:113]
	v_mfma_f32_16x16x32_bf16 v[106:109], v[166:169], v[202:205], v[106:109]
	v_mfma_f32_16x16x32_bf16 v[94:97], v[158:161], v[210:213], v[94:97]
	v_mfma_f32_16x16x32_bf16 v[90:93], v[166:169], v[210:213], v[90:93]
	v_mfma_f32_16x16x32_bf16 v[78:81], v[158:161], v[218:221], v[78:81]
	v_mfma_f32_16x16x32_bf16 v[74:77], v[166:169], v[218:221], v[74:77]
	s_setprio 0
	s_setprio 1
	v_mfma_f32_16x16x32_bf16 v[118:121], v[170:173], v[190:193], v[118:121]
	v_mfma_f32_16x16x32_bf16 v[114:117], v[182:185], v[190:193], v[114:117]
	v_mfma_f32_16x16x32_bf16 v[102:105], v[170:173], v[198:201], v[102:105]
	v_mfma_f32_16x16x32_bf16 v[98:101], v[182:185], v[198:201], v[98:101]
	v_mfma_f32_16x16x32_bf16 v[86:89], v[170:173], v[206:209], v[86:89]
	v_mfma_f32_16x16x32_bf16 v[82:85], v[182:185], v[206:209], v[82:85]
	v_mfma_f32_16x16x32_bf16 v[70:73], v[170:173], v[214:217], v[70:73]
	v_mfma_f32_16x16x32_bf16 v[66:69], v[182:185], v[214:217], v[66:69]
	v_mfma_f32_16x16x32_bf16 v[118:121], v[178:181], v[194:197], v[118:121]
	v_mfma_f32_16x16x32_bf16 v[114:117], v[186:189], v[194:197], v[114:117]
	v_mfma_f32_16x16x32_bf16 v[102:105], v[178:181], v[202:205], v[102:105]
	v_mfma_f32_16x16x32_bf16 v[98:101], v[186:189], v[202:205], v[98:101]
	v_mfma_f32_16x16x32_bf16 v[86:89], v[178:181], v[210:213], v[86:89]
	v_mfma_f32_16x16x32_bf16 v[82:85], v[186:189], v[210:213], v[82:85]
	v_mfma_f32_16x16x32_bf16 v[70:73], v[178:181], v[218:221], v[70:73]
	v_mfma_f32_16x16x32_bf16 v[66:69], v[186:189], v[218:221], v[66:69]
	s_setprio 0
	s_barrier
	s_add_i32 s54, s48, s0
	s_mov_b32 m0, s54
	ds_read_b128 v[190:193], v156 offset:16384
	ds_read_b128 v[194:197], v156 offset:17408
	ds_read_b128 v[198:201], v156 offset:18432
	ds_read_b128 v[202:205], v156 offset:19456
	ds_read_b128 v[206:209], v156 offset:20480
	ds_read_b128 v[210:213], v156 offset:21504
	ds_read_b128 v[214:217], v156 offset:22528
	ds_read_b128 v[218:221], v156 offset:23552
	global_load_lds_dwordx4 v132, s[34:35]
	s_add_i32 m0, s54, 0x2000
	s_add_u32 s54, s34, 0x4000
	s_addc_u32 s55, s35, 0
	s_add_i32 s56, s49, s0
	global_load_lds_dwordx4 v136, s[34:35]
	s_mov_b32 m0, s56
	s_nop 0
	global_load_lds_dwordx4 v132, s[54:55]
	s_add_i32 m0, s56, 0x2000
	s_nop 0
	global_load_lds_dwordx4 v136, s[54:55]
	s_mov_b32 m0, s1
	s_nop 0
	global_load_lds_dwordx4 v130, s[36:37]
	s_mov_b32 m0, s27
	s_nop 0
	global_load_lds_dwordx4 v134, s[36:37]
	s_waitcnt vmcnt(8)
	s_waitcnt lgkmcnt(0)
	s_barrier
	s_setprio 1
	s_waitcnt lgkmcnt(0)
	v_mfma_f32_16x16x32_bf16 v[62:65], v[146:149], v[190:193], v[62:65]
	v_mfma_f32_16x16x32_bf16 v[58:61], v[162:165], v[190:193], v[58:61]
	v_mfma_f32_16x16x32_bf16 v[46:49], v[146:149], v[198:201], v[46:49]
	v_mfma_f32_16x16x32_bf16 v[42:45], v[162:165], v[198:201], v[42:45]
	v_mfma_f32_16x16x32_bf16 v[30:33], v[146:149], v[206:209], v[30:33]
	v_mfma_f32_16x16x32_bf16 v[26:29], v[162:165], v[206:209], v[26:29]
	v_mfma_f32_16x16x32_bf16 v[14:17], v[146:149], v[214:217], v[14:17]
	v_mfma_f32_16x16x32_bf16 v[10:13], v[162:165], v[214:217], v[10:13]
	v_mfma_f32_16x16x32_bf16 v[62:65], v[158:161], v[194:197], v[62:65]
	v_mfma_f32_16x16x32_bf16 v[58:61], v[166:169], v[194:197], v[58:61]
	v_mfma_f32_16x16x32_bf16 v[46:49], v[158:161], v[202:205], v[46:49]
	v_mfma_f32_16x16x32_bf16 v[42:45], v[166:169], v[202:205], v[42:45]
	v_mfma_f32_16x16x32_bf16 v[30:33], v[158:161], v[210:213], v[30:33]
	v_mfma_f32_16x16x32_bf16 v[26:29], v[166:169], v[210:213], v[26:29]
	v_mfma_f32_16x16x32_bf16 v[14:17], v[158:161], v[218:221], v[14:17]
	v_mfma_f32_16x16x32_bf16 v[10:13], v[166:169], v[218:221], v[10:13]
	s_setprio 0
	s_setprio 1
	v_mfma_f32_16x16x32_bf16 v[54:57], v[170:173], v[190:193], v[54:57]
	v_mfma_f32_16x16x32_bf16 v[50:53], v[182:185], v[190:193], v[50:53]
	v_mfma_f32_16x16x32_bf16 v[38:41], v[170:173], v[198:201], v[38:41]
	v_mfma_f32_16x16x32_bf16 v[34:37], v[182:185], v[198:201], v[34:37]
	v_mfma_f32_16x16x32_bf16 v[22:25], v[170:173], v[206:209], v[22:25]
	v_mfma_f32_16x16x32_bf16 v[18:21], v[182:185], v[206:209], v[18:21]
	v_mfma_f32_16x16x32_bf16 v[6:9], v[170:173], v[214:217], v[6:9]
	v_mfma_f32_16x16x32_bf16 v[2:5], v[182:185], v[214:217], v[2:5]
	v_mfma_f32_16x16x32_bf16 v[54:57], v[178:181], v[194:197], v[54:57]
	v_mfma_f32_16x16x32_bf16 v[50:53], v[186:189], v[194:197], v[50:53]
	v_mfma_f32_16x16x32_bf16 v[38:41], v[178:181], v[202:205], v[38:41]
	v_mfma_f32_16x16x32_bf16 v[34:37], v[186:189], v[202:205], v[34:37]
	v_mfma_f32_16x16x32_bf16 v[22:25], v[178:181], v[210:213], v[22:25]
	v_mfma_f32_16x16x32_bf16 v[18:21], v[186:189], v[210:213], v[18:21]
	v_mfma_f32_16x16x32_bf16 v[6:9], v[178:181], v[218:221], v[6:9]
	v_mfma_f32_16x16x32_bf16 v[2:5], v[186:189], v[218:221], v[2:5]
	s_setprio 0
	s_barrier
	s_add_i32 s54, 0, 0x18000
	v_add_u32_e32 v150, s54, v153
	s_add_i32 s55, 0, 0x1c000
	ds_read_b128 v[146:149], v150
	ds_read_b128 v[158:161], v150 offset:1024
	ds_read_b128 v[162:165], v150 offset:2048
	ds_read_b128 v[166:169], v150 offset:3072
	v_add_u32_e32 v150, s55, v153
	ds_read_b128 v[170:173], v150
	ds_read_b128 v[178:181], v150 offset:1024
	ds_read_b128 v[182:185], v150 offset:2048
	ds_read_b128 v[186:189], v150 offset:3072
	s_add_u32 s36, s36, 0x4000
	s_addc_u32 s37, s37, 0
	s_mov_b32 m0, s33
	ds_read_b128 v[190:193], v156 offset:32768
	ds_read_b128 v[194:197], v156 offset:33792
	ds_read_b128 v[198:201], v156 offset:34816
	ds_read_b128 v[202:205], v156 offset:35840
	ds_read_b128 v[206:209], v156 offset:36864
	ds_read_b128 v[210:213], v156 offset:37888
	ds_read_b128 v[214:217], v156 offset:38912
	ds_read_b128 v[218:221], v156 offset:39936
	global_load_lds_dwordx4 v130, s[36:37]
	s_mov_b32 m0, s38
	s_nop 0
	global_load_lds_dwordx4 v134, s[36:37]
	s_waitcnt vmcnt(8)
	s_waitcnt lgkmcnt(0)
	s_barrier
	s_setprio 1
	s_waitcnt lgkmcnt(0)
	v_mfma_f32_16x16x32_bf16 v[126:129], v[146:149], v[190:193], v[126:129]
	v_mfma_f32_16x16x32_bf16 v[122:125], v[162:165], v[190:193], v[122:125]
	v_mfma_f32_16x16x32_bf16 v[110:113], v[146:149], v[198:201], v[110:113]
	v_mfma_f32_16x16x32_bf16 v[106:109], v[162:165], v[198:201], v[106:109]
	v_mfma_f32_16x16x32_bf16 v[94:97], v[146:149], v[206:209], v[94:97]
	v_mfma_f32_16x16x32_bf16 v[90:93], v[162:165], v[206:209], v[90:93]
	v_mfma_f32_16x16x32_bf16 v[78:81], v[146:149], v[214:217], v[78:81]
	v_mfma_f32_16x16x32_bf16 v[74:77], v[162:165], v[214:217], v[74:77]
	v_mfma_f32_16x16x32_bf16 v[126:129], v[158:161], v[194:197], v[126:129]
	v_mfma_f32_16x16x32_bf16 v[122:125], v[166:169], v[194:197], v[122:125]
	v_mfma_f32_16x16x32_bf16 v[110:113], v[158:161], v[202:205], v[110:113]
	v_mfma_f32_16x16x32_bf16 v[106:109], v[166:169], v[202:205], v[106:109]
	v_mfma_f32_16x16x32_bf16 v[94:97], v[158:161], v[210:213], v[94:97]
	v_mfma_f32_16x16x32_bf16 v[90:93], v[166:169], v[210:213], v[90:93]
	v_mfma_f32_16x16x32_bf16 v[78:81], v[158:161], v[218:221], v[78:81]
	v_mfma_f32_16x16x32_bf16 v[74:77], v[166:169], v[218:221], v[74:77]
	s_setprio 0
	s_setprio 1
	v_mfma_f32_16x16x32_bf16 v[118:121], v[170:173], v[190:193], v[118:121]
	v_mfma_f32_16x16x32_bf16 v[114:117], v[182:185], v[190:193], v[114:117]
	v_mfma_f32_16x16x32_bf16 v[102:105], v[170:173], v[198:201], v[102:105]
	v_mfma_f32_16x16x32_bf16 v[98:101], v[182:185], v[198:201], v[98:101]
	v_mfma_f32_16x16x32_bf16 v[86:89], v[170:173], v[206:209], v[86:89]
	v_mfma_f32_16x16x32_bf16 v[82:85], v[182:185], v[206:209], v[82:85]
	v_mfma_f32_16x16x32_bf16 v[70:73], v[170:173], v[214:217], v[70:73]
	v_mfma_f32_16x16x32_bf16 v[66:69], v[182:185], v[214:217], v[66:69]
	v_mfma_f32_16x16x32_bf16 v[118:121], v[178:181], v[194:197], v[118:121]
	v_mfma_f32_16x16x32_bf16 v[114:117], v[186:189], v[194:197], v[114:117]
	v_mfma_f32_16x16x32_bf16 v[102:105], v[178:181], v[202:205], v[102:105]
	v_mfma_f32_16x16x32_bf16 v[98:101], v[186:189], v[202:205], v[98:101]
	v_mfma_f32_16x16x32_bf16 v[86:89], v[178:181], v[210:213], v[86:89]
	v_mfma_f32_16x16x32_bf16 v[82:85], v[186:189], v[210:213], v[82:85]
	v_mfma_f32_16x16x32_bf16 v[70:73], v[178:181], v[218:221], v[70:73]
	v_mfma_f32_16x16x32_bf16 v[66:69], v[186:189], v[218:221], v[66:69]
	s_setprio 0
	s_barrier
	s_add_u32 s36, s34, 0x380000
	s_addc_u32 s37, s35, 0
	s_add_i32 s54, s54, s0
	s_mov_b32 m0, s54
	ds_read_b128 v[190:193], v156 offset:49152
	ds_read_b128 v[194:197], v156 offset:50176
	ds_read_b128 v[198:201], v156 offset:51200
	ds_read_b128 v[202:205], v156 offset:52224
	ds_read_b128 v[206:209], v156 offset:53248
	ds_read_b128 v[210:213], v156 offset:54272
	ds_read_b128 v[214:217], v156 offset:55296
	ds_read_b128 v[218:221], v156 offset:56320
	global_load_lds_dwordx4 v132, s[36:37]
	s_add_i32 m0, s54, 0x2000
	s_add_u32 s34, s34, 0x384000
	s_addc_u32 s35, s35, 0
	global_load_lds_dwordx4 v136, s[36:37]
	s_add_i32 s36, s55, s0
	s_mov_b32 m0, s36
	s_nop 0
	global_load_lds_dwordx4 v132, s[34:35]
	s_add_i32 m0, s36, 0x2000
	s_nop 0
	global_load_lds_dwordx4 v136, s[34:35]
	s_mov_b32 m0, s44
	s_nop 0
	global_load_lds_dwordx4 v130, s[30:31]
	s_mov_b32 m0, s45
	s_nop 0
	global_load_lds_dwordx4 v134, s[30:31]
	s_waitcnt vmcnt(8)
	s_waitcnt lgkmcnt(0)
	s_barrier
	s_setprio 1
	s_waitcnt lgkmcnt(0)
	v_mfma_f32_16x16x32_bf16 v[62:65], v[146:149], v[190:193], v[62:65]
	v_mfma_f32_16x16x32_bf16 v[58:61], v[162:165], v[190:193], v[58:61]
	v_mfma_f32_16x16x32_bf16 v[46:49], v[146:149], v[198:201], v[46:49]
	v_mfma_f32_16x16x32_bf16 v[42:45], v[162:165], v[198:201], v[42:45]
	v_mfma_f32_16x16x32_bf16 v[30:33], v[146:149], v[206:209], v[30:33]
	v_mfma_f32_16x16x32_bf16 v[26:29], v[162:165], v[206:209], v[26:29]
	v_mfma_f32_16x16x32_bf16 v[14:17], v[146:149], v[214:217], v[14:17]
	v_mfma_f32_16x16x32_bf16 v[10:13], v[162:165], v[214:217], v[10:13]
	v_mfma_f32_16x16x32_bf16 v[62:65], v[158:161], v[194:197], v[62:65]
	v_mfma_f32_16x16x32_bf16 v[58:61], v[166:169], v[194:197], v[58:61]
	v_mfma_f32_16x16x32_bf16 v[46:49], v[158:161], v[202:205], v[46:49]
	v_mfma_f32_16x16x32_bf16 v[42:45], v[166:169], v[202:205], v[42:45]
	v_mfma_f32_16x16x32_bf16 v[30:33], v[158:161], v[210:213], v[30:33]
	v_mfma_f32_16x16x32_bf16 v[26:29], v[166:169], v[210:213], v[26:29]
	v_mfma_f32_16x16x32_bf16 v[14:17], v[158:161], v[218:221], v[14:17]
	v_mfma_f32_16x16x32_bf16 v[10:13], v[166:169], v[218:221], v[10:13]
	s_setprio 0
	s_setprio 1
	v_mfma_f32_16x16x32_bf16 v[54:57], v[170:173], v[190:193], v[54:57]
	v_mfma_f32_16x16x32_bf16 v[50:53], v[182:185], v[190:193], v[50:53]
	v_mfma_f32_16x16x32_bf16 v[38:41], v[170:173], v[198:201], v[38:41]
	v_mfma_f32_16x16x32_bf16 v[34:37], v[182:185], v[198:201], v[34:37]
	v_mfma_f32_16x16x32_bf16 v[22:25], v[170:173], v[206:209], v[22:25]
	v_mfma_f32_16x16x32_bf16 v[18:21], v[182:185], v[206:209], v[18:21]
	v_mfma_f32_16x16x32_bf16 v[6:9], v[170:173], v[214:217], v[6:9]
	v_mfma_f32_16x16x32_bf16 v[2:5], v[182:185], v[214:217], v[2:5]
	v_mfma_f32_16x16x32_bf16 v[54:57], v[178:181], v[194:197], v[54:57]
	v_mfma_f32_16x16x32_bf16 v[50:53], v[186:189], v[194:197], v[50:53]
	v_mfma_f32_16x16x32_bf16 v[38:41], v[178:181], v[202:205], v[38:41]
	v_mfma_f32_16x16x32_bf16 v[34:37], v[186:189], v[202:205], v[34:37]
	v_mfma_f32_16x16x32_bf16 v[22:25], v[178:181], v[210:213], v[22:25]
	v_mfma_f32_16x16x32_bf16 v[18:21], v[186:189], v[210:213], v[18:21]
	v_mfma_f32_16x16x32_bf16 v[6:9], v[178:181], v[218:221], v[6:9]
	v_mfma_f32_16x16x32_bf16 v[2:5], v[186:189], v[218:221], v[2:5]
	s_setprio 0
	s_barrier
	s_add_i32 s53, s53, 2
	s_add_u32 s51, s51, 0x700000
	s_addc_u32 s52, s52, 0
	s_add_u32 s28, s28, 0x200000
	s_addc_u32 s29, s29, 0
	s_cmp_gt_u32 s53, 61
	s_cbranch_scc0 .LBB0_422
	s_and_b64 vcc, exec, s[16:17]
	s_cbranch_vccz .LBB0_425
	s_barrier

.LBB0_501:
	ds_read_b128 v[146:149], v152
	ds_read_b128 v[156:159], v152 offset:1024
	ds_read_b128 v[160:163], v152 offset:2048
	ds_read_b128 v[164:167], v152 offset:3072
	ds_read_b128 v[168:171], v153
	ds_read_b128 v[172:175], v153 offset:1024
	ds_read_b128 v[178:181], v153 offset:2048
	ds_read_b128 v[182:185], v153 offset:3072
	s_add_u32 s26, s10, 0xfc000
	s_addc_u32 s27, s11, 0
	s_cmpk_eq_i32 s47, 0xdc
	s_cselect_b32 s30, s21, s26
	s_cselect_b32 s31, s5, s27
	s_cselect_b32 s28, s44, s45
	s_cselect_b32 s29, s19, s46
	s_add_u32 s26, s30, 0x100000
	s_addc_u32 s27, s31, 0
	s_add_i32 m0, s1, 0xc000
	ds_read_b128 v[186:189], v154
	ds_read_b128 v[190:193], v154 offset:1024
	ds_read_b128 v[194:197], v154 offset:2048
	ds_read_b128 v[198:201], v154 offset:3072
	ds_read_b128 v[202:205], v154 offset:4096
	ds_read_b128 v[206:209], v154 offset:5120
	ds_read_b128 v[210:213], v154 offset:6144
	ds_read_b128 v[214:217], v154 offset:7168
	global_load_lds_dwordx4 v138, s[10:11]
	s_add_i32 m0, s1, 0xe000
	s_nop 0
	global_load_lds_dwordx4 v140, s[10:11]
	s_waitcnt vmcnt(8)
	s_waitcnt lgkmcnt(0)
	s_barrier
	s_setprio 1
	s_waitcnt lgkmcnt(0)
	v_mfma_f32_16x16x32_bf16 v[126:129], v[146:149], v[186:189], v[126:129]
	v_mfma_f32_16x16x32_bf16 v[122:125], v[160:163], v[186:189], v[122:125]
	v_mfma_f32_16x16x32_bf16 v[110:113], v[146:149], v[194:197], v[110:113]
	v_mfma_f32_16x16x32_bf16 v[106:109], v[160:163], v[194:197], v[106:109]
	v_mfma_f32_16x16x32_bf16 v[94:97], v[146:149], v[202:205], v[94:97]
	v_mfma_f32_16x16x32_bf16 v[90:93], v[160:163], v[202:205], v[90:93]
	v_mfma_f32_16x16x32_bf16 v[78:81], v[146:149], v[210:213], v[78:81]
	v_mfma_f32_16x16x32_bf16 v[74:77], v[160:163], v[210:213], v[74:77]
	v_mfma_f32_16x16x32_bf16 v[126:129], v[156:159], v[190:193], v[126:129]
	v_mfma_f32_16x16x32_bf16 v[122:125], v[164:167], v[190:193], v[122:125]
	v_mfma_f32_16x16x32_bf16 v[110:113], v[156:159], v[198:201], v[110:113]
	v_mfma_f32_16x16x32_bf16 v[106:109], v[164:167], v[198:201], v[106:109]
	v_mfma_f32_16x16x32_bf16 v[94:97], v[156:159], v[206:209], v[94:97]
	v_mfma_f32_16x16x32_bf16 v[90:93], v[164:167], v[206:209], v[90:93]
	v_mfma_f32_16x16x32_bf16 v[78:81], v[156:159], v[214:217], v[78:81]
	v_mfma_f32_16x16x32_bf16 v[74:77], v[164:167], v[214:217], v[74:77]
	s_setprio 0
	s_setprio 1
	v_mfma_f32_16x16x32_bf16 v[118:121], v[168:171], v[186:189], v[118:121]
	v_mfma_f32_16x16x32_bf16 v[114:117], v[178:181], v[186:189], v[114:117]
	v_mfma_f32_16x16x32_bf16 v[102:105], v[168:171], v[194:197], v[102:105]
	v_mfma_f32_16x16x32_bf16 v[98:101], v[178:181], v[194:197], v[98:101]
	v_mfma_f32_16x16x32_bf16 v[86:89], v[168:171], v[202:205], v[86:89]
	v_mfma_f32_16x16x32_bf16 v[82:85], v[178:181], v[202:205], v[82:85]
	v_mfma_f32_16x16x32_bf16 v[70:73], v[168:171], v[210:213], v[70:73]
	v_mfma_f32_16x16x32_bf16 v[66:69], v[178:181], v[210:213], v[66:69]
	v_mfma_f32_16x16x32_bf16 v[118:121], v[172:175], v[190:193], v[118:121]
	v_mfma_f32_16x16x32_bf16 v[114:117], v[182:185], v[190:193], v[114:117]
	v_mfma_f32_16x16x32_bf16 v[102:105], v[172:175], v[198:201], v[102:105]
	v_mfma_f32_16x16x32_bf16 v[98:101], v[182:185], v[198:201], v[98:101]
	v_mfma_f32_16x16x32_bf16 v[86:89], v[172:175], v[206:209], v[86:89]
	v_mfma_f32_16x16x32_bf16 v[82:85], v[182:185], v[206:209], v[82:85]
	v_mfma_f32_16x16x32_bf16 v[70:73], v[172:175], v[214:217], v[70:73]
	v_mfma_f32_16x16x32_bf16 v[66:69], v[182:185], v[214:217], v[66:69]
	s_setprio 0
	s_barrier
	s_add_i32 s48, s41, s0
	s_mov_b32 m0, s48
	ds_read_b128 v[186:189], v154 offset:16384
	ds_read_b128 v[190:193], v154 offset:17408
	ds_read_b128 v[194:197], v154 offset:18432
	ds_read_b128 v[198:201], v154 offset:19456
	ds_read_b128 v[202:205], v154 offset:20480
	ds_read_b128 v[206:209], v154 offset:21504
	ds_read_b128 v[210:213], v154 offset:22528
	ds_read_b128 v[214:217], v154 offset:23552
	global_load_lds_dwordx4 v132, s[28:29]
	s_add_i32 m0, s48, 0x2000
	s_add_u32 s48, s28, 0x4000
	s_addc_u32 s49, s29, 0
	s_add_i32 s50, s42, s0
	global_load_lds_dwordx4 v136, s[28:29]
	s_mov_b32 m0, s50
	s_nop 0
	global_load_lds_dwordx4 v132, s[48:49]
	s_add_i32 m0, s50, 0x2000
	s_nop 0
	global_load_lds_dwordx4 v136, s[48:49]
	s_mov_b32 m0, s1
	s_nop 0
	global_load_lds_dwordx4 v130, s[30:31]
	s_mov_b32 m0, s33
	s_nop 0
	global_load_lds_dwordx4 v134, s[30:31]
	s_waitcnt vmcnt(8)
	s_waitcnt lgkmcnt(0)
	s_barrier
	s_setprio 1
	s_waitcnt lgkmcnt(0)
	v_mfma_f32_16x16x32_bf16 v[62:65], v[146:149], v[186:189], v[62:65]
	v_mfma_f32_16x16x32_bf16 v[58:61], v[160:163], v[186:189], v[58:61]
	v_mfma_f32_16x16x32_bf16 v[46:49], v[146:149], v[194:197], v[46:49]
	v_mfma_f32_16x16x32_bf16 v[42:45], v[160:163], v[194:197], v[42:45]
	v_mfma_f32_16x16x32_bf16 v[30:33], v[146:149], v[202:205], v[30:33]
	v_mfma_f32_16x16x32_bf16 v[26:29], v[160:163], v[202:205], v[26:29]
	v_mfma_f32_16x16x32_bf16 v[14:17], v[146:149], v[210:213], v[14:17]
	v_mfma_f32_16x16x32_bf16 v[10:13], v[160:163], v[210:213], v[10:13]
	v_mfma_f32_16x16x32_bf16 v[62:65], v[156:159], v[190:193], v[62:65]
	v_mfma_f32_16x16x32_bf16 v[58:61], v[164:167], v[190:193], v[58:61]
	v_mfma_f32_16x16x32_bf16 v[46:49], v[156:159], v[198:201], v[46:49]
	v_mfma_f32_16x16x32_bf16 v[42:45], v[164:167], v[198:201], v[42:45]
	v_mfma_f32_16x16x32_bf16 v[30:33], v[156:159], v[206:209], v[30:33]
	v_mfma_f32_16x16x32_bf16 v[26:29], v[164:167], v[206:209], v[26:29]
	v_mfma_f32_16x16x32_bf16 v[14:17], v[156:159], v[214:217], v[14:17]
	v_mfma_f32_16x16x32_bf16 v[10:13], v[164:167], v[214:217], v[10:13]
	s_setprio 0
	s_setprio 1
	v_mfma_f32_16x16x32_bf16 v[54:57], v[168:171], v[186:189], v[54:57]
	v_mfma_f32_16x16x32_bf16 v[50:53], v[178:181], v[186:189], v[50:53]
	v_mfma_f32_16x16x32_bf16 v[38:41], v[168:171], v[194:197], v[38:41]
	v_mfma_f32_16x16x32_bf16 v[34:37], v[178:181], v[194:197], v[34:37]
	v_mfma_f32_16x16x32_bf16 v[22:25], v[168:171], v[202:205], v[22:25]
	v_mfma_f32_16x16x32_bf16 v[18:21], v[178:181], v[202:205], v[18:21]
	v_mfma_f32_16x16x32_bf16 v[6:9], v[168:171], v[210:213], v[6:9]
	v_mfma_f32_16x16x32_bf16 v[2:5], v[178:181], v[210:213], v[2:5]
	v_mfma_f32_16x16x32_bf16 v[54:57], v[172:175], v[190:193], v[54:57]
	v_mfma_f32_16x16x32_bf16 v[50:53], v[182:185], v[190:193], v[50:53]
	v_mfma_f32_16x16x32_bf16 v[38:41], v[172:175], v[198:201], v[38:41]
	v_mfma_f32_16x16x32_bf16 v[34:37], v[182:185], v[198:201], v[34:37]
	v_mfma_f32_16x16x32_bf16 v[22:25], v[172:175], v[206:209], v[22:25]
	v_mfma_f32_16x16x32_bf16 v[18:21], v[182:185], v[206:209], v[18:21]
	v_mfma_f32_16x16x32_bf16 v[6:9], v[172:175], v[214:217], v[6:9]
	v_mfma_f32_16x16x32_bf16 v[2:5], v[182:185], v[214:217], v[2:5]
	s_setprio 0
	s_barrier
	s_add_i32 s48, 0, 0x18000
	s_add_i32 s49, 0, 0x1c000
	v_add_u32_e32 v164, s48, v151
	v_add_u32_e32 v176, s49, v151
	ds_read_b128 v[146:149], v164
	ds_read_b128 v[156:159], v164 offset:1024
	ds_read_b128 v[160:163], v164 offset:2048
	ds_read_b128 v[164:167], v164 offset:3072
	ds_read_b128 v[168:171], v176
	ds_read_b128 v[172:175], v176 offset:1024
	ds_read_b128 v[178:181], v176 offset:2048
	ds_read_b128 v[182:185], v176 offset:3072
	s_add_u32 s30, s30, 0x4000
	s_addc_u32 s31, s31, 0
	s_mov_b32 m0, s34
	ds_read_b128 v[186:189], v154 offset:32768
	ds_read_b128 v[190:193], v154 offset:33792
	ds_read_b128 v[194:197], v154 offset:34816
	ds_read_b128 v[198:201], v154 offset:35840
	ds_read_b128 v[202:205], v154 offset:36864
	ds_read_b128 v[206:209], v154 offset:37888
	ds_read_b128 v[210:213], v154 offset:38912
	ds_read_b128 v[214:217], v154 offset:39936
	global_load_lds_dwordx4 v130, s[30:31]
	s_mov_b32 m0, s35
	s_nop 0
	global_load_lds_dwordx4 v134, s[30:31]
	s_waitcnt vmcnt(8)
	s_waitcnt lgkmcnt(0)
	s_barrier
	s_setprio 1
	s_waitcnt lgkmcnt(0)
	v_mfma_f32_16x16x32_bf16 v[126:129], v[146:149], v[186:189], v[126:129]
	v_mfma_f32_16x16x32_bf16 v[122:125], v[160:163], v[186:189], v[122:125]
	v_mfma_f32_16x16x32_bf16 v[110:113], v[146:149], v[194:197], v[110:113]
	v_mfma_f32_16x16x32_bf16 v[106:109], v[160:163], v[194:197], v[106:109]
	v_mfma_f32_16x16x32_bf16 v[94:97], v[146:149], v[202:205], v[94:97]
	v_mfma_f32_16x16x32_bf16 v[90:93], v[160:163], v[202:205], v[90:93]
	v_mfma_f32_16x16x32_bf16 v[78:81], v[146:149], v[210:213], v[78:81]
	v_mfma_f32_16x16x32_bf16 v[74:77], v[160:163], v[210:213], v[74:77]
	v_mfma_f32_16x16x32_bf16 v[126:129], v[156:159], v[190:193], v[126:129]
	v_mfma_f32_16x16x32_bf16 v[122:125], v[164:167], v[190:193], v[122:125]
	v_mfma_f32_16x16x32_bf16 v[110:113], v[156:159], v[198:201], v[110:113]
	v_mfma_f32_16x16x32_bf16 v[106:109], v[164:167], v[198:201], v[106:109]
	v_mfma_f32_16x16x32_bf16 v[94:97], v[156:159], v[206:209], v[94:97]
	v_mfma_f32_16x16x32_bf16 v[90:93], v[164:167], v[206:209], v[90:93]
	v_mfma_f32_16x16x32_bf16 v[78:81], v[156:159], v[214:217], v[78:81]
	v_mfma_f32_16x16x32_bf16 v[74:77], v[164:167], v[214:217], v[74:77]
	s_setprio 0
	s_setprio 1
	v_mfma_f32_16x16x32_bf16 v[118:121], v[168:171], v[186:189], v[118:121]
	v_mfma_f32_16x16x32_bf16 v[114:117], v[178:181], v[186:189], v[114:117]
	v_mfma_f32_16x16x32_bf16 v[102:105], v[168:171], v[194:197], v[102:105]
	v_mfma_f32_16x16x32_bf16 v[98:101], v[178:181], v[194:197], v[98:101]
	v_mfma_f32_16x16x32_bf16 v[86:89], v[168:171], v[202:205], v[86:89]
	v_mfma_f32_16x16x32_bf16 v[82:85], v[178:181], v[202:205], v[82:85]
	v_mfma_f32_16x16x32_bf16 v[70:73], v[168:171], v[210:213], v[70:73]
	v_mfma_f32_16x16x32_bf16 v[66:69], v[178:181], v[210:213], v[66:69]
	v_mfma_f32_16x16x32_bf16 v[118:121], v[172:175], v[190:193], v[118:121]
	v_mfma_f32_16x16x32_bf16 v[114:117], v[182:185], v[190:193], v[114:117]
	v_mfma_f32_16x16x32_bf16 v[102:105], v[172:175], v[198:201], v[102:105]
	v_mfma_f32_16x16x32_bf16 v[98:101], v[182:185], v[198:201], v[98:101]
	v_mfma_f32_16x16x32_bf16 v[86:89], v[172:175], v[206:209], v[86:89]
	v_mfma_f32_16x16x32_bf16 v[82:85], v[182:185], v[206:209], v[82:85]
	v_mfma_f32_16x16x32_bf16 v[70:73], v[172:175], v[214:217], v[70:73]
	v_mfma_f32_16x16x32_bf16 v[66:69], v[182:185], v[214:217], v[66:69]
	s_setprio 0
	s_barrier
	s_add_u32 s30, s28, 0x80000
	s_addc_u32 s31, s29, 0
	s_add_i32 s48, s48, s0
	s_mov_b32 m0, s48
	ds_read_b128 v[186:189], v154 offset:49152
	ds_read_b128 v[190:193], v154 offset:50176
	ds_read_b128 v[194:197], v154 offset:51200
	ds_read_b128 v[198:201], v154 offset:52224
	ds_read_b128 v[202:205], v154 offset:53248
	ds_read_b128 v[206:209], v154 offset:54272
	ds_read_b128 v[210:213], v154 offset:55296
	ds_read_b128 v[214:217], v154 offset:56320
	global_load_lds_dwordx4 v132, s[30:31]
	s_add_i32 m0, s48, 0x2000
	s_add_u32 s28, s28, 0x84000
	s_addc_u32 s29, s29, 0
	global_load_lds_dwordx4 v136, s[30:31]
	s_add_i32 s30, s49, s0
	s_mov_b32 m0, s30
	s_nop 0
	global_load_lds_dwordx4 v132, s[28:29]
	s_add_i32 m0, s30, 0x2000
	s_nop 0
	global_load_lds_dwordx4 v136, s[28:29]
	s_mov_b32 m0, s39
	s_nop 0
	global_load_lds_dwordx4 v130, s[26:27]
	s_mov_b32 m0, s40
	s_nop 0
	global_load_lds_dwordx4 v134, s[26:27]
	s_waitcnt vmcnt(8)
	s_waitcnt lgkmcnt(0)
	s_barrier
	s_setprio 1
	s_waitcnt lgkmcnt(0)
	v_mfma_f32_16x16x32_bf16 v[62:65], v[146:149], v[186:189], v[62:65]
	v_mfma_f32_16x16x32_bf16 v[58:61], v[160:163], v[186:189], v[58:61]
	v_mfma_f32_16x16x32_bf16 v[46:49], v[146:149], v[194:197], v[46:49]
	v_mfma_f32_16x16x32_bf16 v[42:45], v[160:163], v[194:197], v[42:45]
	v_mfma_f32_16x16x32_bf16 v[30:33], v[146:149], v[202:205], v[30:33]
	v_mfma_f32_16x16x32_bf16 v[26:29], v[160:163], v[202:205], v[26:29]
	v_mfma_f32_16x16x32_bf16 v[14:17], v[146:149], v[210:213], v[14:17]
	v_mfma_f32_16x16x32_bf16 v[10:13], v[160:163], v[210:213], v[10:13]
	v_mfma_f32_16x16x32_bf16 v[62:65], v[156:159], v[190:193], v[62:65]
	v_mfma_f32_16x16x32_bf16 v[58:61], v[164:167], v[190:193], v[58:61]
	v_mfma_f32_16x16x32_bf16 v[46:49], v[156:159], v[198:201], v[46:49]
	v_mfma_f32_16x16x32_bf16 v[42:45], v[164:167], v[198:201], v[42:45]
	v_mfma_f32_16x16x32_bf16 v[30:33], v[156:159], v[206:209], v[30:33]
	v_mfma_f32_16x16x32_bf16 v[26:29], v[164:167], v[206:209], v[26:29]
	v_mfma_f32_16x16x32_bf16 v[14:17], v[156:159], v[214:217], v[14:17]
	v_mfma_f32_16x16x32_bf16 v[10:13], v[164:167], v[214:217], v[10:13]
	s_setprio 0
	s_setprio 1
	v_mfma_f32_16x16x32_bf16 v[54:57], v[168:171], v[186:189], v[54:57]
	v_mfma_f32_16x16x32_bf16 v[50:53], v[178:181], v[186:189], v[50:53]
	v_mfma_f32_16x16x32_bf16 v[38:41], v[168:171], v[194:197], v[38:41]
	v_mfma_f32_16x16x32_bf16 v[34:37], v[178:181], v[194:197], v[34:37]
	v_mfma_f32_16x16x32_bf16 v[22:25], v[168:171], v[202:205], v[22:25]
	v_mfma_f32_16x16x32_bf16 v[18:21], v[178:181], v[202:205], v[18:21]
	v_mfma_f32_16x16x32_bf16 v[6:9], v[168:171], v[210:213], v[6:9]
	v_mfma_f32_16x16x32_bf16 v[2:5], v[178:181], v[210:213], v[2:5]
	v_mfma_f32_16x16x32_bf16 v[54:57], v[172:175], v[190:193], v[54:57]
	v_mfma_f32_16x16x32_bf16 v[50:53], v[182:185], v[190:193], v[50:53]
	v_mfma_f32_16x16x32_bf16 v[38:41], v[172:175], v[198:201], v[38:41]
	v_mfma_f32_16x16x32_bf16 v[34:37], v[182:185], v[198:201], v[34:37]
	v_mfma_f32_16x16x32_bf16 v[22:25], v[172:175], v[206:209], v[22:25]
	v_mfma_f32_16x16x32_bf16 v[18:21], v[182:185], v[206:209], v[18:21]
	v_mfma_f32_16x16x32_bf16 v[6:9], v[172:175], v[214:217], v[6:9]
	v_mfma_f32_16x16x32_bf16 v[2:5], v[182:185], v[214:217], v[2:5]
	s_setprio 0
	s_barrier
	s_add_i32 s47, s47, 2
	s_add_u32 s45, s45, 0x100000
	s_addc_u32 s46, s46, 0
	s_add_u32 s10, s10, 0x200000
	s_addc_u32 s11, s11, 0
	s_cmpk_gt_u32 s47, 0xdd
	s_cbranch_scc0 .LBB0_501
	s_and_b64 vcc, exec, s[16:17]
	s_cbranch_vccz .LBB0_504
	s_barrier

.LBB0_801:
	ds_read_b128 v[130:133], v179
	ds_read_b128 v[134:137], v179 offset:1024
	ds_read_b128 v[156:159], v179 offset:2048
	ds_read_b128 v[160:163], v179 offset:3072
	ds_read_b128 v[164:167], v180
	ds_read_b128 v[168:171], v180 offset:1024
	ds_read_b128 v[172:175], v180 offset:2048
	ds_read_b128 v[186:189], v180 offset:3072
	s_add_u32 s26, s12, 0xfc000
	s_addc_u32 s27, s13, 0
	s_cmp_eq_u32 s47, 60
	s_cselect_b32 s30, s5, s26
	s_cselect_b32 s31, s3, s27
	s_cselect_b32 s28, s21, s45
	s_cselect_b32 s29, s19, s46
	s_add_u32 s26, s30, 0x100000
	s_addc_u32 s27, s31, 0
	s_add_i32 m0, s1, 0xc000
	ds_read_b128 v[190:193], v181
	ds_read_b128 v[194:197], v181 offset:1024
	ds_read_b128 v[198:201], v181 offset:2048
	ds_read_b128 v[202:205], v181 offset:3072
	ds_read_b128 v[206:209], v181 offset:4096
	ds_read_b128 v[210:213], v181 offset:5120
	ds_read_b128 v[214:217], v181 offset:6144
	ds_read_b128 v[218:221], v181 offset:7168
	global_load_lds_dwordx4 v148, s[12:13]
	s_add_i32 m0, s1, 0xe000
	s_nop 0
	global_load_lds_dwordx4 v150, s[12:13]
	s_waitcnt vmcnt(8)
	s_waitcnt lgkmcnt(0)
	s_barrier
	s_setprio 1
	s_waitcnt lgkmcnt(0)
	v_mfma_f32_16x16x32_bf16 v[126:129], v[130:133], v[190:193], v[126:129]
	v_mfma_f32_16x16x32_bf16 v[122:125], v[156:159], v[190:193], v[122:125]
	v_mfma_f32_16x16x32_bf16 v[110:113], v[130:133], v[198:201], v[110:113]
	v_mfma_f32_16x16x32_bf16 v[106:109], v[156:159], v[198:201], v[106:109]
	v_mfma_f32_16x16x32_bf16 v[94:97], v[130:133], v[206:209], v[94:97]
	v_mfma_f32_16x16x32_bf16 v[90:93], v[156:159], v[206:209], v[90:93]
	v_mfma_f32_16x16x32_bf16 v[78:81], v[130:133], v[214:217], v[78:81]
	v_mfma_f32_16x16x32_bf16 v[74:77], v[156:159], v[214:217], v[74:77]
	v_mfma_f32_16x16x32_bf16 v[126:129], v[134:137], v[194:197], v[126:129]
	v_mfma_f32_16x16x32_bf16 v[122:125], v[160:163], v[194:197], v[122:125]
	v_mfma_f32_16x16x32_bf16 v[110:113], v[134:137], v[202:205], v[110:113]
	v_mfma_f32_16x16x32_bf16 v[106:109], v[160:163], v[202:205], v[106:109]
	v_mfma_f32_16x16x32_bf16 v[94:97], v[134:137], v[210:213], v[94:97]
	v_mfma_f32_16x16x32_bf16 v[90:93], v[160:163], v[210:213], v[90:93]
	v_mfma_f32_16x16x32_bf16 v[78:81], v[134:137], v[218:221], v[78:81]
	v_mfma_f32_16x16x32_bf16 v[74:77], v[160:163], v[218:221], v[74:77]
	s_setprio 0
	s_setprio 1
	v_mfma_f32_16x16x32_bf16 v[118:121], v[164:167], v[190:193], v[118:121]
	v_mfma_f32_16x16x32_bf16 v[114:117], v[172:175], v[190:193], v[114:117]
	v_mfma_f32_16x16x32_bf16 v[102:105], v[164:167], v[198:201], v[102:105]
	v_mfma_f32_16x16x32_bf16 v[98:101], v[172:175], v[198:201], v[98:101]
	v_mfma_f32_16x16x32_bf16 v[86:89], v[164:167], v[206:209], v[86:89]
	v_mfma_f32_16x16x32_bf16 v[82:85], v[172:175], v[206:209], v[82:85]
	v_mfma_f32_16x16x32_bf16 v[70:73], v[164:167], v[214:217], v[70:73]
	v_mfma_f32_16x16x32_bf16 v[66:69], v[172:175], v[214:217], v[66:69]
	v_mfma_f32_16x16x32_bf16 v[118:121], v[168:171], v[194:197], v[118:121]
	v_mfma_f32_16x16x32_bf16 v[114:117], v[186:189], v[194:197], v[114:117]
	v_mfma_f32_16x16x32_bf16 v[102:105], v[168:171], v[202:205], v[102:105]
	v_mfma_f32_16x16x32_bf16 v[98:101], v[186:189], v[202:205], v[98:101]
	v_mfma_f32_16x16x32_bf16 v[86:89], v[168:171], v[210:213], v[86:89]
	v_mfma_f32_16x16x32_bf16 v[82:85], v[186:189], v[210:213], v[82:85]
	v_mfma_f32_16x16x32_bf16 v[70:73], v[168:171], v[218:221], v[70:73]
	v_mfma_f32_16x16x32_bf16 v[66:69], v[186:189], v[218:221], v[66:69]
	s_setprio 0
	s_barrier
	s_add_i32 s48, s42, s0
	s_mov_b32 m0, s48
	ds_read_b128 v[190:193], v181 offset:16384
	ds_read_b128 v[194:197], v181 offset:17408
	ds_read_b128 v[198:201], v181 offset:18432
	ds_read_b128 v[202:205], v181 offset:19456
	ds_read_b128 v[206:209], v181 offset:20480
	ds_read_b128 v[210:213], v181 offset:21504
	ds_read_b128 v[214:217], v181 offset:22528
	ds_read_b128 v[218:221], v181 offset:23552
	global_load_lds_dwordx4 v140, s[28:29]
	s_add_i32 m0, s48, 0x2000
	s_add_u32 s48, s28, 0x4000
	s_addc_u32 s49, s29, 0
	s_add_i32 s50, s43, s0
	global_load_lds_dwordx4 v144, s[28:29]
	s_mov_b32 m0, s50
	s_nop 0
	global_load_lds_dwordx4 v140, s[48:49]
	s_add_i32 m0, s50, 0x2000
	s_nop 0
	global_load_lds_dwordx4 v144, s[48:49]
	s_mov_b32 m0, s1
	s_nop 0
	global_load_lds_dwordx4 v138, s[30:31]
	s_mov_b32 m0, s33
	s_nop 0
	global_load_lds_dwordx4 v142, s[30:31]
	s_waitcnt vmcnt(8)
	s_waitcnt lgkmcnt(0)
	s_barrier
	s_setprio 1
	s_waitcnt lgkmcnt(0)
	v_mfma_f32_16x16x32_bf16 v[62:65], v[130:133], v[190:193], v[62:65]
	v_mfma_f32_16x16x32_bf16 v[58:61], v[156:159], v[190:193], v[58:61]
	v_mfma_f32_16x16x32_bf16 v[46:49], v[130:133], v[198:201], v[46:49]
	v_mfma_f32_16x16x32_bf16 v[42:45], v[156:159], v[198:201], v[42:45]
	v_mfma_f32_16x16x32_bf16 v[30:33], v[130:133], v[206:209], v[30:33]
	v_mfma_f32_16x16x32_bf16 v[26:29], v[156:159], v[206:209], v[26:29]
	v_mfma_f32_16x16x32_bf16 v[14:17], v[130:133], v[214:217], v[14:17]
	v_mfma_f32_16x16x32_bf16 v[10:13], v[156:159], v[214:217], v[10:13]
	v_mfma_f32_16x16x32_bf16 v[62:65], v[134:137], v[194:197], v[62:65]
	v_mfma_f32_16x16x32_bf16 v[58:61], v[160:163], v[194:197], v[58:61]
	v_mfma_f32_16x16x32_bf16 v[46:49], v[134:137], v[202:205], v[46:49]
	v_mfma_f32_16x16x32_bf16 v[42:45], v[160:163], v[202:205], v[42:45]
	v_mfma_f32_16x16x32_bf16 v[30:33], v[134:137], v[210:213], v[30:33]
	v_mfma_f32_16x16x32_bf16 v[26:29], v[160:163], v[210:213], v[26:29]
	v_mfma_f32_16x16x32_bf16 v[14:17], v[134:137], v[218:221], v[14:17]
	v_mfma_f32_16x16x32_bf16 v[10:13], v[160:163], v[218:221], v[10:13]
	s_setprio 0
	s_setprio 1
	v_mfma_f32_16x16x32_bf16 v[54:57], v[164:167], v[190:193], v[54:57]
	v_mfma_f32_16x16x32_bf16 v[50:53], v[172:175], v[190:193], v[50:53]
	v_mfma_f32_16x16x32_bf16 v[38:41], v[164:167], v[198:201], v[38:41]
	v_mfma_f32_16x16x32_bf16 v[34:37], v[172:175], v[198:201], v[34:37]
	v_mfma_f32_16x16x32_bf16 v[22:25], v[164:167], v[206:209], v[22:25]
	v_mfma_f32_16x16x32_bf16 v[18:21], v[172:175], v[206:209], v[18:21]
	v_mfma_f32_16x16x32_bf16 v[6:9], v[164:167], v[214:217], v[6:9]
	v_mfma_f32_16x16x32_bf16 v[2:5], v[172:175], v[214:217], v[2:5]
	v_mfma_f32_16x16x32_bf16 v[54:57], v[168:171], v[194:197], v[54:57]
	v_mfma_f32_16x16x32_bf16 v[50:53], v[186:189], v[194:197], v[50:53]
	v_mfma_f32_16x16x32_bf16 v[38:41], v[168:171], v[202:205], v[38:41]
	v_mfma_f32_16x16x32_bf16 v[34:37], v[186:189], v[202:205], v[34:37]
	v_mfma_f32_16x16x32_bf16 v[22:25], v[168:171], v[210:213], v[22:25]
	v_mfma_f32_16x16x32_bf16 v[18:21], v[186:189], v[210:213], v[18:21]
	v_mfma_f32_16x16x32_bf16 v[6:9], v[168:171], v[218:221], v[6:9]
	v_mfma_f32_16x16x32_bf16 v[2:5], v[186:189], v[218:221], v[2:5]
	s_setprio 0
	s_barrier
	s_add_i32 s48, 0, 0x18000
	v_add_u32_e32 v146, s48, v178
	s_add_i32 s49, 0, 0x1c000
	ds_read_b128 v[130:133], v146
	ds_read_b128 v[134:137], v146 offset:1024
	ds_read_b128 v[156:159], v146 offset:2048
	ds_read_b128 v[160:163], v146 offset:3072
	v_add_u32_e32 v146, s49, v178
	ds_read_b128 v[164:167], v146
	ds_read_b128 v[168:171], v146 offset:1024
	ds_read_b128 v[172:175], v146 offset:2048
	ds_read_b128 v[186:189], v146 offset:3072
	s_add_u32 s30, s30, 0x4000
	s_addc_u32 s31, s31, 0
	s_mov_b32 m0, s34
	ds_read_b128 v[190:193], v181 offset:32768
	ds_read_b128 v[194:197], v181 offset:33792
	ds_read_b128 v[198:201], v181 offset:34816
	ds_read_b128 v[202:205], v181 offset:35840
	ds_read_b128 v[206:209], v181 offset:36864
	ds_read_b128 v[210:213], v181 offset:37888
	ds_read_b128 v[214:217], v181 offset:38912
	ds_read_b128 v[218:221], v181 offset:39936
	global_load_lds_dwordx4 v138, s[30:31]
	s_mov_b32 m0, s35
	s_nop 0
	global_load_lds_dwordx4 v142, s[30:31]
	s_waitcnt vmcnt(8)
	s_waitcnt lgkmcnt(0)
	s_barrier
	s_setprio 1
	s_waitcnt lgkmcnt(0)
	v_mfma_f32_16x16x32_bf16 v[126:129], v[130:133], v[190:193], v[126:129]
	v_mfma_f32_16x16x32_bf16 v[122:125], v[156:159], v[190:193], v[122:125]
	v_mfma_f32_16x16x32_bf16 v[110:113], v[130:133], v[198:201], v[110:113]
	v_mfma_f32_16x16x32_bf16 v[106:109], v[156:159], v[198:201], v[106:109]
	v_mfma_f32_16x16x32_bf16 v[94:97], v[130:133], v[206:209], v[94:97]
	v_mfma_f32_16x16x32_bf16 v[90:93], v[156:159], v[206:209], v[90:93]
	v_mfma_f32_16x16x32_bf16 v[78:81], v[130:133], v[214:217], v[78:81]
	v_mfma_f32_16x16x32_bf16 v[74:77], v[156:159], v[214:217], v[74:77]
	v_mfma_f32_16x16x32_bf16 v[126:129], v[134:137], v[194:197], v[126:129]
	v_mfma_f32_16x16x32_bf16 v[122:125], v[160:163], v[194:197], v[122:125]
	v_mfma_f32_16x16x32_bf16 v[110:113], v[134:137], v[202:205], v[110:113]
	v_mfma_f32_16x16x32_bf16 v[106:109], v[160:163], v[202:205], v[106:109]
	v_mfma_f32_16x16x32_bf16 v[94:97], v[134:137], v[210:213], v[94:97]
	v_mfma_f32_16x16x32_bf16 v[90:93], v[160:163], v[210:213], v[90:93]
	v_mfma_f32_16x16x32_bf16 v[78:81], v[134:137], v[218:221], v[78:81]
	v_mfma_f32_16x16x32_bf16 v[74:77], v[160:163], v[218:221], v[74:77]
	s_setprio 0
	s_setprio 1
	v_mfma_f32_16x16x32_bf16 v[118:121], v[164:167], v[190:193], v[118:121]
	v_mfma_f32_16x16x32_bf16 v[114:117], v[172:175], v[190:193], v[114:117]
	v_mfma_f32_16x16x32_bf16 v[102:105], v[164:167], v[198:201], v[102:105]
	v_mfma_f32_16x16x32_bf16 v[98:101], v[172:175], v[198:201], v[98:101]
	v_mfma_f32_16x16x32_bf16 v[86:89], v[164:167], v[206:209], v[86:89]
	v_mfma_f32_16x16x32_bf16 v[82:85], v[172:175], v[206:209], v[82:85]
	v_mfma_f32_16x16x32_bf16 v[70:73], v[164:167], v[214:217], v[70:73]
	v_mfma_f32_16x16x32_bf16 v[66:69], v[172:175], v[214:217], v[66:69]
	v_mfma_f32_16x16x32_bf16 v[118:121], v[168:171], v[194:197], v[118:121]
	v_mfma_f32_16x16x32_bf16 v[114:117], v[186:189], v[194:197], v[114:117]
	v_mfma_f32_16x16x32_bf16 v[102:105], v[168:171], v[202:205], v[102:105]
	v_mfma_f32_16x16x32_bf16 v[98:101], v[186:189], v[202:205], v[98:101]
	v_mfma_f32_16x16x32_bf16 v[86:89], v[168:171], v[210:213], v[86:89]
	v_mfma_f32_16x16x32_bf16 v[82:85], v[186:189], v[210:213], v[82:85]
	v_mfma_f32_16x16x32_bf16 v[70:73], v[168:171], v[218:221], v[70:73]
	v_mfma_f32_16x16x32_bf16 v[66:69], v[186:189], v[218:221], v[66:69]
	s_setprio 0
	s_barrier
	s_add_u32 s30, s28, 0x180000
	s_addc_u32 s31, s29, 0
	s_add_i32 s48, s48, s0
	s_mov_b32 m0, s48
	ds_read_b128 v[190:193], v181 offset:49152
	ds_read_b128 v[194:197], v181 offset:50176
	ds_read_b128 v[198:201], v181 offset:51200
	ds_read_b128 v[202:205], v181 offset:52224
	ds_read_b128 v[206:209], v181 offset:53248
	ds_read_b128 v[210:213], v181 offset:54272
	ds_read_b128 v[214:217], v181 offset:55296
	ds_read_b128 v[218:221], v181 offset:56320
	global_load_lds_dwordx4 v140, s[30:31]
	s_add_i32 m0, s48, 0x2000
	s_add_u32 s28, s28, 0x184000
	s_addc_u32 s29, s29, 0
	global_load_lds_dwordx4 v144, s[30:31]
	s_add_i32 s30, s49, s0
	s_mov_b32 m0, s30
	s_nop 0
	global_load_lds_dwordx4 v140, s[28:29]
	s_add_i32 m0, s30, 0x2000
	s_nop 0
	global_load_lds_dwordx4 v144, s[28:29]
	s_mov_b32 m0, s38
	s_nop 0
	global_load_lds_dwordx4 v138, s[26:27]
	s_mov_b32 m0, s39
	s_nop 0
	global_load_lds_dwordx4 v142, s[26:27]
	s_waitcnt vmcnt(8)
	s_waitcnt lgkmcnt(0)
	s_barrier
	s_setprio 1
	s_waitcnt lgkmcnt(0)
	v_mfma_f32_16x16x32_bf16 v[62:65], v[130:133], v[190:193], v[62:65]
	v_mfma_f32_16x16x32_bf16 v[58:61], v[156:159], v[190:193], v[58:61]
	v_mfma_f32_16x16x32_bf16 v[46:49], v[130:133], v[198:201], v[46:49]
	v_mfma_f32_16x16x32_bf16 v[42:45], v[156:159], v[198:201], v[42:45]
	v_mfma_f32_16x16x32_bf16 v[30:33], v[130:133], v[206:209], v[30:33]
	v_mfma_f32_16x16x32_bf16 v[26:29], v[156:159], v[206:209], v[26:29]
	v_mfma_f32_16x16x32_bf16 v[14:17], v[130:133], v[214:217], v[14:17]
	v_mfma_f32_16x16x32_bf16 v[10:13], v[156:159], v[214:217], v[10:13]
	v_mfma_f32_16x16x32_bf16 v[62:65], v[134:137], v[194:197], v[62:65]
	v_mfma_f32_16x16x32_bf16 v[58:61], v[160:163], v[194:197], v[58:61]
	v_mfma_f32_16x16x32_bf16 v[46:49], v[134:137], v[202:205], v[46:49]
	v_mfma_f32_16x16x32_bf16 v[42:45], v[160:163], v[202:205], v[42:45]
	v_mfma_f32_16x16x32_bf16 v[30:33], v[134:137], v[210:213], v[30:33]
	v_mfma_f32_16x16x32_bf16 v[26:29], v[160:163], v[210:213], v[26:29]
	v_mfma_f32_16x16x32_bf16 v[14:17], v[134:137], v[218:221], v[14:17]
	v_mfma_f32_16x16x32_bf16 v[10:13], v[160:163], v[218:221], v[10:13]
	s_setprio 0
	s_setprio 1
	v_mfma_f32_16x16x32_bf16 v[54:57], v[164:167], v[190:193], v[54:57]
	v_mfma_f32_16x16x32_bf16 v[50:53], v[172:175], v[190:193], v[50:53]
	v_mfma_f32_16x16x32_bf16 v[38:41], v[164:167], v[198:201], v[38:41]
	v_mfma_f32_16x16x32_bf16 v[34:37], v[172:175], v[198:201], v[34:37]
	v_mfma_f32_16x16x32_bf16 v[22:25], v[164:167], v[206:209], v[22:25]
	v_mfma_f32_16x16x32_bf16 v[18:21], v[172:175], v[206:209], v[18:21]
	v_mfma_f32_16x16x32_bf16 v[6:9], v[164:167], v[214:217], v[6:9]
	v_mfma_f32_16x16x32_bf16 v[2:5], v[172:175], v[214:217], v[2:5]
	v_mfma_f32_16x16x32_bf16 v[54:57], v[168:171], v[194:197], v[54:57]
	v_mfma_f32_16x16x32_bf16 v[50:53], v[186:189], v[194:197], v[50:53]
	v_mfma_f32_16x16x32_bf16 v[38:41], v[168:171], v[202:205], v[38:41]
	v_mfma_f32_16x16x32_bf16 v[34:37], v[186:189], v[202:205], v[34:37]
	v_mfma_f32_16x16x32_bf16 v[22:25], v[168:171], v[210:213], v[22:25]
	v_mfma_f32_16x16x32_bf16 v[18:21], v[186:189], v[210:213], v[18:21]
	v_mfma_f32_16x16x32_bf16 v[6:9], v[168:171], v[218:221], v[6:9]
	v_mfma_f32_16x16x32_bf16 v[2:5], v[186:189], v[218:221], v[2:5]
	s_setprio 0
	s_barrier
	s_add_i32 s47, s47, 2
	s_add_u32 s45, s45, 0x300000
	s_addc_u32 s46, s46, 0
	s_add_u32 s12, s12, 0x200000
	s_addc_u32 s13, s13, 0
	s_cmp_gt_u32 s47, 61
	s_cbranch_scc0 .LBB0_801
	s_and_b64 vcc, exec, s[8:9]
	s_cbranch_vccz .LBB0_804
	s_barrier

.LBB0_1217:
	ds_read_b128 v[146:149], v152
	ds_read_b128 v[156:159], v152 offset:1024
	ds_read_b128 v[160:163], v152 offset:2048
	ds_read_b128 v[164:167], v152 offset:3072
	ds_read_b128 v[168:171], v153
	ds_read_b128 v[172:175], v153 offset:1024
	ds_read_b128 v[176:179], v153 offset:2048
	ds_read_b128 v[180:183], v153 offset:3072
	s_add_u32 s22, s20, 0xfc000
	s_addc_u32 s23, s21, 0
	s_cmp_eq_u32 s43, 60
	s_cselect_b32 s26, s15, s22
	s_cselect_b32 s27, s5, s23
	s_cselect_b32 s24, s40, s41
	s_cselect_b32 s25, s13, s42
	s_add_u32 s22, s26, 0x100000
	s_addc_u32 s23, s27, 0
	s_add_i32 m0, s1, 0xc000
	ds_read_b128 v[184:187], v154
	ds_read_b128 v[188:191], v154 offset:1024
	ds_read_b128 v[192:195], v154 offset:2048
	ds_read_b128 v[196:199], v154 offset:3072
	ds_read_b128 v[206:209], v154 offset:4096
	ds_read_b128 v[212:215], v154 offset:5120
	ds_read_b128 v[220:223], v154 offset:6144
	ds_read_b128 v[224:227], v154 offset:7168
	global_load_lds_dwordx4 v138, s[20:21]
	s_add_i32 m0, s1, 0xe000
	s_nop 0
	global_load_lds_dwordx4 v140, s[20:21]
	s_waitcnt vmcnt(8)
	s_waitcnt lgkmcnt(0)
	s_barrier
	s_setprio 1
	s_waitcnt lgkmcnt(0)
	v_mfma_f32_16x16x32_bf16 v[126:129], v[146:149], v[184:187], v[126:129]
	v_mfma_f32_16x16x32_bf16 v[122:125], v[160:163], v[184:187], v[122:125]
	v_mfma_f32_16x16x32_bf16 v[110:113], v[146:149], v[192:195], v[110:113]
	v_mfma_f32_16x16x32_bf16 v[106:109], v[160:163], v[192:195], v[106:109]
	v_mfma_f32_16x16x32_bf16 v[94:97], v[146:149], v[206:209], v[94:97]
	v_mfma_f32_16x16x32_bf16 v[90:93], v[160:163], v[206:209], v[90:93]
	v_mfma_f32_16x16x32_bf16 v[78:81], v[146:149], v[220:223], v[78:81]
	v_mfma_f32_16x16x32_bf16 v[74:77], v[160:163], v[220:223], v[74:77]
	v_mfma_f32_16x16x32_bf16 v[126:129], v[156:159], v[188:191], v[126:129]
	v_mfma_f32_16x16x32_bf16 v[122:125], v[164:167], v[188:191], v[122:125]
	v_mfma_f32_16x16x32_bf16 v[110:113], v[156:159], v[196:199], v[110:113]
	v_mfma_f32_16x16x32_bf16 v[106:109], v[164:167], v[196:199], v[106:109]
	v_mfma_f32_16x16x32_bf16 v[94:97], v[156:159], v[212:215], v[94:97]
	v_mfma_f32_16x16x32_bf16 v[90:93], v[164:167], v[212:215], v[90:93]
	v_mfma_f32_16x16x32_bf16 v[78:81], v[156:159], v[224:227], v[78:81]
	v_mfma_f32_16x16x32_bf16 v[74:77], v[164:167], v[224:227], v[74:77]
	s_setprio 0
	s_setprio 1
	v_mfma_f32_16x16x32_bf16 v[118:121], v[168:171], v[184:187], v[118:121]
	v_mfma_f32_16x16x32_bf16 v[114:117], v[176:179], v[184:187], v[114:117]
	v_mfma_f32_16x16x32_bf16 v[102:105], v[168:171], v[192:195], v[102:105]
	v_mfma_f32_16x16x32_bf16 v[98:101], v[176:179], v[192:195], v[98:101]
	v_mfma_f32_16x16x32_bf16 v[86:89], v[168:171], v[206:209], v[86:89]
	v_mfma_f32_16x16x32_bf16 v[82:85], v[176:179], v[206:209], v[82:85]
	v_mfma_f32_16x16x32_bf16 v[70:73], v[168:171], v[220:223], v[70:73]
	v_mfma_f32_16x16x32_bf16 v[66:69], v[176:179], v[220:223], v[66:69]
	v_mfma_f32_16x16x32_bf16 v[118:121], v[172:175], v[188:191], v[118:121]
	v_mfma_f32_16x16x32_bf16 v[114:117], v[180:183], v[188:191], v[114:117]
	v_mfma_f32_16x16x32_bf16 v[102:105], v[172:175], v[196:199], v[102:105]
	v_mfma_f32_16x16x32_bf16 v[98:101], v[180:183], v[196:199], v[98:101]
	v_mfma_f32_16x16x32_bf16 v[86:89], v[172:175], v[212:215], v[86:89]
	v_mfma_f32_16x16x32_bf16 v[82:85], v[180:183], v[212:215], v[82:85]
	v_mfma_f32_16x16x32_bf16 v[70:73], v[172:175], v[224:227], v[70:73]
	v_mfma_f32_16x16x32_bf16 v[66:69], v[180:183], v[224:227], v[66:69]
	s_setprio 0
	s_barrier
	s_add_i32 s44, s37, s0
	s_mov_b32 m0, s44
	ds_read_b128 v[184:187], v154 offset:16384
	ds_read_b128 v[188:191], v154 offset:17408
	ds_read_b128 v[192:195], v154 offset:18432
	ds_read_b128 v[196:199], v154 offset:19456
	ds_read_b128 v[206:209], v154 offset:20480
	ds_read_b128 v[212:215], v154 offset:21504
	ds_read_b128 v[220:223], v154 offset:22528
	ds_read_b128 v[224:227], v154 offset:23552
	global_load_lds_dwordx4 v132, s[24:25]
	s_add_i32 m0, s44, 0x2000
	s_add_u32 s44, s24, 0x4000
	s_addc_u32 s45, s25, 0
	s_add_i32 s46, s38, s0
	global_load_lds_dwordx4 v136, s[24:25]
	s_mov_b32 m0, s46
	s_nop 0
	global_load_lds_dwordx4 v132, s[44:45]
	s_add_i32 m0, s46, 0x2000
	s_nop 0
	global_load_lds_dwordx4 v136, s[44:45]
	s_mov_b32 m0, s1
	s_nop 0
	global_load_lds_dwordx4 v130, s[26:27]
	s_mov_b32 m0, s28
	s_nop 0
	global_load_lds_dwordx4 v134, s[26:27]
	s_waitcnt vmcnt(8)
	s_waitcnt lgkmcnt(0)
	s_barrier
	s_setprio 1
	s_waitcnt lgkmcnt(0)
	v_mfma_f32_16x16x32_bf16 v[62:65], v[146:149], v[184:187], v[62:65]
	v_mfma_f32_16x16x32_bf16 v[58:61], v[160:163], v[184:187], v[58:61]
	v_mfma_f32_16x16x32_bf16 v[46:49], v[146:149], v[192:195], v[46:49]
	v_mfma_f32_16x16x32_bf16 v[42:45], v[160:163], v[192:195], v[42:45]
	v_mfma_f32_16x16x32_bf16 v[30:33], v[146:149], v[206:209], v[30:33]
	v_mfma_f32_16x16x32_bf16 v[26:29], v[160:163], v[206:209], v[26:29]
	v_mfma_f32_16x16x32_bf16 v[14:17], v[146:149], v[220:223], v[14:17]
	v_mfma_f32_16x16x32_bf16 v[10:13], v[160:163], v[220:223], v[10:13]
	v_mfma_f32_16x16x32_bf16 v[62:65], v[156:159], v[188:191], v[62:65]
	v_mfma_f32_16x16x32_bf16 v[58:61], v[164:167], v[188:191], v[58:61]
	v_mfma_f32_16x16x32_bf16 v[46:49], v[156:159], v[196:199], v[46:49]
	v_mfma_f32_16x16x32_bf16 v[42:45], v[164:167], v[196:199], v[42:45]
	v_mfma_f32_16x16x32_bf16 v[30:33], v[156:159], v[212:215], v[30:33]
	v_mfma_f32_16x16x32_bf16 v[26:29], v[164:167], v[212:215], v[26:29]
	v_mfma_f32_16x16x32_bf16 v[14:17], v[156:159], v[224:227], v[14:17]
	v_mfma_f32_16x16x32_bf16 v[10:13], v[164:167], v[224:227], v[10:13]
	s_setprio 0
	s_setprio 1
	v_mfma_f32_16x16x32_bf16 v[54:57], v[168:171], v[184:187], v[54:57]
	v_mfma_f32_16x16x32_bf16 v[50:53], v[176:179], v[184:187], v[50:53]
	v_mfma_f32_16x16x32_bf16 v[38:41], v[168:171], v[192:195], v[38:41]
	v_mfma_f32_16x16x32_bf16 v[34:37], v[176:179], v[192:195], v[34:37]
	v_mfma_f32_16x16x32_bf16 v[22:25], v[168:171], v[206:209], v[22:25]
	v_mfma_f32_16x16x32_bf16 v[18:21], v[176:179], v[206:209], v[18:21]
	v_mfma_f32_16x16x32_bf16 v[6:9], v[168:171], v[220:223], v[6:9]
	v_mfma_f32_16x16x32_bf16 v[2:5], v[176:179], v[220:223], v[2:5]
	v_mfma_f32_16x16x32_bf16 v[54:57], v[172:175], v[188:191], v[54:57]
	v_mfma_f32_16x16x32_bf16 v[50:53], v[180:183], v[188:191], v[50:53]
	v_mfma_f32_16x16x32_bf16 v[38:41], v[172:175], v[196:199], v[38:41]
	v_mfma_f32_16x16x32_bf16 v[34:37], v[180:183], v[196:199], v[34:37]
	v_mfma_f32_16x16x32_bf16 v[22:25], v[172:175], v[212:215], v[22:25]
	v_mfma_f32_16x16x32_bf16 v[18:21], v[180:183], v[212:215], v[18:21]
	v_mfma_f32_16x16x32_bf16 v[6:9], v[172:175], v[224:227], v[6:9]
	v_mfma_f32_16x16x32_bf16 v[2:5], v[180:183], v[224:227], v[2:5]
	s_setprio 0
	s_barrier
	s_add_i32 s44, 0, 0x18000
	v_add_u32_e32 v155, s44, v151
	s_add_i32 s45, 0, 0x1c000
	ds_read_b128 v[146:149], v155
	ds_read_b128 v[156:159], v155 offset:1024
	ds_read_b128 v[160:163], v155 offset:2048
	ds_read_b128 v[164:167], v155 offset:3072
	v_add_u32_e32 v155, s45, v151
	ds_read_b128 v[168:171], v155
	ds_read_b128 v[172:175], v155 offset:1024
	ds_read_b128 v[176:179], v155 offset:2048
	ds_read_b128 v[180:183], v155 offset:3072
	s_add_u32 s26, s26, 0x4000
	s_addc_u32 s27, s27, 0
	s_mov_b32 m0, s29
	ds_read_b128 v[184:187], v154 offset:32768
	ds_read_b128 v[188:191], v154 offset:33792
	ds_read_b128 v[192:195], v154 offset:34816
	ds_read_b128 v[196:199], v154 offset:35840
	ds_read_b128 v[206:209], v154 offset:36864
	ds_read_b128 v[212:215], v154 offset:37888
	ds_read_b128 v[220:223], v154 offset:38912
	ds_read_b128 v[224:227], v154 offset:39936
	global_load_lds_dwordx4 v130, s[26:27]
	s_mov_b32 m0, s30
	s_nop 0
	global_load_lds_dwordx4 v134, s[26:27]
	s_waitcnt vmcnt(8)
	s_waitcnt lgkmcnt(0)
	s_barrier
	s_setprio 1
	s_waitcnt lgkmcnt(0)
	v_mfma_f32_16x16x32_bf16 v[126:129], v[146:149], v[184:187], v[126:129]
	v_mfma_f32_16x16x32_bf16 v[122:125], v[160:163], v[184:187], v[122:125]
	v_mfma_f32_16x16x32_bf16 v[110:113], v[146:149], v[192:195], v[110:113]
	v_mfma_f32_16x16x32_bf16 v[106:109], v[160:163], v[192:195], v[106:109]
	v_mfma_f32_16x16x32_bf16 v[94:97], v[146:149], v[206:209], v[94:97]
	v_mfma_f32_16x16x32_bf16 v[90:93], v[160:163], v[206:209], v[90:93]
	v_mfma_f32_16x16x32_bf16 v[78:81], v[146:149], v[220:223], v[78:81]
	v_mfma_f32_16x16x32_bf16 v[74:77], v[160:163], v[220:223], v[74:77]
	v_mfma_f32_16x16x32_bf16 v[126:129], v[156:159], v[188:191], v[126:129]
	v_mfma_f32_16x16x32_bf16 v[122:125], v[164:167], v[188:191], v[122:125]
	v_mfma_f32_16x16x32_bf16 v[110:113], v[156:159], v[196:199], v[110:113]
	v_mfma_f32_16x16x32_bf16 v[106:109], v[164:167], v[196:199], v[106:109]
	v_mfma_f32_16x16x32_bf16 v[94:97], v[156:159], v[212:215], v[94:97]
	v_mfma_f32_16x16x32_bf16 v[90:93], v[164:167], v[212:215], v[90:93]
	v_mfma_f32_16x16x32_bf16 v[78:81], v[156:159], v[224:227], v[78:81]
	v_mfma_f32_16x16x32_bf16 v[74:77], v[164:167], v[224:227], v[74:77]
	s_setprio 0
	s_setprio 1
	v_mfma_f32_16x16x32_bf16 v[118:121], v[168:171], v[184:187], v[118:121]
	v_mfma_f32_16x16x32_bf16 v[114:117], v[176:179], v[184:187], v[114:117]
	v_mfma_f32_16x16x32_bf16 v[102:105], v[168:171], v[192:195], v[102:105]
	v_mfma_f32_16x16x32_bf16 v[98:101], v[176:179], v[192:195], v[98:101]
	v_mfma_f32_16x16x32_bf16 v[86:89], v[168:171], v[206:209], v[86:89]
	v_mfma_f32_16x16x32_bf16 v[82:85], v[176:179], v[206:209], v[82:85]
	v_mfma_f32_16x16x32_bf16 v[70:73], v[168:171], v[220:223], v[70:73]
	v_mfma_f32_16x16x32_bf16 v[66:69], v[176:179], v[220:223], v[66:69]
	v_mfma_f32_16x16x32_bf16 v[118:121], v[172:175], v[188:191], v[118:121]
	v_mfma_f32_16x16x32_bf16 v[114:117], v[180:183], v[188:191], v[114:117]
	v_mfma_f32_16x16x32_bf16 v[102:105], v[172:175], v[196:199], v[102:105]
	v_mfma_f32_16x16x32_bf16 v[98:101], v[180:183], v[196:199], v[98:101]
	v_mfma_f32_16x16x32_bf16 v[86:89], v[172:175], v[212:215], v[86:89]
	v_mfma_f32_16x16x32_bf16 v[82:85], v[180:183], v[212:215], v[82:85]
	v_mfma_f32_16x16x32_bf16 v[70:73], v[172:175], v[224:227], v[70:73]
	v_mfma_f32_16x16x32_bf16 v[66:69], v[180:183], v[224:227], v[66:69]
	s_setprio 0
	s_barrier
	s_add_u32 s26, s24, 0x80000
	s_addc_u32 s27, s25, 0
	s_add_i32 s44, s44, s0
	s_mov_b32 m0, s44
	ds_read_b128 v[184:187], v154 offset:49152
	ds_read_b128 v[188:191], v154 offset:50176
	ds_read_b128 v[192:195], v154 offset:51200
	ds_read_b128 v[196:199], v154 offset:52224
	ds_read_b128 v[206:209], v154 offset:53248
	ds_read_b128 v[212:215], v154 offset:54272
	ds_read_b128 v[220:223], v154 offset:55296
	ds_read_b128 v[224:227], v154 offset:56320
	global_load_lds_dwordx4 v132, s[26:27]
	s_add_i32 m0, s44, 0x2000
	s_add_u32 s24, s24, 0x84000
	s_addc_u32 s25, s25, 0
	global_load_lds_dwordx4 v136, s[26:27]
	s_add_i32 s26, s45, s0
	s_mov_b32 m0, s26
	s_nop 0
	global_load_lds_dwordx4 v132, s[24:25]
	s_add_i32 m0, s26, 0x2000
	s_nop 0
	global_load_lds_dwordx4 v136, s[24:25]
	s_mov_b32 m0, s35
	s_nop 0
	global_load_lds_dwordx4 v130, s[22:23]
	s_mov_b32 m0, s36
	s_nop 0
	global_load_lds_dwordx4 v134, s[22:23]
	s_waitcnt vmcnt(8)
	s_waitcnt lgkmcnt(0)
	s_barrier
	s_setprio 1
	s_waitcnt lgkmcnt(0)
	v_mfma_f32_16x16x32_bf16 v[62:65], v[146:149], v[184:187], v[62:65]
	v_mfma_f32_16x16x32_bf16 v[58:61], v[160:163], v[184:187], v[58:61]
	v_mfma_f32_16x16x32_bf16 v[46:49], v[146:149], v[192:195], v[46:49]
	v_mfma_f32_16x16x32_bf16 v[42:45], v[160:163], v[192:195], v[42:45]
	v_mfma_f32_16x16x32_bf16 v[30:33], v[146:149], v[206:209], v[30:33]
	v_mfma_f32_16x16x32_bf16 v[26:29], v[160:163], v[206:209], v[26:29]
	v_mfma_f32_16x16x32_bf16 v[14:17], v[146:149], v[220:223], v[14:17]
	v_mfma_f32_16x16x32_bf16 v[10:13], v[160:163], v[220:223], v[10:13]
	v_mfma_f32_16x16x32_bf16 v[62:65], v[156:159], v[188:191], v[62:65]
	v_mfma_f32_16x16x32_bf16 v[58:61], v[164:167], v[188:191], v[58:61]
	v_mfma_f32_16x16x32_bf16 v[46:49], v[156:159], v[196:199], v[46:49]
	v_mfma_f32_16x16x32_bf16 v[42:45], v[164:167], v[196:199], v[42:45]
	v_mfma_f32_16x16x32_bf16 v[30:33], v[156:159], v[212:215], v[30:33]
	v_mfma_f32_16x16x32_bf16 v[26:29], v[164:167], v[212:215], v[26:29]
	v_mfma_f32_16x16x32_bf16 v[14:17], v[156:159], v[224:227], v[14:17]
	v_mfma_f32_16x16x32_bf16 v[10:13], v[164:167], v[224:227], v[10:13]
	s_setprio 0
	s_setprio 1
	v_mfma_f32_16x16x32_bf16 v[54:57], v[168:171], v[184:187], v[54:57]
	v_mfma_f32_16x16x32_bf16 v[50:53], v[176:179], v[184:187], v[50:53]
	v_mfma_f32_16x16x32_bf16 v[38:41], v[168:171], v[192:195], v[38:41]
	v_mfma_f32_16x16x32_bf16 v[34:37], v[176:179], v[192:195], v[34:37]
	v_mfma_f32_16x16x32_bf16 v[22:25], v[168:171], v[206:209], v[22:25]
	v_mfma_f32_16x16x32_bf16 v[18:21], v[176:179], v[206:209], v[18:21]
	v_mfma_f32_16x16x32_bf16 v[6:9], v[168:171], v[220:223], v[6:9]
	v_mfma_f32_16x16x32_bf16 v[2:5], v[176:179], v[220:223], v[2:5]
	v_mfma_f32_16x16x32_bf16 v[54:57], v[172:175], v[188:191], v[54:57]
	v_mfma_f32_16x16x32_bf16 v[50:53], v[180:183], v[188:191], v[50:53]
	v_mfma_f32_16x16x32_bf16 v[38:41], v[172:175], v[196:199], v[38:41]
	v_mfma_f32_16x16x32_bf16 v[34:37], v[180:183], v[196:199], v[34:37]
	v_mfma_f32_16x16x32_bf16 v[22:25], v[172:175], v[212:215], v[22:25]
	v_mfma_f32_16x16x32_bf16 v[18:21], v[180:183], v[212:215], v[18:21]
	v_mfma_f32_16x16x32_bf16 v[6:9], v[172:175], v[224:227], v[6:9]
	v_mfma_f32_16x16x32_bf16 v[2:5], v[180:183], v[224:227], v[2:5]
	s_setprio 0
	s_barrier
	s_add_i32 s43, s43, 2
	s_add_u32 s41, s41, 0x100000
	s_addc_u32 s42, s42, 0
	s_add_u32 s20, s20, 0x200000
	s_addc_u32 s21, s21, 0
	s_cmp_gt_u32 s43, 61
	s_cbranch_scc0 .LBB0_1217
	s_and_b64 vcc, exec, s[8:9]
	s_cbranch_vccz .LBB0_1220
	s_barrier

.LBB0_1670:
	ds_read_b128 v[148:151], v143
	ds_read_b128 v[152:155], v143 offset:1024
	ds_read_b128 v[156:159], v143 offset:2048
	ds_read_b128 v[160:163], v143 offset:3072
	ds_read_b128 v[164:167], v144
	ds_read_b128 v[168:171], v144 offset:1024
	ds_read_b128 v[172:175], v144 offset:2048
	ds_read_b128 v[176:179], v144 offset:3072
	s_add_u32 s10, s6, 0x4000
	s_addc_u32 s11, s7, 0
	s_cmp_eq_u32 s28, 60
	s_cselect_b32 s18, s14, s10
	s_cselect_b32 s19, s15, s11
	s_cselect_b32 s16, s4, s26
	s_cselect_b32 s17, s5, s27
	s_add_u32 s10, s18, 0x8000
	s_addc_u32 s11, s19, 0
	s_mov_b32 m0, s29
	ds_read_b128 v[180:183], v145
	ds_read_b128 v[184:187], v145 offset:1024
	ds_read_b128 v[188:191], v145 offset:2048
	ds_read_b128 v[192:195], v145 offset:3072
	ds_read_b128 v[196:199], v145 offset:4096
	ds_read_b128 v[206:209], v145 offset:5120
	ds_read_b128 v[212:215], v145 offset:6144
	ds_read_b128 v[220:223], v145 offset:7168
	global_load_lds_dwordx4 v138, s[6:7]
	s_mov_b32 m0, s30
	s_nop 0
	global_load_lds_dwordx4 v140, s[6:7]
	s_waitcnt vmcnt(8)
	s_waitcnt lgkmcnt(0)
	s_barrier
	s_setprio 1
	s_waitcnt lgkmcnt(0)
	v_mfma_f32_16x16x32_bf16 v[126:129], v[148:151], v[180:183], v[126:129]
	v_mfma_f32_16x16x32_bf16 v[122:125], v[156:159], v[180:183], v[122:125]
	v_mfma_f32_16x16x32_bf16 v[118:121], v[148:151], v[188:191], v[118:121]
	v_mfma_f32_16x16x32_bf16 v[110:113], v[156:159], v[188:191], v[110:113]
	v_mfma_f32_16x16x32_bf16 v[102:105], v[148:151], v[196:199], v[102:105]
	v_mfma_f32_16x16x32_bf16 v[94:97], v[156:159], v[196:199], v[94:97]
	v_mfma_f32_16x16x32_bf16 v[86:89], v[148:151], v[212:215], v[86:89]
	v_mfma_f32_16x16x32_bf16 v[78:81], v[156:159], v[212:215], v[78:81]
	v_mfma_f32_16x16x32_bf16 v[126:129], v[152:155], v[184:187], v[126:129]
	v_mfma_f32_16x16x32_bf16 v[122:125], v[160:163], v[184:187], v[122:125]
	v_mfma_f32_16x16x32_bf16 v[118:121], v[152:155], v[192:195], v[118:121]
	v_mfma_f32_16x16x32_bf16 v[110:113], v[160:163], v[192:195], v[110:113]
	v_mfma_f32_16x16x32_bf16 v[102:105], v[152:155], v[206:209], v[102:105]
	v_mfma_f32_16x16x32_bf16 v[94:97], v[160:163], v[206:209], v[94:97]
	v_mfma_f32_16x16x32_bf16 v[86:89], v[152:155], v[220:223], v[86:89]
	v_mfma_f32_16x16x32_bf16 v[78:81], v[160:163], v[220:223], v[78:81]
	s_setprio 0
	s_setprio 1
	v_mfma_f32_16x16x32_bf16 v[114:117], v[164:167], v[180:183], v[114:117]
	v_mfma_f32_16x16x32_bf16 v[106:109], v[172:175], v[180:183], v[106:109]
	v_mfma_f32_16x16x32_bf16 v[98:101], v[164:167], v[188:191], v[98:101]
	v_mfma_f32_16x16x32_bf16 v[90:93], v[172:175], v[188:191], v[90:93]
	v_mfma_f32_16x16x32_bf16 v[82:85], v[164:167], v[196:199], v[82:85]
	v_mfma_f32_16x16x32_bf16 v[74:77], v[172:175], v[196:199], v[74:77]
	v_mfma_f32_16x16x32_bf16 v[70:73], v[164:167], v[212:215], v[70:73]
	v_mfma_f32_16x16x32_bf16 v[66:69], v[172:175], v[212:215], v[66:69]
	v_mfma_f32_16x16x32_bf16 v[114:117], v[168:171], v[184:187], v[114:117]
	v_mfma_f32_16x16x32_bf16 v[106:109], v[176:179], v[184:187], v[106:109]
	v_mfma_f32_16x16x32_bf16 v[98:101], v[168:171], v[192:195], v[98:101]
	v_mfma_f32_16x16x32_bf16 v[90:93], v[176:179], v[192:195], v[90:93]
	v_mfma_f32_16x16x32_bf16 v[82:85], v[168:171], v[206:209], v[82:85]
	v_mfma_f32_16x16x32_bf16 v[74:77], v[176:179], v[206:209], v[74:77]
	v_mfma_f32_16x16x32_bf16 v[70:73], v[168:171], v[220:223], v[70:73]
	v_mfma_f32_16x16x32_bf16 v[66:69], v[176:179], v[220:223], v[66:69]
	s_setprio 0
	s_barrier
	s_mov_b32 m0, s31
	s_add_u32 s40, s16, 0x4000
	ds_read_b128 v[180:183], v145 offset:16384
	ds_read_b128 v[184:187], v145 offset:17408
	ds_read_b128 v[188:191], v145 offset:18432
	ds_read_b128 v[192:195], v145 offset:19456
	ds_read_b128 v[196:199], v145 offset:20480
	ds_read_b128 v[206:209], v145 offset:21504
	ds_read_b128 v[212:215], v145 offset:22528
	ds_read_b128 v[220:223], v145 offset:23552
	global_load_lds_dwordx4 v134, s[16:17]
	s_mov_b32 m0, s33
	s_addc_u32 s41, s17, 0
	global_load_lds_dwordx4 v130, s[16:17]
	s_mov_b32 m0, s34
	s_nop 0
	global_load_lds_dwordx4 v134, s[40:41]
	s_mov_b32 m0, s35
	s_nop 0
	global_load_lds_dwordx4 v130, s[40:41]
	s_mov_b32 m0, s1
	s_nop 0
	global_load_lds_dwordx4 v136, s[18:19]
	s_mov_b32 m0, s3
	s_nop 0
	global_load_lds_dwordx4 v132, s[18:19]
	s_waitcnt vmcnt(8)
	s_waitcnt lgkmcnt(0)
	s_barrier
	s_setprio 1
	s_waitcnt lgkmcnt(0)
	v_mfma_f32_16x16x32_bf16 v[62:65], v[148:151], v[180:183], v[62:65]
	v_mfma_f32_16x16x32_bf16 v[58:61], v[156:159], v[180:183], v[58:61]
	v_mfma_f32_16x16x32_bf16 v[54:57], v[148:151], v[188:191], v[54:57]
	v_mfma_f32_16x16x32_bf16 v[46:49], v[156:159], v[188:191], v[46:49]
	v_mfma_f32_16x16x32_bf16 v[38:41], v[148:151], v[196:199], v[38:41]
	v_mfma_f32_16x16x32_bf16 v[30:33], v[156:159], v[196:199], v[30:33]
	v_mfma_f32_16x16x32_bf16 v[22:25], v[148:151], v[212:215], v[22:25]
	v_mfma_f32_16x16x32_bf16 v[14:17], v[156:159], v[212:215], v[14:17]
	v_mfma_f32_16x16x32_bf16 v[62:65], v[152:155], v[184:187], v[62:65]
	v_mfma_f32_16x16x32_bf16 v[58:61], v[160:163], v[184:187], v[58:61]
	v_mfma_f32_16x16x32_bf16 v[54:57], v[152:155], v[192:195], v[54:57]
	v_mfma_f32_16x16x32_bf16 v[46:49], v[160:163], v[192:195], v[46:49]
	v_mfma_f32_16x16x32_bf16 v[38:41], v[152:155], v[206:209], v[38:41]
	v_mfma_f32_16x16x32_bf16 v[30:33], v[160:163], v[206:209], v[30:33]
	v_mfma_f32_16x16x32_bf16 v[22:25], v[152:155], v[220:223], v[22:25]
	v_mfma_f32_16x16x32_bf16 v[14:17], v[160:163], v[220:223], v[14:17]
	s_setprio 0
	s_setprio 1
	v_mfma_f32_16x16x32_bf16 v[50:53], v[164:167], v[180:183], v[50:53]
	v_mfma_f32_16x16x32_bf16 v[42:45], v[172:175], v[180:183], v[42:45]
	v_mfma_f32_16x16x32_bf16 v[34:37], v[164:167], v[188:191], v[34:37]
	v_mfma_f32_16x16x32_bf16 v[26:29], v[172:175], v[188:191], v[26:29]
	v_mfma_f32_16x16x32_bf16 v[18:21], v[164:167], v[196:199], v[18:21]
	v_mfma_f32_16x16x32_bf16 v[10:13], v[172:175], v[196:199], v[10:13]
	v_mfma_f32_16x16x32_bf16 v[6:9], v[164:167], v[212:215], v[6:9]
	v_mfma_f32_16x16x32_bf16 v[2:5], v[172:175], v[212:215], v[2:5]
	v_mfma_f32_16x16x32_bf16 v[50:53], v[168:171], v[184:187], v[50:53]
	v_mfma_f32_16x16x32_bf16 v[42:45], v[176:179], v[184:187], v[42:45]
	v_mfma_f32_16x16x32_bf16 v[34:37], v[168:171], v[192:195], v[34:37]
	v_mfma_f32_16x16x32_bf16 v[26:29], v[176:179], v[192:195], v[26:29]
	v_mfma_f32_16x16x32_bf16 v[18:21], v[168:171], v[206:209], v[18:21]
	v_mfma_f32_16x16x32_bf16 v[10:13], v[176:179], v[206:209], v[10:13]
	v_mfma_f32_16x16x32_bf16 v[6:9], v[168:171], v[220:223], v[6:9]
	v_mfma_f32_16x16x32_bf16 v[2:5], v[176:179], v[220:223], v[2:5]
	s_setprio 0
	s_barrier
	ds_read_b128 v[148:151], v146
	ds_read_b128 v[152:155], v146 offset:1024
	ds_read_b128 v[156:159], v146 offset:2048
	ds_read_b128 v[160:163], v146 offset:3072
	ds_read_b128 v[164:167], v147
	ds_read_b128 v[168:171], v147 offset:1024
	ds_read_b128 v[172:175], v147 offset:2048
	ds_read_b128 v[176:179], v147 offset:3072
	s_add_u32 s18, s18, 0x4000
	s_addc_u32 s19, s19, 0
	s_mov_b32 m0, s20
	ds_read_b128 v[180:183], v145 offset:32768
	ds_read_b128 v[184:187], v145 offset:33792
	ds_read_b128 v[188:191], v145 offset:34816
	ds_read_b128 v[192:195], v145 offset:35840
	ds_read_b128 v[196:199], v145 offset:36864
	ds_read_b128 v[206:209], v145 offset:37888
	ds_read_b128 v[212:215], v145 offset:38912
	ds_read_b128 v[220:223], v145 offset:39936
	global_load_lds_dwordx4 v136, s[18:19]
	s_mov_b32 m0, s21
	s_nop 0
	global_load_lds_dwordx4 v132, s[18:19]
	s_waitcnt vmcnt(8)
	s_waitcnt lgkmcnt(0)
	s_barrier
	s_setprio 1
	s_waitcnt lgkmcnt(0)
	v_mfma_f32_16x16x32_bf16 v[126:129], v[148:151], v[180:183], v[126:129]
	v_mfma_f32_16x16x32_bf16 v[122:125], v[156:159], v[180:183], v[122:125]
	v_mfma_f32_16x16x32_bf16 v[118:121], v[148:151], v[188:191], v[118:121]
	v_mfma_f32_16x16x32_bf16 v[110:113], v[156:159], v[188:191], v[110:113]
	v_mfma_f32_16x16x32_bf16 v[102:105], v[148:151], v[196:199], v[102:105]
	v_mfma_f32_16x16x32_bf16 v[94:97], v[156:159], v[196:199], v[94:97]
	v_mfma_f32_16x16x32_bf16 v[86:89], v[148:151], v[212:215], v[86:89]
	v_mfma_f32_16x16x32_bf16 v[78:81], v[156:159], v[212:215], v[78:81]
	v_mfma_f32_16x16x32_bf16 v[126:129], v[152:155], v[184:187], v[126:129]
	v_mfma_f32_16x16x32_bf16 v[122:125], v[160:163], v[184:187], v[122:125]
	v_mfma_f32_16x16x32_bf16 v[118:121], v[152:155], v[192:195], v[118:121]
	v_mfma_f32_16x16x32_bf16 v[110:113], v[160:163], v[192:195], v[110:113]
	v_mfma_f32_16x16x32_bf16 v[102:105], v[152:155], v[206:209], v[102:105]
	v_mfma_f32_16x16x32_bf16 v[94:97], v[160:163], v[206:209], v[94:97]
	v_mfma_f32_16x16x32_bf16 v[86:89], v[152:155], v[220:223], v[86:89]
	v_mfma_f32_16x16x32_bf16 v[78:81], v[160:163], v[220:223], v[78:81]
	s_setprio 0
	s_setprio 1
	v_mfma_f32_16x16x32_bf16 v[114:117], v[164:167], v[180:183], v[114:117]
	v_mfma_f32_16x16x32_bf16 v[106:109], v[172:175], v[180:183], v[106:109]
	v_mfma_f32_16x16x32_bf16 v[98:101], v[164:167], v[188:191], v[98:101]
	v_mfma_f32_16x16x32_bf16 v[90:93], v[172:175], v[188:191], v[90:93]
	v_mfma_f32_16x16x32_bf16 v[82:85], v[164:167], v[196:199], v[82:85]
	v_mfma_f32_16x16x32_bf16 v[74:77], v[172:175], v[196:199], v[74:77]
	v_mfma_f32_16x16x32_bf16 v[70:73], v[164:167], v[212:215], v[70:73]
	v_mfma_f32_16x16x32_bf16 v[66:69], v[172:175], v[212:215], v[66:69]
	v_mfma_f32_16x16x32_bf16 v[114:117], v[168:171], v[184:187], v[114:117]
	v_mfma_f32_16x16x32_bf16 v[106:109], v[176:179], v[184:187], v[106:109]
	v_mfma_f32_16x16x32_bf16 v[98:101], v[168:171], v[192:195], v[98:101]
	v_mfma_f32_16x16x32_bf16 v[90:93], v[176:179], v[192:195], v[90:93]
	v_mfma_f32_16x16x32_bf16 v[82:85], v[168:171], v[206:209], v[82:85]
	v_mfma_f32_16x16x32_bf16 v[74:77], v[176:179], v[206:209], v[74:77]
	v_mfma_f32_16x16x32_bf16 v[70:73], v[168:171], v[220:223], v[70:73]
	v_mfma_f32_16x16x32_bf16 v[66:69], v[176:179], v[220:223], v[66:69]
	s_setprio 0
	s_barrier
	s_add_u32 s18, s16, 0x20000
	s_addc_u32 s19, s17, 0
	s_mov_b32 m0, s36
	s_add_u32 s16, s16, 0x24000
	ds_read_b128 v[180:183], v145 offset:49152
	ds_read_b128 v[184:187], v145 offset:50176
	ds_read_b128 v[188:191], v145 offset:51200
	ds_read_b128 v[192:195], v145 offset:52224
	ds_read_b128 v[196:199], v145 offset:53248
	ds_read_b128 v[206:209], v145 offset:54272
	ds_read_b128 v[212:215], v145 offset:55296
	ds_read_b128 v[220:223], v145 offset:56320
	global_load_lds_dwordx4 v134, s[18:19]
	s_mov_b32 m0, s37
	s_addc_u32 s17, s17, 0
	global_load_lds_dwordx4 v130, s[18:19]
	s_mov_b32 m0, s38
	s_nop 0
	global_load_lds_dwordx4 v134, s[16:17]
	s_mov_b32 m0, s39
	s_nop 0
	global_load_lds_dwordx4 v130, s[16:17]
	s_mov_b32 m0, s24
	s_nop 0
	global_load_lds_dwordx4 v136, s[10:11]
	s_mov_b32 m0, s25
	s_nop 0
	global_load_lds_dwordx4 v132, s[10:11]
	s_waitcnt vmcnt(8)
	s_waitcnt lgkmcnt(0)
	s_barrier
	s_setprio 1
	s_waitcnt lgkmcnt(0)
	v_mfma_f32_16x16x32_bf16 v[62:65], v[148:151], v[180:183], v[62:65]
	v_mfma_f32_16x16x32_bf16 v[58:61], v[156:159], v[180:183], v[58:61]
	v_mfma_f32_16x16x32_bf16 v[54:57], v[148:151], v[188:191], v[54:57]
	v_mfma_f32_16x16x32_bf16 v[46:49], v[156:159], v[188:191], v[46:49]
	v_mfma_f32_16x16x32_bf16 v[38:41], v[148:151], v[196:199], v[38:41]
	v_mfma_f32_16x16x32_bf16 v[30:33], v[156:159], v[196:199], v[30:33]
	v_mfma_f32_16x16x32_bf16 v[22:25], v[148:151], v[212:215], v[22:25]
	v_mfma_f32_16x16x32_bf16 v[14:17], v[156:159], v[212:215], v[14:17]
	v_mfma_f32_16x16x32_bf16 v[62:65], v[152:155], v[184:187], v[62:65]
	v_mfma_f32_16x16x32_bf16 v[58:61], v[160:163], v[184:187], v[58:61]
	v_mfma_f32_16x16x32_bf16 v[54:57], v[152:155], v[192:195], v[54:57]
	v_mfma_f32_16x16x32_bf16 v[46:49], v[160:163], v[192:195], v[46:49]
	v_mfma_f32_16x16x32_bf16 v[38:41], v[152:155], v[206:209], v[38:41]
	v_mfma_f32_16x16x32_bf16 v[30:33], v[160:163], v[206:209], v[30:33]
	v_mfma_f32_16x16x32_bf16 v[22:25], v[152:155], v[220:223], v[22:25]
	v_mfma_f32_16x16x32_bf16 v[14:17], v[160:163], v[220:223], v[14:17]
	s_setprio 0
	s_setprio 1
	v_mfma_f32_16x16x32_bf16 v[50:53], v[164:167], v[180:183], v[50:53]
	v_mfma_f32_16x16x32_bf16 v[42:45], v[172:175], v[180:183], v[42:45]
	v_mfma_f32_16x16x32_bf16 v[34:37], v[164:167], v[188:191], v[34:37]
	v_mfma_f32_16x16x32_bf16 v[26:29], v[172:175], v[188:191], v[26:29]
	v_mfma_f32_16x16x32_bf16 v[18:21], v[164:167], v[196:199], v[18:21]
	v_mfma_f32_16x16x32_bf16 v[10:13], v[172:175], v[196:199], v[10:13]
	v_mfma_f32_16x16x32_bf16 v[6:9], v[164:167], v[212:215], v[6:9]
	v_mfma_f32_16x16x32_bf16 v[2:5], v[172:175], v[212:215], v[2:5]
	v_mfma_f32_16x16x32_bf16 v[50:53], v[168:171], v[184:187], v[50:53]
	v_mfma_f32_16x16x32_bf16 v[42:45], v[176:179], v[184:187], v[42:45]
	v_mfma_f32_16x16x32_bf16 v[34:37], v[168:171], v[192:195], v[34:37]
	v_mfma_f32_16x16x32_bf16 v[26:29], v[176:179], v[192:195], v[26:29]
	v_mfma_f32_16x16x32_bf16 v[18:21], v[168:171], v[206:209], v[18:21]
	v_mfma_f32_16x16x32_bf16 v[10:13], v[176:179], v[206:209], v[10:13]
	v_mfma_f32_16x16x32_bf16 v[6:9], v[168:171], v[220:223], v[6:9]
	v_mfma_f32_16x16x32_bf16 v[2:5], v[176:179], v[220:223], v[2:5]
	s_setprio 0
	s_barrier
	s_add_i32 s28, s28, 2
	s_add_u32 s26, s26, 0x40000
	s_addc_u32 s27, s27, 0
	s_add_u32 s6, s6, 0x10000
	s_addc_u32 s7, s7, 0
	s_cmp_gt_u32 s28, 61
	s_cbranch_scc0 .LBB0_1670
	s_lshl_b32 s1, s2, 8
	v_and_or_b32 v132, v142, 15, s22
	v_lshrrev_b32_e32 v130, 1, v142
	v_and_or_b32 v130, v130, 24, s1
	v_ashrrev_i32_e32 v133, 31, v132
	v_or_b32_e32 v134, s23, v130
	v_lshlrev_b64 v[130:131], 11, v[132:133]
	v_lshl_add_u64 v[130:131], s[8:9], 0, v[130:131]
	v_lshlrev_b32_e32 v134, 1, v134
	v_mov_b32_e32 v135, 0
	v_lshl_add_u64 v[130:131], v[130:131], 0, v[134:135]
	v_cvt_pk_bf16_f32 v126, v126, v127
	v_cvt_pk_bf16_f32 v127, v128, v129
	v_cvt_pk_bf16_f32 v128, v122, v123
	v_cvt_pk_bf16_f32 v129, v124, v125
	global_store_dwordx4 v[130:131], v[126:129], off
	v_cvt_pk_bf16_f32 v114, v114, v115
	v_cvt_pk_bf16_f32 v115, v116, v117
	v_cvt_pk_bf16_f32 v116, v106, v107
	v_or_b32_e32 v106, 16, v132
	v_ashrrev_i32_e32 v107, 31, v106
	v_lshlrev_b64 v[106:107], 11, v[106:107]
	v_lshl_add_u64 v[106:107], s[8:9], 0, v[106:107]
	v_cvt_pk_bf16_f32 v117, v108, v109
	global_store_dwordx4 v[130:131], v[114:117], off offset:256
	s_mov_b32 s1, 0x40000
	s_mov_b64 s[2:3], 0x40000
	v_lshl_add_u64 v[114:115], v[106:107], 0, v[134:135]
	v_cvt_pk_bf16_f32 v106, v118, v119
	v_cvt_pk_bf16_f32 v107, v120, v121
	v_cvt_pk_bf16_f32 v108, v110, v111
	v_cvt_pk_bf16_f32 v109, v112, v113
	global_store_dwordx4 v[114:115], v[106:109], off
	v_cvt_pk_bf16_f32 v98, v98, v99
	v_cvt_pk_bf16_f32 v99, v100, v101
	v_cvt_pk_bf16_f32 v100, v90, v91
	v_or_b32_e32 v90, 32, v132
	v_ashrrev_i32_e32 v91, 31, v90
	v_lshlrev_b64 v[90:91], 11, v[90:91]
	v_lshl_add_u64 v[90:91], s[8:9], 0, v[90:91]
	v_cvt_pk_bf16_f32 v101, v92, v93
	global_store_dwordx4 v[114:115], v[98:101], off offset:256
	s_cmpk_lt_u32 s0, 0x100
	s_nop 0
	v_lshl_add_u64 v[98:99], v[90:91], 0, v[134:135]
	v_cvt_pk_bf16_f32 v90, v102, v103
	v_cvt_pk_bf16_f32 v91, v104, v105
	v_cvt_pk_bf16_f32 v92, v94, v95
	v_cvt_pk_bf16_f32 v93, v96, v97
	global_store_dwordx4 v[98:99], v[90:93], off
	v_cvt_pk_bf16_f32 v82, v82, v83
	v_cvt_pk_bf16_f32 v83, v84, v85
	v_cvt_pk_bf16_f32 v84, v74, v75
	v_or_b32_e32 v74, 48, v132
	v_ashrrev_i32_e32 v75, 31, v74
	v_lshlrev_b64 v[74:75], 11, v[74:75]
	v_lshl_add_u64 v[74:75], s[8:9], 0, v[74:75]
	v_cvt_pk_bf16_f32 v85, v76, v77
	global_store_dwordx4 v[98:99], v[82:85], off offset:256
	s_nop 1
	v_lshl_add_u64 v[82:83], v[74:75], 0, v[134:135]
	v_cvt_pk_bf16_f32 v74, v86, v87
	v_cvt_pk_bf16_f32 v75, v88, v89
	v_cvt_pk_bf16_f32 v76, v78, v79
	v_cvt_pk_bf16_f32 v77, v80, v81
	global_store_dwordx4 v[82:83], v[74:77], off
	v_cvt_pk_bf16_f32 v70, v70, v71
	v_cvt_pk_bf16_f32 v71, v72, v73
	v_cvt_pk_bf16_f32 v72, v66, v67
	v_cvt_pk_bf16_f32 v73, v68, v69
	global_store_dwordx4 v[82:83], v[70:73], off offset:256
	v_cvt_pk_bf16_f32 v62, v62, v63
	v_cvt_pk_bf16_f32 v63, v64, v65
	v_cvt_pk_bf16_f32 v64, v58, v59
	v_add_co_u32_e32 v58, vcc, s1, v130
	v_lshl_add_u64 v[66:67], v[130:131], 0, s[2:3]
	s_nop 0
	v_addc_co_u32_e32 v59, vcc, 0, v131, vcc
	s_mov_b32 s1, 0x48000
	v_cvt_pk_bf16_f32 v65, v60, v61
	global_store_dwordx4 v[58:59], v[62:65], off
	v_cvt_pk_bf16_f32 v50, v50, v51
	v_cvt_pk_bf16_f32 v51, v52, v53
	v_cvt_pk_bf16_f32 v52, v42, v43
	v_cvt_pk_bf16_f32 v53, v44, v45
	global_store_dwordx4 v[66:67], v[50:53], off offset:256
	s_mov_b64 s[2:3], 0x48000
	v_cvt_pk_bf16_f32 v42, v54, v55
	v_cvt_pk_bf16_f32 v43, v56, v57
	v_cvt_pk_bf16_f32 v44, v46, v47
	v_add_co_u32_e32 v46, vcc, s1, v130
	v_lshl_add_u64 v[50:51], v[130:131], 0, s[2:3]
	s_nop 0
	v_addc_co_u32_e32 v47, vcc, 0, v131, vcc
	s_mov_b32 s1, 0x50000
	v_cvt_pk_bf16_f32 v45, v48, v49
	global_store_dwordx4 v[46:47], v[42:45], off
	v_cvt_pk_bf16_f32 v34, v34, v35
	v_cvt_pk_bf16_f32 v35, v36, v37
	v_cvt_pk_bf16_f32 v36, v26, v27
	v_cvt_pk_bf16_f32 v37, v28, v29
	global_store_dwordx4 v[50:51], v[34:37], off offset:256
	s_mov_b64 s[2:3], 0x50000
	v_cvt_pk_bf16_f32 v26, v38, v39
	v_cvt_pk_bf16_f32 v27, v40, v41
	v_cvt_pk_bf16_f32 v28, v30, v31
	v_add_co_u32_e32 v30, vcc, s1, v130
	v_lshl_add_u64 v[34:35], v[130:131], 0, s[2:3]
	s_nop 0
	v_addc_co_u32_e32 v31, vcc, 0, v131, vcc
	s_mov_b32 s1, 0x58000
	v_cvt_pk_bf16_f32 v29, v32, v33
	global_store_dwordx4 v[30:31], v[26:29], off
	v_cvt_pk_bf16_f32 v18, v18, v19
	v_cvt_pk_bf16_f32 v19, v20, v21
	v_cvt_pk_bf16_f32 v20, v10, v11
	v_cvt_pk_bf16_f32 v21, v12, v13
	global_store_dwordx4 v[34:35], v[18:21], off offset:256
	s_mov_b64 s[2:3], 0x58000
	v_cvt_pk_bf16_f32 v10, v22, v23
	v_cvt_pk_bf16_f32 v11, v24, v25
	v_cvt_pk_bf16_f32 v12, v14, v15
	v_add_co_u32_e32 v14, vcc, s1, v130
	v_lshl_add_u64 v[18:19], v[130:131], 0, s[2:3]
	s_nop 0
	v_addc_co_u32_e32 v15, vcc, 0, v131, vcc
	v_cvt_pk_bf16_f32 v13, v16, v17
	global_store_dwordx4 v[14:15], v[10:13], off
	v_cvt_pk_bf16_f32 v6, v6, v7
	v_cvt_pk_bf16_f32 v7, v8, v9
	v_cvt_pk_bf16_f32 v8, v2, v3
	v_cvt_pk_bf16_f32 v9, v4, v5
	global_store_dwordx4 v[18:19], v[6:9], off offset:256
	s_waitcnt vmcnt(0)
	s_cbranch_scc0 .LBB0_1673
	s_barrier

.LBB0_1691:
	ds_read_b128 v[142:145], v150
	ds_read_b128 v[154:157], v150 offset:1024
	ds_read_b128 v[158:161], v150 offset:2048
	ds_read_b128 v[162:165], v150 offset:3072
	ds_read_b128 v[166:169], v151
	ds_read_b128 v[170:173], v151 offset:1024
	ds_read_b128 v[174:177], v151 offset:2048
	ds_read_b128 v[178:181], v151 offset:3072
	s_add_u32 s24, s22, 0xfc000
	s_addc_u32 s25, s23, 0
	s_cmp_eq_u32 s46, 60
	s_cselect_b32 s28, s17, s24
	s_cselect_b32 s29, s11, s25
	s_cselect_b32 s26, s43, s44
	s_cselect_b32 s27, s7, s45
	s_add_u32 s24, s28, 0x100000
	s_addc_u32 s25, s29, 0
	s_add_i32 m0, s30, 0xc000
	ds_read_b128 v[182:185], v152
	ds_read_b128 v[186:189], v152 offset:1024
	ds_read_b128 v[190:193], v152 offset:2048
	ds_read_b128 v[194:197], v152 offset:3072
	ds_read_b128 v[206:209], v152 offset:4096
	ds_read_b128 v[212:215], v152 offset:5120
	ds_read_b128 v[220:223], v152 offset:6144
	ds_read_b128 v[224:227], v152 offset:7168
	global_load_lds_dwordx4 v138, s[22:23]
	s_add_i32 m0, s30, 0xe000
	s_nop 0
	global_load_lds_dwordx4 v140, s[22:23]
	s_waitcnt vmcnt(8)
	s_waitcnt lgkmcnt(0)
	s_barrier
	s_setprio 1
	s_waitcnt lgkmcnt(0)
	v_mfma_f32_16x16x32_bf16 v[126:129], v[142:145], v[182:185], v[126:129]
	v_mfma_f32_16x16x32_bf16 v[122:125], v[158:161], v[182:185], v[122:125]
	v_mfma_f32_16x16x32_bf16 v[110:113], v[142:145], v[190:193], v[110:113]
	v_mfma_f32_16x16x32_bf16 v[106:109], v[158:161], v[190:193], v[106:109]
	v_mfma_f32_16x16x32_bf16 v[94:97], v[142:145], v[206:209], v[94:97]
	v_mfma_f32_16x16x32_bf16 v[90:93], v[158:161], v[206:209], v[90:93]
	v_mfma_f32_16x16x32_bf16 v[78:81], v[142:145], v[220:223], v[78:81]
	v_mfma_f32_16x16x32_bf16 v[74:77], v[158:161], v[220:223], v[74:77]
	v_mfma_f32_16x16x32_bf16 v[126:129], v[154:157], v[186:189], v[126:129]
	v_mfma_f32_16x16x32_bf16 v[122:125], v[162:165], v[186:189], v[122:125]
	v_mfma_f32_16x16x32_bf16 v[110:113], v[154:157], v[194:197], v[110:113]
	v_mfma_f32_16x16x32_bf16 v[106:109], v[162:165], v[194:197], v[106:109]
	v_mfma_f32_16x16x32_bf16 v[94:97], v[154:157], v[212:215], v[94:97]
	v_mfma_f32_16x16x32_bf16 v[90:93], v[162:165], v[212:215], v[90:93]
	v_mfma_f32_16x16x32_bf16 v[78:81], v[154:157], v[224:227], v[78:81]
	v_mfma_f32_16x16x32_bf16 v[74:77], v[162:165], v[224:227], v[74:77]
	s_setprio 0
	s_setprio 1
	v_mfma_f32_16x16x32_bf16 v[118:121], v[166:169], v[182:185], v[118:121]
	v_mfma_f32_16x16x32_bf16 v[114:117], v[174:177], v[182:185], v[114:117]
	v_mfma_f32_16x16x32_bf16 v[102:105], v[166:169], v[190:193], v[102:105]
	v_mfma_f32_16x16x32_bf16 v[98:101], v[174:177], v[190:193], v[98:101]
	v_mfma_f32_16x16x32_bf16 v[86:89], v[166:169], v[206:209], v[86:89]
	v_mfma_f32_16x16x32_bf16 v[82:85], v[174:177], v[206:209], v[82:85]
	v_mfma_f32_16x16x32_bf16 v[70:73], v[166:169], v[220:223], v[70:73]
	v_mfma_f32_16x16x32_bf16 v[66:69], v[174:177], v[220:223], v[66:69]
	v_mfma_f32_16x16x32_bf16 v[118:121], v[170:173], v[186:189], v[118:121]
	v_mfma_f32_16x16x32_bf16 v[114:117], v[178:181], v[186:189], v[114:117]
	v_mfma_f32_16x16x32_bf16 v[102:105], v[170:173], v[194:197], v[102:105]
	v_mfma_f32_16x16x32_bf16 v[98:101], v[178:181], v[194:197], v[98:101]
	v_mfma_f32_16x16x32_bf16 v[86:89], v[170:173], v[212:215], v[86:89]
	v_mfma_f32_16x16x32_bf16 v[82:85], v[178:181], v[212:215], v[82:85]
	v_mfma_f32_16x16x32_bf16 v[70:73], v[170:173], v[224:227], v[70:73]
	v_mfma_f32_16x16x32_bf16 v[66:69], v[178:181], v[224:227], v[66:69]
	s_setprio 0
	s_barrier
	s_add_i32 s47, s40, s1
	s_mov_b32 m0, s47
	ds_read_b128 v[182:185], v152 offset:16384
	ds_read_b128 v[186:189], v152 offset:17408
	ds_read_b128 v[190:193], v152 offset:18432
	ds_read_b128 v[194:197], v152 offset:19456
	ds_read_b128 v[206:209], v152 offset:20480
	ds_read_b128 v[212:215], v152 offset:21504
	ds_read_b128 v[220:223], v152 offset:22528
	ds_read_b128 v[224:227], v152 offset:23552
	global_load_lds_dwordx4 v132, s[26:27]
	s_add_i32 m0, s47, 0x2000
	s_add_u32 s48, s26, 0x4000
	s_addc_u32 s49, s27, 0
	s_add_i32 s47, s41, s1
	global_load_lds_dwordx4 v136, s[26:27]
	s_mov_b32 m0, s47
	s_nop 0
	global_load_lds_dwordx4 v132, s[48:49]
	s_add_i32 m0, s47, 0x2000
	s_nop 0
	global_load_lds_dwordx4 v136, s[48:49]
	s_mov_b32 m0, s30
	s_nop 0
	global_load_lds_dwordx4 v130, s[28:29]
	s_mov_b32 m0, s31
	s_nop 0
	global_load_lds_dwordx4 v134, s[28:29]
	s_waitcnt vmcnt(8)
	s_waitcnt lgkmcnt(0)
	s_barrier
	s_setprio 1
	s_waitcnt lgkmcnt(0)
	v_mfma_f32_16x16x32_bf16 v[62:65], v[142:145], v[182:185], v[62:65]
	v_mfma_f32_16x16x32_bf16 v[58:61], v[158:161], v[182:185], v[58:61]
	v_mfma_f32_16x16x32_bf16 v[46:49], v[142:145], v[190:193], v[46:49]
	v_mfma_f32_16x16x32_bf16 v[42:45], v[158:161], v[190:193], v[42:45]
	v_mfma_f32_16x16x32_bf16 v[30:33], v[142:145], v[206:209], v[30:33]
	v_mfma_f32_16x16x32_bf16 v[26:29], v[158:161], v[206:209], v[26:29]
	v_mfma_f32_16x16x32_bf16 v[14:17], v[142:145], v[220:223], v[14:17]
	v_mfma_f32_16x16x32_bf16 v[10:13], v[158:161], v[220:223], v[10:13]
	v_mfma_f32_16x16x32_bf16 v[62:65], v[154:157], v[186:189], v[62:65]
	v_mfma_f32_16x16x32_bf16 v[58:61], v[162:165], v[186:189], v[58:61]
	v_mfma_f32_16x16x32_bf16 v[46:49], v[154:157], v[194:197], v[46:49]
	v_mfma_f32_16x16x32_bf16 v[42:45], v[162:165], v[194:197], v[42:45]
	v_mfma_f32_16x16x32_bf16 v[30:33], v[154:157], v[212:215], v[30:33]
	v_mfma_f32_16x16x32_bf16 v[26:29], v[162:165], v[212:215], v[26:29]
	v_mfma_f32_16x16x32_bf16 v[14:17], v[154:157], v[224:227], v[14:17]
	v_mfma_f32_16x16x32_bf16 v[10:13], v[162:165], v[224:227], v[10:13]
	s_setprio 0
	s_setprio 1
	v_mfma_f32_16x16x32_bf16 v[54:57], v[166:169], v[182:185], v[54:57]
	v_mfma_f32_16x16x32_bf16 v[50:53], v[174:177], v[182:185], v[50:53]
	v_mfma_f32_16x16x32_bf16 v[38:41], v[166:169], v[190:193], v[38:41]
	v_mfma_f32_16x16x32_bf16 v[34:37], v[174:177], v[190:193], v[34:37]
	v_mfma_f32_16x16x32_bf16 v[22:25], v[166:169], v[206:209], v[22:25]
	v_mfma_f32_16x16x32_bf16 v[18:21], v[174:177], v[206:209], v[18:21]
	v_mfma_f32_16x16x32_bf16 v[6:9], v[166:169], v[220:223], v[6:9]
	v_mfma_f32_16x16x32_bf16 v[2:5], v[174:177], v[220:223], v[2:5]
	v_mfma_f32_16x16x32_bf16 v[54:57], v[170:173], v[186:189], v[54:57]
	v_mfma_f32_16x16x32_bf16 v[50:53], v[178:181], v[186:189], v[50:53]
	v_mfma_f32_16x16x32_bf16 v[38:41], v[170:173], v[194:197], v[38:41]
	v_mfma_f32_16x16x32_bf16 v[34:37], v[178:181], v[194:197], v[34:37]
	v_mfma_f32_16x16x32_bf16 v[22:25], v[170:173], v[212:215], v[22:25]
	v_mfma_f32_16x16x32_bf16 v[18:21], v[178:181], v[212:215], v[18:21]
	v_mfma_f32_16x16x32_bf16 v[6:9], v[170:173], v[224:227], v[6:9]
	v_mfma_f32_16x16x32_bf16 v[2:5], v[178:181], v[224:227], v[2:5]
	s_setprio 0
	s_barrier
	s_add_i32 s47, 0, 0x18000
	v_add_u32_e32 v146, s47, v149
	s_add_i32 s48, 0, 0x1c000
	ds_read_b128 v[142:145], v146
	ds_read_b128 v[154:157], v146 offset:1024
	ds_read_b128 v[158:161], v146 offset:2048
	ds_read_b128 v[162:165], v146 offset:3072
	v_add_u32_e32 v146, s48, v149
	ds_read_b128 v[166:169], v146
	ds_read_b128 v[170:173], v146 offset:1024
	ds_read_b128 v[174:177], v146 offset:2048
	ds_read_b128 v[178:181], v146 offset:3072
	s_add_u32 s28, s28, 0x4000
	s_addc_u32 s29, s29, 0
	s_mov_b32 m0, s33
	ds_read_b128 v[182:185], v152 offset:32768
	ds_read_b128 v[186:189], v152 offset:33792
	ds_read_b128 v[190:193], v152 offset:34816
	ds_read_b128 v[194:197], v152 offset:35840
	ds_read_b128 v[206:209], v152 offset:36864
	ds_read_b128 v[212:215], v152 offset:37888
	ds_read_b128 v[220:223], v152 offset:38912
	ds_read_b128 v[224:227], v152 offset:39936
	global_load_lds_dwordx4 v130, s[28:29]
	s_mov_b32 m0, s34
	s_nop 0
	global_load_lds_dwordx4 v134, s[28:29]
	s_waitcnt vmcnt(8)
	s_waitcnt lgkmcnt(0)
	s_barrier
	s_setprio 1
	s_waitcnt lgkmcnt(0)
	v_mfma_f32_16x16x32_bf16 v[126:129], v[142:145], v[182:185], v[126:129]
	v_mfma_f32_16x16x32_bf16 v[122:125], v[158:161], v[182:185], v[122:125]
	v_mfma_f32_16x16x32_bf16 v[110:113], v[142:145], v[190:193], v[110:113]
	v_mfma_f32_16x16x32_bf16 v[106:109], v[158:161], v[190:193], v[106:109]
	v_mfma_f32_16x16x32_bf16 v[94:97], v[142:145], v[206:209], v[94:97]
	v_mfma_f32_16x16x32_bf16 v[90:93], v[158:161], v[206:209], v[90:93]
	v_mfma_f32_16x16x32_bf16 v[78:81], v[142:145], v[220:223], v[78:81]
	v_mfma_f32_16x16x32_bf16 v[74:77], v[158:161], v[220:223], v[74:77]
	v_mfma_f32_16x16x32_bf16 v[126:129], v[154:157], v[186:189], v[126:129]
	v_mfma_f32_16x16x32_bf16 v[122:125], v[162:165], v[186:189], v[122:125]
	v_mfma_f32_16x16x32_bf16 v[110:113], v[154:157], v[194:197], v[110:113]
	v_mfma_f32_16x16x32_bf16 v[106:109], v[162:165], v[194:197], v[106:109]
	v_mfma_f32_16x16x32_bf16 v[94:97], v[154:157], v[212:215], v[94:97]
	v_mfma_f32_16x16x32_bf16 v[90:93], v[162:165], v[212:215], v[90:93]
	v_mfma_f32_16x16x32_bf16 v[78:81], v[154:157], v[224:227], v[78:81]
	v_mfma_f32_16x16x32_bf16 v[74:77], v[162:165], v[224:227], v[74:77]
	s_setprio 0
	s_setprio 1
	v_mfma_f32_16x16x32_bf16 v[118:121], v[166:169], v[182:185], v[118:121]
	v_mfma_f32_16x16x32_bf16 v[114:117], v[174:177], v[182:185], v[114:117]
	v_mfma_f32_16x16x32_bf16 v[102:105], v[166:169], v[190:193], v[102:105]
	v_mfma_f32_16x16x32_bf16 v[98:101], v[174:177], v[190:193], v[98:101]
	v_mfma_f32_16x16x32_bf16 v[86:89], v[166:169], v[206:209], v[86:89]
	v_mfma_f32_16x16x32_bf16 v[82:85], v[174:177], v[206:209], v[82:85]
	v_mfma_f32_16x16x32_bf16 v[70:73], v[166:169], v[220:223], v[70:73]
	v_mfma_f32_16x16x32_bf16 v[66:69], v[174:177], v[220:223], v[66:69]
	v_mfma_f32_16x16x32_bf16 v[118:121], v[170:173], v[186:189], v[118:121]
	v_mfma_f32_16x16x32_bf16 v[114:117], v[178:181], v[186:189], v[114:117]
	v_mfma_f32_16x16x32_bf16 v[102:105], v[170:173], v[194:197], v[102:105]
	v_mfma_f32_16x16x32_bf16 v[98:101], v[178:181], v[194:197], v[98:101]
	v_mfma_f32_16x16x32_bf16 v[86:89], v[170:173], v[212:215], v[86:89]
	v_mfma_f32_16x16x32_bf16 v[82:85], v[178:181], v[212:215], v[82:85]
	v_mfma_f32_16x16x32_bf16 v[70:73], v[170:173], v[224:227], v[70:73]
	v_mfma_f32_16x16x32_bf16 v[66:69], v[178:181], v[224:227], v[66:69]
	s_setprio 0
	s_barrier
	s_add_u32 s28, s26, 0x10000
	s_addc_u32 s29, s27, 0
	s_add_i32 s47, s47, s1
	s_mov_b32 m0, s47
	ds_read_b128 v[182:185], v152 offset:49152
	ds_read_b128 v[186:189], v152 offset:50176
	ds_read_b128 v[190:193], v152 offset:51200
	ds_read_b128 v[194:197], v152 offset:52224
	ds_read_b128 v[206:209], v152 offset:53248
	ds_read_b128 v[212:215], v152 offset:54272
	ds_read_b128 v[220:223], v152 offset:55296
	ds_read_b128 v[224:227], v152 offset:56320
	global_load_lds_dwordx4 v132, s[28:29]
	s_add_i32 m0, s47, 0x2000
	s_add_u32 s26, s26, 0x14000
	s_addc_u32 s27, s27, 0
	global_load_lds_dwordx4 v136, s[28:29]
	s_add_i32 s28, s48, s1
	s_mov_b32 m0, s28
	s_nop 0
	global_load_lds_dwordx4 v132, s[26:27]
	s_add_i32 m0, s28, 0x2000
	s_nop 0
	global_load_lds_dwordx4 v136, s[26:27]
	s_mov_b32 m0, s38
	s_nop 0
	global_load_lds_dwordx4 v130, s[24:25]
	s_mov_b32 m0, s39
	s_nop 0
	global_load_lds_dwordx4 v134, s[24:25]
	s_waitcnt vmcnt(8)
	s_waitcnt lgkmcnt(0)
	s_barrier
	s_setprio 1
	s_waitcnt lgkmcnt(0)
	v_mfma_f32_16x16x32_bf16 v[62:65], v[142:145], v[182:185], v[62:65]
	v_mfma_f32_16x16x32_bf16 v[58:61], v[158:161], v[182:185], v[58:61]
	v_mfma_f32_16x16x32_bf16 v[46:49], v[142:145], v[190:193], v[46:49]
	v_mfma_f32_16x16x32_bf16 v[42:45], v[158:161], v[190:193], v[42:45]
	v_mfma_f32_16x16x32_bf16 v[30:33], v[142:145], v[206:209], v[30:33]
	v_mfma_f32_16x16x32_bf16 v[26:29], v[158:161], v[206:209], v[26:29]
	v_mfma_f32_16x16x32_bf16 v[14:17], v[142:145], v[220:223], v[14:17]
	v_mfma_f32_16x16x32_bf16 v[10:13], v[158:161], v[220:223], v[10:13]
	v_mfma_f32_16x16x32_bf16 v[62:65], v[154:157], v[186:189], v[62:65]
	v_mfma_f32_16x16x32_bf16 v[58:61], v[162:165], v[186:189], v[58:61]
	v_mfma_f32_16x16x32_bf16 v[46:49], v[154:157], v[194:197], v[46:49]
	v_mfma_f32_16x16x32_bf16 v[42:45], v[162:165], v[194:197], v[42:45]
	v_mfma_f32_16x16x32_bf16 v[30:33], v[154:157], v[212:215], v[30:33]
	v_mfma_f32_16x16x32_bf16 v[26:29], v[162:165], v[212:215], v[26:29]
	v_mfma_f32_16x16x32_bf16 v[14:17], v[154:157], v[224:227], v[14:17]
	v_mfma_f32_16x16x32_bf16 v[10:13], v[162:165], v[224:227], v[10:13]
	s_setprio 0
	s_setprio 1
	v_mfma_f32_16x16x32_bf16 v[54:57], v[166:169], v[182:185], v[54:57]
	v_mfma_f32_16x16x32_bf16 v[50:53], v[174:177], v[182:185], v[50:53]
	v_mfma_f32_16x16x32_bf16 v[38:41], v[166:169], v[190:193], v[38:41]
	v_mfma_f32_16x16x32_bf16 v[34:37], v[174:177], v[190:193], v[34:37]
	v_mfma_f32_16x16x32_bf16 v[22:25], v[166:169], v[206:209], v[22:25]
	v_mfma_f32_16x16x32_bf16 v[18:21], v[174:177], v[206:209], v[18:21]
	v_mfma_f32_16x16x32_bf16 v[6:9], v[166:169], v[220:223], v[6:9]
	v_mfma_f32_16x16x32_bf16 v[2:5], v[174:177], v[220:223], v[2:5]
	v_mfma_f32_16x16x32_bf16 v[54:57], v[170:173], v[186:189], v[54:57]
	v_mfma_f32_16x16x32_bf16 v[50:53], v[178:181], v[186:189], v[50:53]
	v_mfma_f32_16x16x32_bf16 v[38:41], v[170:173], v[194:197], v[38:41]
	v_mfma_f32_16x16x32_bf16 v[34:37], v[178:181], v[194:197], v[34:37]
	v_mfma_f32_16x16x32_bf16 v[22:25], v[170:173], v[212:215], v[22:25]
	v_mfma_f32_16x16x32_bf16 v[18:21], v[178:181], v[212:215], v[18:21]
	v_mfma_f32_16x16x32_bf16 v[6:9], v[170:173], v[224:227], v[6:9]
	v_mfma_f32_16x16x32_bf16 v[2:5], v[178:181], v[224:227], v[2:5]
	s_setprio 0
	s_barrier
	s_add_i32 s46, s46, 2
	s_add_u32 s44, s44, 0x20000
	s_addc_u32 s45, s45, 0
	s_add_u32 s22, s22, 0x200000
	s_addc_u32 s23, s23, 0
	s_cmp_gt_u32 s46, 61
	s_cbranch_scc0 .LBB0_1691
	s_lshl_b32 s7, s10, 8
	v_mov_b32_e32 v144, v147
	s_add_i32 s7, s7, s36
	v_cndmask_b32_e64 v145, 0, 1, s[2:3]
	v_and_or_b32 v142, v144, 15, s7
	v_ashrrev_i32_e32 v143, 31, v142
	v_mov_b32_e32 v146, 0x3e0293ee
	v_cmp_ne_u32_e64 s[10:11], 1, v145
	s_andn2_b64 vcc, exec, s[2:3]
	v_mov_b32_e32 v148, 0x3e0293ee
	s_cbranch_vccnz .LBB0_1694
	v_readlane_b32 s22, v245, 16
	v_readlane_b32 s23, v245, 17
	s_nop 1
	v_lshl_add_u64 v[154:155], v[142:143], 2, s[22:23]
	global_load_dword v145, v[154:155], off
	s_waitcnt vmcnt(0)
	v_mul_f32_e32 v148, 0x3e0293ee, v145

.LBB0_1718:
	ds_read_b128 v[152:155], v147
	ds_read_b128 v[156:159], v147 offset:1024
	ds_read_b128 v[160:163], v147 offset:2048
	ds_read_b128 v[164:167], v147 offset:3072
	ds_read_b128 v[168:171], v148
	ds_read_b128 v[172:175], v148 offset:1024
	ds_read_b128 v[176:179], v148 offset:2048
	ds_read_b128 v[180:183], v148 offset:3072
	s_add_u32 s18, s16, 0x4000
	s_addc_u32 s19, s17, 0
	s_cmp_eq_u32 s50, 60
	s_cselect_b32 s22, s14, s18
	s_cselect_b32 s23, s15, s19
	s_cselect_b32 s20, s47, s48
	s_cselect_b32 s21, s46, s49
	s_add_u32 s18, s22, 0x8000
	s_addc_u32 s19, s23, 0
	s_mov_b32 m0, s31
	ds_read_b128 v[184:187], v149
	ds_read_b128 v[188:191], v149 offset:1024
	ds_read_b128 v[192:195], v149 offset:2048
	ds_read_b128 v[196:199], v149 offset:3072
	ds_read_b128 v[206:209], v149 offset:4096
	ds_read_b128 v[212:215], v149 offset:5120
	ds_read_b128 v[220:223], v149 offset:6144
	ds_read_b128 v[224:227], v149 offset:7168
	global_load_lds_dwordx4 v140, s[16:17]
	s_mov_b32 m0, s33
	s_nop 0
	global_load_lds_dwordx4 v142, s[16:17]
	s_waitcnt vmcnt(8)
	s_waitcnt lgkmcnt(0)
	s_barrier
	s_setprio 1
	s_waitcnt lgkmcnt(0)
	v_mfma_f32_16x16x32_bf16 v[126:129], v[152:155], v[184:187], v[126:129]
	v_mfma_f32_16x16x32_bf16 v[122:125], v[160:163], v[184:187], v[122:125]
	v_mfma_f32_16x16x32_bf16 v[118:121], v[152:155], v[192:195], v[118:121]
	v_mfma_f32_16x16x32_bf16 v[110:113], v[160:163], v[192:195], v[110:113]
	v_mfma_f32_16x16x32_bf16 v[102:105], v[152:155], v[206:209], v[102:105]
	v_mfma_f32_16x16x32_bf16 v[94:97], v[160:163], v[206:209], v[94:97]
	v_mfma_f32_16x16x32_bf16 v[86:89], v[152:155], v[220:223], v[86:89]
	v_mfma_f32_16x16x32_bf16 v[78:81], v[160:163], v[220:223], v[78:81]
	v_mfma_f32_16x16x32_bf16 v[126:129], v[156:159], v[188:191], v[126:129]
	v_mfma_f32_16x16x32_bf16 v[122:125], v[164:167], v[188:191], v[122:125]
	v_mfma_f32_16x16x32_bf16 v[118:121], v[156:159], v[196:199], v[118:121]
	v_mfma_f32_16x16x32_bf16 v[110:113], v[164:167], v[196:199], v[110:113]
	v_mfma_f32_16x16x32_bf16 v[102:105], v[156:159], v[212:215], v[102:105]
	v_mfma_f32_16x16x32_bf16 v[94:97], v[164:167], v[212:215], v[94:97]
	v_mfma_f32_16x16x32_bf16 v[86:89], v[156:159], v[224:227], v[86:89]
	v_mfma_f32_16x16x32_bf16 v[78:81], v[164:167], v[224:227], v[78:81]
	s_setprio 0
	s_setprio 1
	v_mfma_f32_16x16x32_bf16 v[114:117], v[168:171], v[184:187], v[114:117]
	v_mfma_f32_16x16x32_bf16 v[106:109], v[176:179], v[184:187], v[106:109]
	v_mfma_f32_16x16x32_bf16 v[98:101], v[168:171], v[192:195], v[98:101]
	v_mfma_f32_16x16x32_bf16 v[90:93], v[176:179], v[192:195], v[90:93]
	v_mfma_f32_16x16x32_bf16 v[82:85], v[168:171], v[206:209], v[82:85]
	v_mfma_f32_16x16x32_bf16 v[74:77], v[176:179], v[206:209], v[74:77]
	v_mfma_f32_16x16x32_bf16 v[70:73], v[168:171], v[220:223], v[70:73]
	v_mfma_f32_16x16x32_bf16 v[66:69], v[176:179], v[220:223], v[66:69]
	v_mfma_f32_16x16x32_bf16 v[114:117], v[172:175], v[188:191], v[114:117]
	v_mfma_f32_16x16x32_bf16 v[106:109], v[180:183], v[188:191], v[106:109]
	v_mfma_f32_16x16x32_bf16 v[98:101], v[172:175], v[196:199], v[98:101]
	v_mfma_f32_16x16x32_bf16 v[90:93], v[180:183], v[196:199], v[90:93]
	v_mfma_f32_16x16x32_bf16 v[82:85], v[172:175], v[212:215], v[82:85]
	v_mfma_f32_16x16x32_bf16 v[74:77], v[180:183], v[212:215], v[74:77]
	v_mfma_f32_16x16x32_bf16 v[70:73], v[172:175], v[224:227], v[70:73]
	v_mfma_f32_16x16x32_bf16 v[66:69], v[180:183], v[224:227], v[66:69]
	s_setprio 0
	s_barrier
	s_mov_b32 m0, s36
	s_add_u32 s52, s20, 0x4000
	ds_read_b128 v[184:187], v149 offset:16384
	ds_read_b128 v[188:191], v149 offset:17408
	ds_read_b128 v[192:195], v149 offset:18432
	ds_read_b128 v[196:199], v149 offset:19456
	ds_read_b128 v[206:209], v149 offset:20480
	ds_read_b128 v[212:215], v149 offset:21504
	ds_read_b128 v[220:223], v149 offset:22528
	ds_read_b128 v[224:227], v149 offset:23552
	global_load_lds_dwordx4 v134, s[20:21]
	s_mov_b32 m0, s37
	s_addc_u32 s53, s21, 0
	global_load_lds_dwordx4 v130, s[20:21]
	s_mov_b32 m0, s38
	s_nop 0
	global_load_lds_dwordx4 v134, s[52:53]
	s_mov_b32 m0, s39
	s_nop 0
	global_load_lds_dwordx4 v130, s[52:53]
	s_mov_b32 m0, s1
	s_nop 0
	global_load_lds_dwordx4 v136, s[22:23]
	s_mov_b32 m0, s24
	s_nop 0
	global_load_lds_dwordx4 v132, s[22:23]
	s_waitcnt vmcnt(8)
	s_waitcnt lgkmcnt(0)
	s_barrier
	s_setprio 1
	s_waitcnt lgkmcnt(0)
	v_mfma_f32_16x16x32_bf16 v[62:65], v[152:155], v[184:187], v[62:65]
	v_mfma_f32_16x16x32_bf16 v[58:61], v[160:163], v[184:187], v[58:61]
	v_mfma_f32_16x16x32_bf16 v[54:57], v[152:155], v[192:195], v[54:57]
	v_mfma_f32_16x16x32_bf16 v[46:49], v[160:163], v[192:195], v[46:49]
	v_mfma_f32_16x16x32_bf16 v[38:41], v[152:155], v[206:209], v[38:41]
	v_mfma_f32_16x16x32_bf16 v[30:33], v[160:163], v[206:209], v[30:33]
	v_mfma_f32_16x16x32_bf16 v[22:25], v[152:155], v[220:223], v[22:25]
	v_mfma_f32_16x16x32_bf16 v[14:17], v[160:163], v[220:223], v[14:17]
	v_mfma_f32_16x16x32_bf16 v[62:65], v[156:159], v[188:191], v[62:65]
	v_mfma_f32_16x16x32_bf16 v[58:61], v[164:167], v[188:191], v[58:61]
	v_mfma_f32_16x16x32_bf16 v[54:57], v[156:159], v[196:199], v[54:57]
	v_mfma_f32_16x16x32_bf16 v[46:49], v[164:167], v[196:199], v[46:49]
	v_mfma_f32_16x16x32_bf16 v[38:41], v[156:159], v[212:215], v[38:41]
	v_mfma_f32_16x16x32_bf16 v[30:33], v[164:167], v[212:215], v[30:33]
	v_mfma_f32_16x16x32_bf16 v[22:25], v[156:159], v[224:227], v[22:25]
	v_mfma_f32_16x16x32_bf16 v[14:17], v[164:167], v[224:227], v[14:17]
	s_setprio 0
	s_setprio 1
	v_mfma_f32_16x16x32_bf16 v[50:53], v[168:171], v[184:187], v[50:53]
	v_mfma_f32_16x16x32_bf16 v[42:45], v[176:179], v[184:187], v[42:45]
	v_mfma_f32_16x16x32_bf16 v[34:37], v[168:171], v[192:195], v[34:37]
	v_mfma_f32_16x16x32_bf16 v[26:29], v[176:179], v[192:195], v[26:29]
	v_mfma_f32_16x16x32_bf16 v[18:21], v[168:171], v[206:209], v[18:21]
	v_mfma_f32_16x16x32_bf16 v[10:13], v[176:179], v[206:209], v[10:13]
	v_mfma_f32_16x16x32_bf16 v[6:9], v[168:171], v[220:223], v[6:9]
	v_mfma_f32_16x16x32_bf16 v[2:5], v[176:179], v[220:223], v[2:5]
	v_mfma_f32_16x16x32_bf16 v[50:53], v[172:175], v[188:191], v[50:53]
	v_mfma_f32_16x16x32_bf16 v[42:45], v[180:183], v[188:191], v[42:45]
	v_mfma_f32_16x16x32_bf16 v[34:37], v[172:175], v[196:199], v[34:37]
	v_mfma_f32_16x16x32_bf16 v[26:29], v[180:183], v[196:199], v[26:29]
	v_mfma_f32_16x16x32_bf16 v[18:21], v[172:175], v[212:215], v[18:21]
	v_mfma_f32_16x16x32_bf16 v[10:13], v[180:183], v[212:215], v[10:13]
	v_mfma_f32_16x16x32_bf16 v[6:9], v[172:175], v[224:227], v[6:9]
	v_mfma_f32_16x16x32_bf16 v[2:5], v[180:183], v[224:227], v[2:5]
	s_setprio 0
	s_barrier
	ds_read_b128 v[152:155], v150
	ds_read_b128 v[156:159], v150 offset:1024
	ds_read_b128 v[160:163], v150 offset:2048
	ds_read_b128 v[164:167], v150 offset:3072
	ds_read_b128 v[168:171], v151
	ds_read_b128 v[172:175], v151 offset:1024
	ds_read_b128 v[176:179], v151 offset:2048
	ds_read_b128 v[180:183], v151 offset:3072
	s_add_u32 s22, s22, 0x4000
	s_addc_u32 s23, s23, 0
	s_mov_b32 m0, s25
	ds_read_b128 v[184:187], v149 offset:32768
	ds_read_b128 v[188:191], v149 offset:33792
	ds_read_b128 v[192:195], v149 offset:34816
	ds_read_b128 v[196:199], v149 offset:35840
	ds_read_b128 v[206:209], v149 offset:36864
	ds_read_b128 v[212:215], v149 offset:37888
	ds_read_b128 v[220:223], v149 offset:38912
	ds_read_b128 v[224:227], v149 offset:39936
	global_load_lds_dwordx4 v136, s[22:23]
	s_mov_b32 m0, s26
	s_nop 0
	global_load_lds_dwordx4 v132, s[22:23]
	s_waitcnt vmcnt(8)
	s_waitcnt lgkmcnt(0)
	s_barrier
	s_setprio 1
	s_waitcnt lgkmcnt(0)
	v_mfma_f32_16x16x32_bf16 v[126:129], v[152:155], v[184:187], v[126:129]
	v_mfma_f32_16x16x32_bf16 v[122:125], v[160:163], v[184:187], v[122:125]
	v_mfma_f32_16x16x32_bf16 v[118:121], v[152:155], v[192:195], v[118:121]
	v_mfma_f32_16x16x32_bf16 v[110:113], v[160:163], v[192:195], v[110:113]
	v_mfma_f32_16x16x32_bf16 v[102:105], v[152:155], v[206:209], v[102:105]
	v_mfma_f32_16x16x32_bf16 v[94:97], v[160:163], v[206:209], v[94:97]
	v_mfma_f32_16x16x32_bf16 v[86:89], v[152:155], v[220:223], v[86:89]
	v_mfma_f32_16x16x32_bf16 v[78:81], v[160:163], v[220:223], v[78:81]
	v_mfma_f32_16x16x32_bf16 v[126:129], v[156:159], v[188:191], v[126:129]
	v_mfma_f32_16x16x32_bf16 v[122:125], v[164:167], v[188:191], v[122:125]
	v_mfma_f32_16x16x32_bf16 v[118:121], v[156:159], v[196:199], v[118:121]
	v_mfma_f32_16x16x32_bf16 v[110:113], v[164:167], v[196:199], v[110:113]
	v_mfma_f32_16x16x32_bf16 v[102:105], v[156:159], v[212:215], v[102:105]
	v_mfma_f32_16x16x32_bf16 v[94:97], v[164:167], v[212:215], v[94:97]
	v_mfma_f32_16x16x32_bf16 v[86:89], v[156:159], v[224:227], v[86:89]
	v_mfma_f32_16x16x32_bf16 v[78:81], v[164:167], v[224:227], v[78:81]
	s_setprio 0
	s_setprio 1
	v_mfma_f32_16x16x32_bf16 v[114:117], v[168:171], v[184:187], v[114:117]
	v_mfma_f32_16x16x32_bf16 v[106:109], v[176:179], v[184:187], v[106:109]
	v_mfma_f32_16x16x32_bf16 v[98:101], v[168:171], v[192:195], v[98:101]
	v_mfma_f32_16x16x32_bf16 v[90:93], v[176:179], v[192:195], v[90:93]
	v_mfma_f32_16x16x32_bf16 v[82:85], v[168:171], v[206:209], v[82:85]
	v_mfma_f32_16x16x32_bf16 v[74:77], v[176:179], v[206:209], v[74:77]
	v_mfma_f32_16x16x32_bf16 v[70:73], v[168:171], v[220:223], v[70:73]
	v_mfma_f32_16x16x32_bf16 v[66:69], v[176:179], v[220:223], v[66:69]
	v_mfma_f32_16x16x32_bf16 v[114:117], v[172:175], v[188:191], v[114:117]
	v_mfma_f32_16x16x32_bf16 v[106:109], v[180:183], v[188:191], v[106:109]
	v_mfma_f32_16x16x32_bf16 v[98:101], v[172:175], v[196:199], v[98:101]
	v_mfma_f32_16x16x32_bf16 v[90:93], v[180:183], v[196:199], v[90:93]
	v_mfma_f32_16x16x32_bf16 v[82:85], v[172:175], v[212:215], v[82:85]
	v_mfma_f32_16x16x32_bf16 v[74:77], v[180:183], v[212:215], v[74:77]
	v_mfma_f32_16x16x32_bf16 v[70:73], v[172:175], v[224:227], v[70:73]
	v_mfma_f32_16x16x32_bf16 v[66:69], v[180:183], v[224:227], v[66:69]
	s_setprio 0
	s_barrier
	s_add_u32 s22, s20, 0x20000
	s_addc_u32 s23, s21, 0
	s_mov_b32 m0, s40
	s_add_u32 s20, s20, 0x24000
	ds_read_b128 v[184:187], v149 offset:49152
	ds_read_b128 v[188:191], v149 offset:50176
	ds_read_b128 v[192:195], v149 offset:51200
	ds_read_b128 v[196:199], v149 offset:52224
	ds_read_b128 v[206:209], v149 offset:53248
	ds_read_b128 v[212:215], v149 offset:54272
	ds_read_b128 v[220:223], v149 offset:55296
	ds_read_b128 v[224:227], v149 offset:56320
	global_load_lds_dwordx4 v134, s[22:23]
	s_mov_b32 m0, s41
	s_addc_u32 s21, s21, 0
	global_load_lds_dwordx4 v130, s[22:23]
	s_mov_b32 m0, s42
	s_nop 0
	global_load_lds_dwordx4 v134, s[20:21]
	s_mov_b32 m0, s43
	s_nop 0
	global_load_lds_dwordx4 v130, s[20:21]
	s_mov_b32 m0, s29
	s_nop 0
	global_load_lds_dwordx4 v136, s[18:19]
	s_mov_b32 m0, s30
	s_nop 0
	global_load_lds_dwordx4 v132, s[18:19]
	s_waitcnt vmcnt(8)
	s_waitcnt lgkmcnt(0)
	s_barrier
	s_setprio 1
	s_waitcnt lgkmcnt(0)
	v_mfma_f32_16x16x32_bf16 v[62:65], v[152:155], v[184:187], v[62:65]
	v_mfma_f32_16x16x32_bf16 v[58:61], v[160:163], v[184:187], v[58:61]
	v_mfma_f32_16x16x32_bf16 v[54:57], v[152:155], v[192:195], v[54:57]
	v_mfma_f32_16x16x32_bf16 v[46:49], v[160:163], v[192:195], v[46:49]
	v_mfma_f32_16x16x32_bf16 v[38:41], v[152:155], v[206:209], v[38:41]
	v_mfma_f32_16x16x32_bf16 v[30:33], v[160:163], v[206:209], v[30:33]
	v_mfma_f32_16x16x32_bf16 v[22:25], v[152:155], v[220:223], v[22:25]
	v_mfma_f32_16x16x32_bf16 v[14:17], v[160:163], v[220:223], v[14:17]
	v_mfma_f32_16x16x32_bf16 v[62:65], v[156:159], v[188:191], v[62:65]
	v_mfma_f32_16x16x32_bf16 v[58:61], v[164:167], v[188:191], v[58:61]
	v_mfma_f32_16x16x32_bf16 v[54:57], v[156:159], v[196:199], v[54:57]
	v_mfma_f32_16x16x32_bf16 v[46:49], v[164:167], v[196:199], v[46:49]
	v_mfma_f32_16x16x32_bf16 v[38:41], v[156:159], v[212:215], v[38:41]
	v_mfma_f32_16x16x32_bf16 v[30:33], v[164:167], v[212:215], v[30:33]
	v_mfma_f32_16x16x32_bf16 v[22:25], v[156:159], v[224:227], v[22:25]
	v_mfma_f32_16x16x32_bf16 v[14:17], v[164:167], v[224:227], v[14:17]
	s_setprio 0
	s_setprio 1
	v_mfma_f32_16x16x32_bf16 v[50:53], v[168:171], v[184:187], v[50:53]
	v_mfma_f32_16x16x32_bf16 v[42:45], v[176:179], v[184:187], v[42:45]
	v_mfma_f32_16x16x32_bf16 v[34:37], v[168:171], v[192:195], v[34:37]
	v_mfma_f32_16x16x32_bf16 v[26:29], v[176:179], v[192:195], v[26:29]
	v_mfma_f32_16x16x32_bf16 v[18:21], v[168:171], v[206:209], v[18:21]
	v_mfma_f32_16x16x32_bf16 v[10:13], v[176:179], v[206:209], v[10:13]
	v_mfma_f32_16x16x32_bf16 v[6:9], v[168:171], v[220:223], v[6:9]
	v_mfma_f32_16x16x32_bf16 v[2:5], v[176:179], v[220:223], v[2:5]
	v_mfma_f32_16x16x32_bf16 v[50:53], v[172:175], v[188:191], v[50:53]
	v_mfma_f32_16x16x32_bf16 v[42:45], v[180:183], v[188:191], v[42:45]
	v_mfma_f32_16x16x32_bf16 v[34:37], v[172:175], v[196:199], v[34:37]
	v_mfma_f32_16x16x32_bf16 v[26:29], v[180:183], v[196:199], v[26:29]
	v_mfma_f32_16x16x32_bf16 v[18:21], v[172:175], v[212:215], v[18:21]
	v_mfma_f32_16x16x32_bf16 v[10:13], v[180:183], v[212:215], v[10:13]
	v_mfma_f32_16x16x32_bf16 v[6:9], v[172:175], v[224:227], v[6:9]
	v_mfma_f32_16x16x32_bf16 v[2:5], v[180:183], v[224:227], v[2:5]
	s_setprio 0
	s_barrier
	s_add_i32 s50, s50, 2
	s_add_u32 s48, s48, 0x40000
	s_addc_u32 s49, s49, 0
	s_add_u32 s16, s16, 0x10000
	s_addc_u32 s17, s17, 0
	s_cmp_gt_u32 s50, 61
	s_cbranch_scc0 .LBB0_1718
	v_mov_b32_e32 v138, v146
	s_lshl_b32 s16, s45, 8
	v_and_or_b32 v152, v138, 15, s27
	v_lshrrev_b32_e32 v138, 1, v138
	v_and_or_b32 v138, v138, 24, s16
	v_ashrrev_i32_e32 v153, 31, v152
	v_or_b32_e32 v138, s28, v138
	v_lshlrev_b64 v[144:145], 11, v[152:153]
	v_lshl_add_u64 v[144:145], s[8:9], 0, v[144:145]
	v_lshlrev_b64 v[154:155], 1, v[138:139]
	v_lshl_add_u64 v[144:145], v[144:145], 0, v[154:155]
	v_cvt_pk_bf16_f32 v126, v126, v127
	v_cvt_pk_bf16_f32 v127, v128, v129
	v_cvt_pk_bf16_f32 v128, v122, v123
	v_cvt_pk_bf16_f32 v129, v124, v125
	global_store_dwordx4 v[144:145], v[126:129], off
	v_cvt_pk_bf16_f32 v114, v114, v115
	v_cvt_pk_bf16_f32 v115, v116, v117
	v_cvt_pk_bf16_f32 v116, v106, v107
	v_or_b32_e32 v106, 16, v152
	v_ashrrev_i32_e32 v107, 31, v106
	v_lshlrev_b64 v[106:107], 11, v[106:107]
	v_lshl_add_u64 v[106:107], s[8:9], 0, v[106:107]
	v_cvt_pk_bf16_f32 v117, v108, v109
	global_store_dwordx4 v[144:145], v[114:117], off offset:256
	s_mov_b64 s[16:17], 0x40000
	s_cmp_eq_u32 s44, 4
	v_lshl_add_u64 v[114:115], v[106:107], 0, v[154:155]
	v_cvt_pk_bf16_f32 v106, v118, v119
	v_cvt_pk_bf16_f32 v107, v120, v121
	v_cvt_pk_bf16_f32 v108, v110, v111
	v_cvt_pk_bf16_f32 v109, v112, v113
	global_store_dwordx4 v[114:115], v[106:109], off
	v_cvt_pk_bf16_f32 v98, v98, v99
	v_cvt_pk_bf16_f32 v99, v100, v101
	v_cvt_pk_bf16_f32 v100, v90, v91
	v_or_b32_e32 v90, 32, v152
	v_ashrrev_i32_e32 v91, 31, v90
	v_lshlrev_b64 v[90:91], 11, v[90:91]
	v_lshl_add_u64 v[90:91], s[8:9], 0, v[90:91]
	v_cvt_pk_bf16_f32 v101, v92, v93
	global_store_dwordx4 v[114:115], v[98:101], off offset:256
	s_mov_b32 s45, s44
	s_nop 0
	v_lshl_add_u64 v[98:99], v[90:91], 0, v[154:155]
	v_cvt_pk_bf16_f32 v90, v102, v103
	v_cvt_pk_bf16_f32 v91, v104, v105
	v_cvt_pk_bf16_f32 v92, v94, v95
	v_cvt_pk_bf16_f32 v93, v96, v97
	global_store_dwordx4 v[98:99], v[90:93], off
	v_cvt_pk_bf16_f32 v82, v82, v83
	v_cvt_pk_bf16_f32 v83, v84, v85
	v_cvt_pk_bf16_f32 v84, v74, v75
	v_or_b32_e32 v74, 48, v152
	v_ashrrev_i32_e32 v75, 31, v74
	v_lshlrev_b64 v[74:75], 11, v[74:75]
	v_lshl_add_u64 v[74:75], s[8:9], 0, v[74:75]
	v_cvt_pk_bf16_f32 v85, v76, v77
	global_store_dwordx4 v[98:99], v[82:85], off offset:256
	s_nop 1
	v_lshl_add_u64 v[82:83], v[74:75], 0, v[154:155]
	v_cvt_pk_bf16_f32 v74, v86, v87
	v_cvt_pk_bf16_f32 v75, v88, v89
	v_cvt_pk_bf16_f32 v76, v78, v79
	v_cvt_pk_bf16_f32 v77, v80, v81
	global_store_dwordx4 v[82:83], v[74:77], off
	v_cvt_pk_bf16_f32 v70, v70, v71
	v_cvt_pk_bf16_f32 v71, v72, v73
	v_cvt_pk_bf16_f32 v72, v66, v67
	v_lshl_add_u64 v[66:67], v[144:145], 0, s[16:17]
	s_mov_b32 s16, 0x40000
	v_cvt_pk_bf16_f32 v73, v68, v69
	global_store_dwordx4 v[82:83], v[70:73], off offset:256
	v_cvt_pk_bf16_f32 v62, v62, v63
	v_cvt_pk_bf16_f32 v63, v64, v65
	v_cvt_pk_bf16_f32 v64, v58, v59
	v_add_co_u32_e32 v58, vcc, s16, v144
	v_cvt_pk_bf16_f32 v65, v60, v61
	s_mov_b64 s[16:17], 0x48000
	s_nop 0
	v_addc_co_u32_e32 v59, vcc, 0, v145, vcc
	global_store_dwordx4 v[58:59], v[62:65], off
	v_cvt_pk_bf16_f32 v50, v50, v51
	v_cvt_pk_bf16_f32 v51, v52, v53
	v_cvt_pk_bf16_f32 v52, v42, v43
	v_cvt_pk_bf16_f32 v53, v44, v45
	global_store_dwordx4 v[66:67], v[50:53], off offset:256
	v_cvt_pk_bf16_f32 v42, v54, v55
	v_cvt_pk_bf16_f32 v43, v56, v57
	v_cvt_pk_bf16_f32 v44, v46, v47
	v_cvt_pk_bf16_f32 v45, v48, v49
	s_nop 1
	v_lshl_add_u64 v[50:51], v[144:145], 0, s[16:17]
	s_mov_b32 s16, 0x48000
	v_add_co_u32_e32 v46, vcc, s16, v144
	s_mov_b64 s[16:17], s[10:11]
	s_nop 0
	v_addc_co_u32_e32 v47, vcc, 0, v145, vcc
	global_store_dwordx4 v[46:47], v[42:45], off
	v_cvt_pk_bf16_f32 v34, v34, v35
	v_cvt_pk_bf16_f32 v35, v36, v37
	v_cvt_pk_bf16_f32 v36, v26, v27
	v_cvt_pk_bf16_f32 v37, v28, v29
	global_store_dwordx4 v[50:51], v[34:37], off offset:256
	v_cvt_pk_bf16_f32 v26, v38, v39
	v_cvt_pk_bf16_f32 v27, v40, v41
	v_cvt_pk_bf16_f32 v28, v30, v31
	v_add_co_u32_e32 v30, vcc, s34, v144
	s_nop 0
	v_lshl_add_u64 v[34:35], v[144:145], 0, s[4:5]
	v_addc_co_u32_e32 v31, vcc, 0, v145, vcc
	v_cvt_pk_bf16_f32 v29, v32, v33
	global_store_dwordx4 v[30:31], v[26:29], off
	v_cvt_pk_bf16_f32 v18, v18, v19
	v_cvt_pk_bf16_f32 v19, v20, v21
	v_cvt_pk_bf16_f32 v20, v10, v11
	v_cvt_pk_bf16_f32 v21, v12, v13
	global_store_dwordx4 v[34:35], v[18:21], off offset:256
	v_cvt_pk_bf16_f32 v10, v22, v23
	v_cvt_pk_bf16_f32 v11, v24, v25
	v_cvt_pk_bf16_f32 v12, v14, v15
	v_add_co_u32_e32 v14, vcc, s35, v144
	s_nop 0
	v_lshl_add_u64 v[18:19], v[144:145], 0, s[6:7]
	v_addc_co_u32_e32 v15, vcc, 0, v145, vcc
	v_cvt_pk_bf16_f32 v13, v16, v17
	global_store_dwordx4 v[14:15], v[10:13], off
	v_cvt_pk_bf16_f32 v6, v6, v7
	v_cvt_pk_bf16_f32 v7, v8, v9
	v_cvt_pk_bf16_f32 v8, v2, v3
	v_cvt_pk_bf16_f32 v9, v4, v5
	global_store_dwordx4 v[18:19], v[6:9], off offset:256
	s_cbranch_scc0 .LBB0_1717
	s_waitcnt vmcnt(0)
	s_cmpk_gt_u32 s0, 0xff
	s_cbranch_scc1 .LBB0_1722
	s_barrier

.LBB0_2185:
	ds_read_b128 v[146:149], v152
	ds_read_b128 v[156:159], v152 offset:1024
	ds_read_b128 v[160:163], v152 offset:2048
	ds_read_b128 v[164:167], v152 offset:3072
	ds_read_b128 v[168:171], v153
	ds_read_b128 v[172:175], v153 offset:1024
	ds_read_b128 v[176:179], v153 offset:2048
	ds_read_b128 v[180:183], v153 offset:3072
	s_add_u32 s22, s20, 0xfc000
	s_addc_u32 s23, s21, 0
	s_cmp_eq_u32 s44, 4
	s_cselect_b32 s26, s15, s22
	s_cselect_b32 s27, s5, s23
	s_cselect_b32 s24, s41, s42
	s_cselect_b32 s25, s13, s43
	s_add_u32 s22, s26, 0x100000
	s_addc_u32 s23, s27, 0
	s_add_i32 m0, s1, 0xc000
	ds_read_b128 v[184:187], v154
	ds_read_b128 v[188:191], v154 offset:1024
	ds_read_b128 v[192:195], v154 offset:2048
	ds_read_b128 v[196:199], v154 offset:3072
	ds_read_b128 v[206:209], v154 offset:4096
	ds_read_b128 v[212:215], v154 offset:5120
	ds_read_b128 v[220:223], v154 offset:6144
	ds_read_b128 v[224:227], v154 offset:7168
	global_load_lds_dwordx4 v138, s[20:21]
	s_add_i32 m0, s1, 0xe000
	s_nop 0
	global_load_lds_dwordx4 v140, s[20:21]
	s_waitcnt vmcnt(8)
	s_waitcnt lgkmcnt(0)
	s_barrier
	s_setprio 1
	s_waitcnt lgkmcnt(0)
	v_mfma_f32_16x16x32_bf16 v[126:129], v[146:149], v[184:187], v[126:129]
	v_mfma_f32_16x16x32_bf16 v[122:125], v[160:163], v[184:187], v[122:125]
	v_mfma_f32_16x16x32_bf16 v[110:113], v[146:149], v[192:195], v[110:113]
	v_mfma_f32_16x16x32_bf16 v[106:109], v[160:163], v[192:195], v[106:109]
	v_mfma_f32_16x16x32_bf16 v[94:97], v[146:149], v[206:209], v[94:97]
	v_mfma_f32_16x16x32_bf16 v[90:93], v[160:163], v[206:209], v[90:93]
	v_mfma_f32_16x16x32_bf16 v[78:81], v[146:149], v[220:223], v[78:81]
	v_mfma_f32_16x16x32_bf16 v[74:77], v[160:163], v[220:223], v[74:77]
	v_mfma_f32_16x16x32_bf16 v[126:129], v[156:159], v[188:191], v[126:129]
	v_mfma_f32_16x16x32_bf16 v[122:125], v[164:167], v[188:191], v[122:125]
	v_mfma_f32_16x16x32_bf16 v[110:113], v[156:159], v[196:199], v[110:113]
	v_mfma_f32_16x16x32_bf16 v[106:109], v[164:167], v[196:199], v[106:109]
	v_mfma_f32_16x16x32_bf16 v[94:97], v[156:159], v[212:215], v[94:97]
	v_mfma_f32_16x16x32_bf16 v[90:93], v[164:167], v[212:215], v[90:93]
	v_mfma_f32_16x16x32_bf16 v[78:81], v[156:159], v[224:227], v[78:81]
	v_mfma_f32_16x16x32_bf16 v[74:77], v[164:167], v[224:227], v[74:77]
	s_setprio 0
	s_setprio 1
	v_mfma_f32_16x16x32_bf16 v[118:121], v[168:171], v[184:187], v[118:121]
	v_mfma_f32_16x16x32_bf16 v[114:117], v[176:179], v[184:187], v[114:117]
	v_mfma_f32_16x16x32_bf16 v[102:105], v[168:171], v[192:195], v[102:105]
	v_mfma_f32_16x16x32_bf16 v[98:101], v[176:179], v[192:195], v[98:101]
	v_mfma_f32_16x16x32_bf16 v[86:89], v[168:171], v[206:209], v[86:89]
	v_mfma_f32_16x16x32_bf16 v[82:85], v[176:179], v[206:209], v[82:85]
	v_mfma_f32_16x16x32_bf16 v[70:73], v[168:171], v[220:223], v[70:73]
	v_mfma_f32_16x16x32_bf16 v[66:69], v[176:179], v[220:223], v[66:69]
	v_mfma_f32_16x16x32_bf16 v[118:121], v[172:175], v[188:191], v[118:121]
	v_mfma_f32_16x16x32_bf16 v[114:117], v[180:183], v[188:191], v[114:117]
	v_mfma_f32_16x16x32_bf16 v[102:105], v[172:175], v[196:199], v[102:105]
	v_mfma_f32_16x16x32_bf16 v[98:101], v[180:183], v[196:199], v[98:101]
	v_mfma_f32_16x16x32_bf16 v[86:89], v[172:175], v[212:215], v[86:89]
	v_mfma_f32_16x16x32_bf16 v[82:85], v[180:183], v[212:215], v[82:85]
	v_mfma_f32_16x16x32_bf16 v[70:73], v[172:175], v[224:227], v[70:73]
	v_mfma_f32_16x16x32_bf16 v[66:69], v[180:183], v[224:227], v[66:69]
	s_setprio 0
	s_barrier
	s_add_i32 s45, s38, s0
	s_mov_b32 m0, s45
	ds_read_b128 v[184:187], v154 offset:16384
	ds_read_b128 v[188:191], v154 offset:17408
	ds_read_b128 v[192:195], v154 offset:18432
	ds_read_b128 v[196:199], v154 offset:19456
	ds_read_b128 v[206:209], v154 offset:20480
	ds_read_b128 v[212:215], v154 offset:21504
	ds_read_b128 v[220:223], v154 offset:22528
	ds_read_b128 v[224:227], v154 offset:23552
	global_load_lds_dwordx4 v132, s[24:25]
	s_add_i32 m0, s45, 0x2000
	s_add_u32 s46, s24, 0x4000
	s_addc_u32 s47, s25, 0
	s_add_i32 s45, s39, s0
	global_load_lds_dwordx4 v136, s[24:25]
	s_mov_b32 m0, s45
	s_nop 0
	global_load_lds_dwordx4 v132, s[46:47]
	s_add_i32 m0, s45, 0x2000
	s_nop 0
	global_load_lds_dwordx4 v136, s[46:47]
	s_mov_b32 m0, s1
	s_nop 0
	global_load_lds_dwordx4 v130, s[26:27]
	s_mov_b32 m0, s28
	s_nop 0
	global_load_lds_dwordx4 v134, s[26:27]
	s_waitcnt vmcnt(8)
	s_waitcnt lgkmcnt(0)
	s_barrier
	s_setprio 1
	s_waitcnt lgkmcnt(0)
	v_mfma_f32_16x16x32_bf16 v[62:65], v[146:149], v[184:187], v[62:65]
	v_mfma_f32_16x16x32_bf16 v[58:61], v[160:163], v[184:187], v[58:61]
	v_mfma_f32_16x16x32_bf16 v[46:49], v[146:149], v[192:195], v[46:49]
	v_mfma_f32_16x16x32_bf16 v[42:45], v[160:163], v[192:195], v[42:45]
	v_mfma_f32_16x16x32_bf16 v[30:33], v[146:149], v[206:209], v[30:33]
	v_mfma_f32_16x16x32_bf16 v[26:29], v[160:163], v[206:209], v[26:29]
	v_mfma_f32_16x16x32_bf16 v[14:17], v[146:149], v[220:223], v[14:17]
	v_mfma_f32_16x16x32_bf16 v[10:13], v[160:163], v[220:223], v[10:13]
	v_mfma_f32_16x16x32_bf16 v[62:65], v[156:159], v[188:191], v[62:65]
	v_mfma_f32_16x16x32_bf16 v[58:61], v[164:167], v[188:191], v[58:61]
	v_mfma_f32_16x16x32_bf16 v[46:49], v[156:159], v[196:199], v[46:49]
	v_mfma_f32_16x16x32_bf16 v[42:45], v[164:167], v[196:199], v[42:45]
	v_mfma_f32_16x16x32_bf16 v[30:33], v[156:159], v[212:215], v[30:33]
	v_mfma_f32_16x16x32_bf16 v[26:29], v[164:167], v[212:215], v[26:29]
	v_mfma_f32_16x16x32_bf16 v[14:17], v[156:159], v[224:227], v[14:17]
	v_mfma_f32_16x16x32_bf16 v[10:13], v[164:167], v[224:227], v[10:13]
	s_setprio 0
	s_setprio 1
	v_mfma_f32_16x16x32_bf16 v[54:57], v[168:171], v[184:187], v[54:57]
	v_mfma_f32_16x16x32_bf16 v[50:53], v[176:179], v[184:187], v[50:53]
	v_mfma_f32_16x16x32_bf16 v[38:41], v[168:171], v[192:195], v[38:41]
	v_mfma_f32_16x16x32_bf16 v[34:37], v[176:179], v[192:195], v[34:37]
	v_mfma_f32_16x16x32_bf16 v[22:25], v[168:171], v[206:209], v[22:25]
	v_mfma_f32_16x16x32_bf16 v[18:21], v[176:179], v[206:209], v[18:21]
	v_mfma_f32_16x16x32_bf16 v[6:9], v[168:171], v[220:223], v[6:9]
	v_mfma_f32_16x16x32_bf16 v[2:5], v[176:179], v[220:223], v[2:5]
	v_mfma_f32_16x16x32_bf16 v[54:57], v[172:175], v[188:191], v[54:57]
	v_mfma_f32_16x16x32_bf16 v[50:53], v[180:183], v[188:191], v[50:53]
	v_mfma_f32_16x16x32_bf16 v[38:41], v[172:175], v[196:199], v[38:41]
	v_mfma_f32_16x16x32_bf16 v[34:37], v[180:183], v[196:199], v[34:37]
	v_mfma_f32_16x16x32_bf16 v[22:25], v[172:175], v[212:215], v[22:25]
	v_mfma_f32_16x16x32_bf16 v[18:21], v[180:183], v[212:215], v[18:21]
	v_mfma_f32_16x16x32_bf16 v[6:9], v[172:175], v[224:227], v[6:9]
	v_mfma_f32_16x16x32_bf16 v[2:5], v[180:183], v[224:227], v[2:5]
	s_setprio 0
	s_barrier
	s_add_i32 s45, 0, 0x18000
	v_add_u32_e32 v155, s45, v151
	s_add_i32 s46, 0, 0x1c000
	ds_read_b128 v[146:149], v155
	ds_read_b128 v[156:159], v155 offset:1024
	ds_read_b128 v[160:163], v155 offset:2048
	ds_read_b128 v[164:167], v155 offset:3072
	v_add_u32_e32 v155, s46, v151
	ds_read_b128 v[168:171], v155
	ds_read_b128 v[172:175], v155 offset:1024
	ds_read_b128 v[176:179], v155 offset:2048
	ds_read_b128 v[180:183], v155 offset:3072
	s_add_u32 s26, s26, 0x4000
	s_addc_u32 s27, s27, 0
	s_mov_b32 m0, s29
	ds_read_b128 v[184:187], v154 offset:32768
	ds_read_b128 v[188:191], v154 offset:33792
	ds_read_b128 v[192:195], v154 offset:34816
	ds_read_b128 v[196:199], v154 offset:35840
	ds_read_b128 v[206:209], v154 offset:36864
	ds_read_b128 v[212:215], v154 offset:37888
	ds_read_b128 v[220:223], v154 offset:38912
	ds_read_b128 v[224:227], v154 offset:39936
	global_load_lds_dwordx4 v130, s[26:27]
	s_mov_b32 m0, s30
	s_nop 0
	global_load_lds_dwordx4 v134, s[26:27]
	s_waitcnt vmcnt(8)
	s_waitcnt lgkmcnt(0)
	s_barrier
	s_setprio 1
	s_waitcnt lgkmcnt(0)
	v_mfma_f32_16x16x32_bf16 v[126:129], v[146:149], v[184:187], v[126:129]
	v_mfma_f32_16x16x32_bf16 v[122:125], v[160:163], v[184:187], v[122:125]
	v_mfma_f32_16x16x32_bf16 v[110:113], v[146:149], v[192:195], v[110:113]
	v_mfma_f32_16x16x32_bf16 v[106:109], v[160:163], v[192:195], v[106:109]
	v_mfma_f32_16x16x32_bf16 v[94:97], v[146:149], v[206:209], v[94:97]
	v_mfma_f32_16x16x32_bf16 v[90:93], v[160:163], v[206:209], v[90:93]
	v_mfma_f32_16x16x32_bf16 v[78:81], v[146:149], v[220:223], v[78:81]
	v_mfma_f32_16x16x32_bf16 v[74:77], v[160:163], v[220:223], v[74:77]
	v_mfma_f32_16x16x32_bf16 v[126:129], v[156:159], v[188:191], v[126:129]
	v_mfma_f32_16x16x32_bf16 v[122:125], v[164:167], v[188:191], v[122:125]
	v_mfma_f32_16x16x32_bf16 v[110:113], v[156:159], v[196:199], v[110:113]
	v_mfma_f32_16x16x32_bf16 v[106:109], v[164:167], v[196:199], v[106:109]
	v_mfma_f32_16x16x32_bf16 v[94:97], v[156:159], v[212:215], v[94:97]
	v_mfma_f32_16x16x32_bf16 v[90:93], v[164:167], v[212:215], v[90:93]
	v_mfma_f32_16x16x32_bf16 v[78:81], v[156:159], v[224:227], v[78:81]
	v_mfma_f32_16x16x32_bf16 v[74:77], v[164:167], v[224:227], v[74:77]
	s_setprio 0
	s_setprio 1
	v_mfma_f32_16x16x32_bf16 v[118:121], v[168:171], v[184:187], v[118:121]
	v_mfma_f32_16x16x32_bf16 v[114:117], v[176:179], v[184:187], v[114:117]
	v_mfma_f32_16x16x32_bf16 v[102:105], v[168:171], v[192:195], v[102:105]
	v_mfma_f32_16x16x32_bf16 v[98:101], v[176:179], v[192:195], v[98:101]
	v_mfma_f32_16x16x32_bf16 v[86:89], v[168:171], v[206:209], v[86:89]
	v_mfma_f32_16x16x32_bf16 v[82:85], v[176:179], v[206:209], v[82:85]
	v_mfma_f32_16x16x32_bf16 v[70:73], v[168:171], v[220:223], v[70:73]
	v_mfma_f32_16x16x32_bf16 v[66:69], v[176:179], v[220:223], v[66:69]
	v_mfma_f32_16x16x32_bf16 v[118:121], v[172:175], v[188:191], v[118:121]
	v_mfma_f32_16x16x32_bf16 v[114:117], v[180:183], v[188:191], v[114:117]
	v_mfma_f32_16x16x32_bf16 v[102:105], v[172:175], v[196:199], v[102:105]
	v_mfma_f32_16x16x32_bf16 v[98:101], v[180:183], v[196:199], v[98:101]
	v_mfma_f32_16x16x32_bf16 v[86:89], v[172:175], v[212:215], v[86:89]
	v_mfma_f32_16x16x32_bf16 v[82:85], v[180:183], v[212:215], v[82:85]
	v_mfma_f32_16x16x32_bf16 v[70:73], v[172:175], v[224:227], v[70:73]
	v_mfma_f32_16x16x32_bf16 v[66:69], v[180:183], v[224:227], v[66:69]
	s_setprio 0
	s_barrier
	s_add_u32 s26, s24, 0x80000
	s_addc_u32 s27, s25, 0
	s_add_i32 s45, s45, s0
	s_mov_b32 m0, s45
	ds_read_b128 v[184:187], v154 offset:49152
	ds_read_b128 v[188:191], v154 offset:50176
	ds_read_b128 v[192:195], v154 offset:51200
	ds_read_b128 v[196:199], v154 offset:52224
	ds_read_b128 v[206:209], v154 offset:53248
	ds_read_b128 v[212:215], v154 offset:54272
	ds_read_b128 v[220:223], v154 offset:55296
	ds_read_b128 v[224:227], v154 offset:56320
	global_load_lds_dwordx4 v132, s[26:27]
	s_add_i32 m0, s45, 0x2000
	s_add_u32 s24, s24, 0x84000
	s_addc_u32 s25, s25, 0
	global_load_lds_dwordx4 v136, s[26:27]
	s_add_i32 s26, s46, s0
	s_mov_b32 m0, s26
	s_nop 0
	global_load_lds_dwordx4 v132, s[24:25]
	s_add_i32 m0, s26, 0x2000
	s_nop 0
	global_load_lds_dwordx4 v136, s[24:25]
	s_mov_b32 m0, s36
	s_nop 0
	global_load_lds_dwordx4 v130, s[22:23]
	s_mov_b32 m0, s37
	s_nop 0
	global_load_lds_dwordx4 v134, s[22:23]
	s_waitcnt vmcnt(8)
	s_waitcnt lgkmcnt(0)
	s_barrier
	s_setprio 1
	s_waitcnt lgkmcnt(0)
	v_mfma_f32_16x16x32_bf16 v[62:65], v[146:149], v[184:187], v[62:65]
	v_mfma_f32_16x16x32_bf16 v[58:61], v[160:163], v[184:187], v[58:61]
	v_mfma_f32_16x16x32_bf16 v[46:49], v[146:149], v[192:195], v[46:49]
	v_mfma_f32_16x16x32_bf16 v[42:45], v[160:163], v[192:195], v[42:45]
	v_mfma_f32_16x16x32_bf16 v[30:33], v[146:149], v[206:209], v[30:33]
	v_mfma_f32_16x16x32_bf16 v[26:29], v[160:163], v[206:209], v[26:29]
	v_mfma_f32_16x16x32_bf16 v[14:17], v[146:149], v[220:223], v[14:17]
	v_mfma_f32_16x16x32_bf16 v[10:13], v[160:163], v[220:223], v[10:13]
	v_mfma_f32_16x16x32_bf16 v[62:65], v[156:159], v[188:191], v[62:65]
	v_mfma_f32_16x16x32_bf16 v[58:61], v[164:167], v[188:191], v[58:61]
	v_mfma_f32_16x16x32_bf16 v[46:49], v[156:159], v[196:199], v[46:49]
	v_mfma_f32_16x16x32_bf16 v[42:45], v[164:167], v[196:199], v[42:45]
	v_mfma_f32_16x16x32_bf16 v[30:33], v[156:159], v[212:215], v[30:33]
	v_mfma_f32_16x16x32_bf16 v[26:29], v[164:167], v[212:215], v[26:29]
	v_mfma_f32_16x16x32_bf16 v[14:17], v[156:159], v[224:227], v[14:17]
	v_mfma_f32_16x16x32_bf16 v[10:13], v[164:167], v[224:227], v[10:13]
	s_setprio 0
	s_setprio 1
	v_mfma_f32_16x16x32_bf16 v[54:57], v[168:171], v[184:187], v[54:57]
	v_mfma_f32_16x16x32_bf16 v[50:53], v[176:179], v[184:187], v[50:53]
	v_mfma_f32_16x16x32_bf16 v[38:41], v[168:171], v[192:195], v[38:41]
	v_mfma_f32_16x16x32_bf16 v[34:37], v[176:179], v[192:195], v[34:37]
	v_mfma_f32_16x16x32_bf16 v[22:25], v[168:171], v[206:209], v[22:25]
	v_mfma_f32_16x16x32_bf16 v[18:21], v[176:179], v[206:209], v[18:21]
	v_mfma_f32_16x16x32_bf16 v[6:9], v[168:171], v[220:223], v[6:9]
	v_mfma_f32_16x16x32_bf16 v[2:5], v[176:179], v[220:223], v[2:5]
	v_mfma_f32_16x16x32_bf16 v[54:57], v[172:175], v[188:191], v[54:57]
	v_mfma_f32_16x16x32_bf16 v[50:53], v[180:183], v[188:191], v[50:53]
	v_mfma_f32_16x16x32_bf16 v[38:41], v[172:175], v[196:199], v[38:41]
	v_mfma_f32_16x16x32_bf16 v[34:37], v[180:183], v[196:199], v[34:37]
	v_mfma_f32_16x16x32_bf16 v[22:25], v[172:175], v[212:215], v[22:25]
	v_mfma_f32_16x16x32_bf16 v[18:21], v[180:183], v[212:215], v[18:21]
	v_mfma_f32_16x16x32_bf16 v[6:9], v[172:175], v[224:227], v[6:9]
	v_mfma_f32_16x16x32_bf16 v[2:5], v[180:183], v[224:227], v[2:5]
	s_setprio 0
	s_barrier
	s_add_i32 s44, s44, 2
	s_add_u32 s42, s42, 0x100000
	s_addc_u32 s43, s43, 0
	s_add_u32 s20, s20, 0x200000
	s_addc_u32 s21, s21, 0
	s_cmp_gt_u32 s44, 5
	s_cbranch_scc0 .LBB0_2185
	s_and_b64 vcc, exec, s[8:9]
	s_cbranch_vccz .LBB0_2188
	s_barrier

.LBB0_2480:
	ds_read_b128 v[18:21], v182
	ds_read_b128 v[22:25], v182 offset:1024
	ds_read_b128 v[26:29], v182 offset:2048
	ds_read_b128 v[30:33], v182 offset:3072
	ds_read_b128 v[2:5], v183
	ds_read_b128 v[6:9], v183 offset:1024
	ds_read_b128 v[10:13], v183 offset:2048
	ds_read_b128 v[14:17], v183 offset:3072
	s_add_u32 s26, s24, 0xfc000
	s_addc_u32 s27, s25, 0
	s_cmp_eq_u32 s48, 28
	s_cselect_b32 s30, s17, s26
	s_cselect_b32 s31, s5, s27
	s_cselect_b32 s28, s23, s46
	s_cselect_b32 s29, s15, s47
	s_add_u32 s26, s30, 0x100000
	s_addc_u32 s27, s31, 0
	s_add_i32 m0, s34, 0xc000
	ds_read_b128 v[186:189], v184
	ds_read_b128 v[190:193], v184 offset:1024
	ds_read_b128 v[220:223], v184 offset:2048
	ds_read_b128 v[224:227], v184 offset:3072
	ds_read_b128 v[228:231], v184 offset:4096
	ds_read_b128 v[232:235], v184 offset:5120
	ds_read_b128 v[236:239], v184 offset:6144
	ds_read_b128 v[240:243], v184 offset:7168
	global_load_lds_dwordx4 v172, s[24:25]
	s_add_i32 m0, s34, 0xe000
	s_nop 0
	global_load_lds_dwordx4 v174, s[24:25]
	s_waitcnt vmcnt(8)
	s_waitcnt lgkmcnt(0)
	s_barrier
	s_setprio 1
	s_waitcnt lgkmcnt(0)
	v_mfma_scale_f32_16x16x128_f8f6f4 v[158:161], v[18:25], v[186:193], v[158:161], v185, v185 op_sel_hi:[0,0,0]
	v_mfma_scale_f32_16x16x128_f8f6f4 v[154:157], v[26:33], v[186:193], v[154:157], v185, v185 op_sel_hi:[0,0,0]
	v_mfma_scale_f32_16x16x128_f8f6f4 v[142:145], v[18:25], v[220:227], v[142:145], v185, v185 op_sel_hi:[0,0,0]
	v_mfma_scale_f32_16x16x128_f8f6f4 v[138:141], v[26:33], v[220:227], v[138:141], v185, v185 op_sel_hi:[0,0,0]
	v_mfma_scale_f32_16x16x128_f8f6f4 v[126:129], v[18:25], v[228:235], v[126:129], v185, v185 op_sel_hi:[0,0,0]
	v_mfma_scale_f32_16x16x128_f8f6f4 v[122:125], v[26:33], v[228:235], v[122:125], v185, v185 op_sel_hi:[0,0,0]
	v_mfma_scale_f32_16x16x128_f8f6f4 v[110:113], v[18:25], v[236:243], v[110:113], v185, v185 op_sel_hi:[0,0,0]
	v_mfma_scale_f32_16x16x128_f8f6f4 v[106:109], v[26:33], v[236:243], v[106:109], v185, v185 op_sel_hi:[0,0,0]
	s_setprio 0
	s_setprio 1
	v_mfma_scale_f32_16x16x128_f8f6f4 v[150:153], v[2:9], v[186:193], v[150:153], v185, v185 op_sel_hi:[0,0,0]
	v_mfma_scale_f32_16x16x128_f8f6f4 v[146:149], v[10:17], v[186:193], v[146:149], v185, v185 op_sel_hi:[0,0,0]
	v_mfma_scale_f32_16x16x128_f8f6f4 v[134:137], v[2:9], v[220:227], v[134:137], v185, v185 op_sel_hi:[0,0,0]
	v_mfma_scale_f32_16x16x128_f8f6f4 v[130:133], v[10:17], v[220:227], v[130:133], v185, v185 op_sel_hi:[0,0,0]
	v_mfma_scale_f32_16x16x128_f8f6f4 v[118:121], v[2:9], v[228:235], v[118:121], v185, v185 op_sel_hi:[0,0,0]
	v_mfma_scale_f32_16x16x128_f8f6f4 v[114:117], v[10:17], v[228:235], v[114:117], v185, v185 op_sel_hi:[0,0,0]
	v_mfma_scale_f32_16x16x128_f8f6f4 v[102:105], v[2:9], v[236:243], v[102:105], v185, v185 op_sel_hi:[0,0,0]
	v_mfma_scale_f32_16x16x128_f8f6f4 v[98:101], v[10:17], v[236:243], v[98:101], v185, v185 op_sel_hi:[0,0,0]
	s_setprio 0
	s_barrier
	s_add_i32 s49, s42, s0
	s_mov_b32 m0, s49
	ds_read_b128 v[186:189], v184 offset:16384
	ds_read_b128 v[190:193], v184 offset:17408
	ds_read_b128 v[220:223], v184 offset:18432
	ds_read_b128 v[224:227], v184 offset:19456
	ds_read_b128 v[228:231], v184 offset:20480
	ds_read_b128 v[232:235], v184 offset:21504
	ds_read_b128 v[236:239], v184 offset:22528
	ds_read_b128 v[240:243], v184 offset:23552
	global_load_lds_dwordx4 v166, s[28:29]
	s_add_i32 m0, s49, 0x2000
	s_add_u32 s50, s28, 0x4000
	s_addc_u32 s51, s29, 0
	s_add_i32 s49, s43, s0
	global_load_lds_dwordx4 v162, s[28:29]
	s_mov_b32 m0, s49
	s_nop 0
	global_load_lds_dwordx4 v166, s[50:51]
	s_add_i32 m0, s49, 0x2000
	s_nop 0
	global_load_lds_dwordx4 v162, s[50:51]
	s_mov_b32 m0, s34
	s_nop 0
	global_load_lds_dwordx4 v168, s[30:31]
	s_mov_b32 m0, s35
	s_nop 0
	global_load_lds_dwordx4 v164, s[30:31]
	s_waitcnt vmcnt(8)
	s_waitcnt lgkmcnt(0)
	s_barrier
	s_setprio 1
	s_waitcnt lgkmcnt(0)
	v_mfma_scale_f32_16x16x128_f8f6f4 v[94:97], v[18:25], v[186:193], v[94:97], v185, v185 op_sel_hi:[0,0,0]
	v_mfma_scale_f32_16x16x128_f8f6f4 v[90:93], v[26:33], v[186:193], v[90:93], v185, v185 op_sel_hi:[0,0,0]
	v_mfma_scale_f32_16x16x128_f8f6f4 v[78:81], v[18:25], v[220:227], v[78:81], v185, v185 op_sel_hi:[0,0,0]
	v_mfma_scale_f32_16x16x128_f8f6f4 v[74:77], v[26:33], v[220:227], v[74:77], v185, v185 op_sel_hi:[0,0,0]
	v_mfma_scale_f32_16x16x128_f8f6f4 v[62:65], v[18:25], v[228:235], v[62:65], v185, v185 op_sel_hi:[0,0,0]
	v_mfma_scale_f32_16x16x128_f8f6f4 v[58:61], v[26:33], v[228:235], v[58:61], v185, v185 op_sel_hi:[0,0,0]
	v_mfma_scale_f32_16x16x128_f8f6f4 v[46:49], v[18:25], v[236:243], v[46:49], v185, v185 op_sel_hi:[0,0,0]
	v_mfma_scale_f32_16x16x128_f8f6f4 v[42:45], v[26:33], v[236:243], v[42:45], v185, v185 op_sel_hi:[0,0,0]
	s_setprio 0
	s_setprio 1
	v_mfma_scale_f32_16x16x128_f8f6f4 v[86:89], v[2:9], v[186:193], v[86:89], v185, v185 op_sel_hi:[0,0,0]
	v_mfma_scale_f32_16x16x128_f8f6f4 v[82:85], v[10:17], v[186:193], v[82:85], v185, v185 op_sel_hi:[0,0,0]
	v_mfma_scale_f32_16x16x128_f8f6f4 v[70:73], v[2:9], v[220:227], v[70:73], v185, v185 op_sel_hi:[0,0,0]
	v_mfma_scale_f32_16x16x128_f8f6f4 v[66:69], v[10:17], v[220:227], v[66:69], v185, v185 op_sel_hi:[0,0,0]
	v_mfma_scale_f32_16x16x128_f8f6f4 v[54:57], v[2:9], v[228:235], v[54:57], v185, v185 op_sel_hi:[0,0,0]
	v_mfma_scale_f32_16x16x128_f8f6f4 v[50:53], v[10:17], v[228:235], v[50:53], v185, v185 op_sel_hi:[0,0,0]
	v_mfma_scale_f32_16x16x128_f8f6f4 v[38:41], v[2:9], v[236:243], v[38:41], v185, v185 op_sel_hi:[0,0,0]
	v_mfma_scale_f32_16x16x128_f8f6f4 v[34:37], v[10:17], v[236:243], v[34:37], v185, v185 op_sel_hi:[0,0,0]
	s_setprio 0
	s_barrier
	s_add_i32 s49, 0, 0x18000
	s_add_i32 s50, 0, 0x1c000
	v_add_u32_e32 v14, s49, v181
	v_add_u32_e32 v30, s50, v181
	ds_read_b128 v[2:5], v14
	ds_read_b128 v[6:9], v14 offset:1024
	ds_read_b128 v[10:13], v14 offset:2048
	ds_read_b128 v[14:17], v14 offset:3072
	ds_read_b128 v[18:21], v30
	ds_read_b128 v[22:25], v30 offset:1024
	ds_read_b128 v[26:29], v30 offset:2048
	ds_read_b128 v[30:33], v30 offset:3072
	s_add_u32 s30, s30, 0x4000
	s_addc_u32 s31, s31, 0
	s_mov_b32 m0, s36
	ds_read_b128 v[186:189], v184 offset:32768
	ds_read_b128 v[190:193], v184 offset:33792
	ds_read_b128 v[220:223], v184 offset:34816
	ds_read_b128 v[224:227], v184 offset:35840
	ds_read_b128 v[228:231], v184 offset:36864
	ds_read_b128 v[232:235], v184 offset:37888
	ds_read_b128 v[236:239], v184 offset:38912
	ds_read_b128 v[240:243], v184 offset:39936
	global_load_lds_dwordx4 v168, s[30:31]
	s_mov_b32 m0, s37
	s_nop 0
	global_load_lds_dwordx4 v164, s[30:31]
	s_waitcnt vmcnt(8)
	s_waitcnt lgkmcnt(0)
	s_barrier
	s_setprio 1
	s_waitcnt lgkmcnt(0)
	v_mfma_scale_f32_16x16x128_f8f6f4 v[158:161], v[2:9], v[186:193], v[158:161], v185, v185 op_sel_hi:[0,0,0]
	v_mfma_scale_f32_16x16x128_f8f6f4 v[154:157], v[10:17], v[186:193], v[154:157], v185, v185 op_sel_hi:[0,0,0]
	v_mfma_scale_f32_16x16x128_f8f6f4 v[142:145], v[2:9], v[220:227], v[142:145], v185, v185 op_sel_hi:[0,0,0]
	v_mfma_scale_f32_16x16x128_f8f6f4 v[138:141], v[10:17], v[220:227], v[138:141], v185, v185 op_sel_hi:[0,0,0]
	v_mfma_scale_f32_16x16x128_f8f6f4 v[126:129], v[2:9], v[228:235], v[126:129], v185, v185 op_sel_hi:[0,0,0]
	v_mfma_scale_f32_16x16x128_f8f6f4 v[122:125], v[10:17], v[228:235], v[122:125], v185, v185 op_sel_hi:[0,0,0]
	v_mfma_scale_f32_16x16x128_f8f6f4 v[110:113], v[2:9], v[236:243], v[110:113], v185, v185 op_sel_hi:[0,0,0]
	v_mfma_scale_f32_16x16x128_f8f6f4 v[106:109], v[10:17], v[236:243], v[106:109], v185, v185 op_sel_hi:[0,0,0]
	s_setprio 0
	s_setprio 1
	v_mfma_scale_f32_16x16x128_f8f6f4 v[150:153], v[18:25], v[186:193], v[150:153], v185, v185 op_sel_hi:[0,0,0]
	v_mfma_scale_f32_16x16x128_f8f6f4 v[146:149], v[26:33], v[186:193], v[146:149], v185, v185 op_sel_hi:[0,0,0]
	v_mfma_scale_f32_16x16x128_f8f6f4 v[134:137], v[18:25], v[220:227], v[134:137], v185, v185 op_sel_hi:[0,0,0]
	v_mfma_scale_f32_16x16x128_f8f6f4 v[130:133], v[26:33], v[220:227], v[130:133], v185, v185 op_sel_hi:[0,0,0]
	v_mfma_scale_f32_16x16x128_f8f6f4 v[118:121], v[18:25], v[228:235], v[118:121], v185, v185 op_sel_hi:[0,0,0]
	v_mfma_scale_f32_16x16x128_f8f6f4 v[114:117], v[26:33], v[228:235], v[114:117], v185, v185 op_sel_hi:[0,0,0]
	v_mfma_scale_f32_16x16x128_f8f6f4 v[102:105], v[18:25], v[236:243], v[102:105], v185, v185 op_sel_hi:[0,0,0]
	v_mfma_scale_f32_16x16x128_f8f6f4 v[98:101], v[26:33], v[236:243], v[98:101], v185, v185 op_sel_hi:[0,0,0]
	s_setprio 0
	s_barrier
	s_add_u32 s30, s28, 0x380000
	s_addc_u32 s31, s29, 0
	s_add_i32 s49, s49, s0
	s_mov_b32 m0, s49
	ds_read_b128 v[186:189], v184 offset:49152
	ds_read_b128 v[190:193], v184 offset:50176
	ds_read_b128 v[220:223], v184 offset:51200
	ds_read_b128 v[224:227], v184 offset:52224
	ds_read_b128 v[228:231], v184 offset:53248
	ds_read_b128 v[232:235], v184 offset:54272
	ds_read_b128 v[236:239], v184 offset:55296
	ds_read_b128 v[240:243], v184 offset:56320
	global_load_lds_dwordx4 v166, s[30:31]
	s_add_i32 m0, s49, 0x2000
	s_add_u32 s28, s28, 0x384000
	s_addc_u32 s29, s29, 0
	global_load_lds_dwordx4 v162, s[30:31]
	s_add_i32 s30, s50, s0
	s_mov_b32 m0, s30
	s_nop 0
	global_load_lds_dwordx4 v166, s[28:29]
	s_add_i32 m0, s30, 0x2000
	s_nop 0
	global_load_lds_dwordx4 v162, s[28:29]
	s_mov_b32 m0, s40
	s_nop 0
	global_load_lds_dwordx4 v168, s[26:27]
	s_mov_b32 m0, s41
	s_nop 0
	global_load_lds_dwordx4 v164, s[26:27]
	s_waitcnt vmcnt(8)
	s_waitcnt lgkmcnt(0)
	s_barrier
	s_setprio 1
	s_waitcnt lgkmcnt(0)
	v_mfma_scale_f32_16x16x128_f8f6f4 v[94:97], v[2:9], v[186:193], v[94:97], v185, v185 op_sel_hi:[0,0,0]
	v_mfma_scale_f32_16x16x128_f8f6f4 v[90:93], v[10:17], v[186:193], v[90:93], v185, v185 op_sel_hi:[0,0,0]
	v_mfma_scale_f32_16x16x128_f8f6f4 v[78:81], v[2:9], v[220:227], v[78:81], v185, v185 op_sel_hi:[0,0,0]
	v_mfma_scale_f32_16x16x128_f8f6f4 v[74:77], v[10:17], v[220:227], v[74:77], v185, v185 op_sel_hi:[0,0,0]
	v_mfma_scale_f32_16x16x128_f8f6f4 v[62:65], v[2:9], v[228:235], v[62:65], v185, v185 op_sel_hi:[0,0,0]
	v_mfma_scale_f32_16x16x128_f8f6f4 v[58:61], v[10:17], v[228:235], v[58:61], v185, v185 op_sel_hi:[0,0,0]
	v_mfma_scale_f32_16x16x128_f8f6f4 v[46:49], v[2:9], v[236:243], v[46:49], v185, v185 op_sel_hi:[0,0,0]
	v_mfma_scale_f32_16x16x128_f8f6f4 v[42:45], v[10:17], v[236:243], v[42:45], v185, v185 op_sel_hi:[0,0,0]
	s_setprio 0
	s_setprio 1
	v_mfma_scale_f32_16x16x128_f8f6f4 v[86:89], v[18:25], v[186:193], v[86:89], v185, v185 op_sel_hi:[0,0,0]
	v_mfma_scale_f32_16x16x128_f8f6f4 v[82:85], v[26:33], v[186:193], v[82:85], v185, v185 op_sel_hi:[0,0,0]
	v_mfma_scale_f32_16x16x128_f8f6f4 v[70:73], v[18:25], v[220:227], v[70:73], v185, v185 op_sel_hi:[0,0,0]
	v_mfma_scale_f32_16x16x128_f8f6f4 v[66:69], v[26:33], v[220:227], v[66:69], v185, v185 op_sel_hi:[0,0,0]
	v_mfma_scale_f32_16x16x128_f8f6f4 v[54:57], v[18:25], v[228:235], v[54:57], v185, v185 op_sel_hi:[0,0,0]
	v_mfma_scale_f32_16x16x128_f8f6f4 v[50:53], v[26:33], v[228:235], v[50:53], v185, v185 op_sel_hi:[0,0,0]
	v_mfma_scale_f32_16x16x128_f8f6f4 v[38:41], v[18:25], v[236:243], v[38:41], v185, v185 op_sel_hi:[0,0,0]
	v_mfma_scale_f32_16x16x128_f8f6f4 v[34:37], v[26:33], v[236:243], v[34:37], v185, v185 op_sel_hi:[0,0,0]
	s_setprio 0
	s_barrier
	s_add_i32 s48, s48, 2
	s_add_u32 s46, s46, 0x700000
	s_addc_u32 s47, s47, 0
	s_add_u32 s24, s24, 0x200000
	s_addc_u32 s25, s25, 0
	s_cmp_gt_u32 s48, 29
	s_cbranch_scc0 .LBB0_2480
	s_and_b64 vcc, exec, s[8:9]
	s_cbranch_vccz .LBB0_2483
	s_barrier

.LBB0_2714:
	ds_read_b128 v[18:21], v180
	ds_read_b128 v[22:25], v180 offset:1024
	ds_read_b128 v[26:29], v180 offset:2048
	ds_read_b128 v[30:33], v180 offset:3072
	s_waitcnt lgkmcnt(0)
	ds_read_b128 v[2:5], v181
	ds_read_b128 v[6:9], v181 offset:1024
	ds_read_b128 v[10:13], v181 offset:2048
	ds_read_b128 v[14:17], v181 offset:3072
	s_add_u32 s24, s22, 0xfc000
	s_addc_u32 s25, s23, 0
	s_cmpk_eq_i32 s44, 0x6c
	s_cselect_b32 s28, s17, s24
	s_cselect_b32 s29, s5, s25
	s_cselect_b32 s26, s41, s42
	s_cselect_b32 s27, s15, s43
	s_add_u32 s24, s28, 0x100000
	s_addc_u32 s25, s29, 0
	s_add_i32 m0, s1, 0xc000
	ds_read_b128 v[184:187], v182
	ds_read_b128 v[188:191], v182 offset:1024
	ds_read_b128 v[192:195], v182 offset:2048
	ds_read_b128 v[196:199], v182 offset:3072
	ds_read_b128 v[220:223], v182 offset:4096
	ds_read_b128 v[224:227], v182 offset:5120
	ds_read_b128 v[228:231], v182 offset:6144
	ds_read_b128 v[232:235], v182 offset:7168
	global_load_lds_dwordx4 v170, s[22:23]
	s_add_i32 m0, s1, 0xe000
	s_nop 0
	global_load_lds_dwordx4 v172, s[22:23]
	s_waitcnt vmcnt(8)
	s_waitcnt lgkmcnt(0)
	s_barrier
	s_setprio 1
	s_waitcnt lgkmcnt(0)
	v_mfma_scale_f32_16x16x128_f8f6f4 v[158:161], v[18:25], v[184:191], v[158:161], v183, v183 op_sel_hi:[0,0,0]
	v_mfma_scale_f32_16x16x128_f8f6f4 v[154:157], v[26:33], v[184:191], v[154:157], v183, v183 op_sel_hi:[0,0,0]
	v_mfma_scale_f32_16x16x128_f8f6f4 v[142:145], v[18:25], v[192:199], v[142:145], v183, v183 op_sel_hi:[0,0,0]
	v_mfma_scale_f32_16x16x128_f8f6f4 v[138:141], v[26:33], v[192:199], v[138:141], v183, v183 op_sel_hi:[0,0,0]
	v_mfma_scale_f32_16x16x128_f8f6f4 v[126:129], v[18:25], v[220:227], v[126:129], v183, v183 op_sel_hi:[0,0,0]
	v_mfma_scale_f32_16x16x128_f8f6f4 v[122:125], v[26:33], v[220:227], v[122:125], v183, v183 op_sel_hi:[0,0,0]
	v_mfma_scale_f32_16x16x128_f8f6f4 v[110:113], v[18:25], v[228:235], v[110:113], v183, v183 op_sel_hi:[0,0,0]
	v_mfma_scale_f32_16x16x128_f8f6f4 v[106:109], v[26:33], v[228:235], v[106:109], v183, v183 op_sel_hi:[0,0,0]
	s_setprio 0
	s_setprio 1
	v_mfma_scale_f32_16x16x128_f8f6f4 v[150:153], v[2:9], v[184:191], v[150:153], v183, v183 op_sel_hi:[0,0,0]
	v_mfma_scale_f32_16x16x128_f8f6f4 v[146:149], v[10:17], v[184:191], v[146:149], v183, v183 op_sel_hi:[0,0,0]
	v_mfma_scale_f32_16x16x128_f8f6f4 v[134:137], v[2:9], v[192:199], v[134:137], v183, v183 op_sel_hi:[0,0,0]
	v_mfma_scale_f32_16x16x128_f8f6f4 v[130:133], v[10:17], v[192:199], v[130:133], v183, v183 op_sel_hi:[0,0,0]
	v_mfma_scale_f32_16x16x128_f8f6f4 v[118:121], v[2:9], v[220:227], v[118:121], v183, v183 op_sel_hi:[0,0,0]
	v_mfma_scale_f32_16x16x128_f8f6f4 v[114:117], v[10:17], v[220:227], v[114:117], v183, v183 op_sel_hi:[0,0,0]
	v_mfma_scale_f32_16x16x128_f8f6f4 v[102:105], v[2:9], v[228:235], v[102:105], v183, v183 op_sel_hi:[0,0,0]
	v_mfma_scale_f32_16x16x128_f8f6f4 v[98:101], v[10:17], v[228:235], v[98:101], v183, v183 op_sel_hi:[0,0,0]
	s_setprio 0
	s_barrier
	s_add_i32 s45, s38, s0
	s_mov_b32 m0, s45
	ds_read_b128 v[184:187], v182 offset:16384
	ds_read_b128 v[188:191], v182 offset:17408
	ds_read_b128 v[192:195], v182 offset:18432
	ds_read_b128 v[196:199], v182 offset:19456
	ds_read_b128 v[220:223], v182 offset:20480
	ds_read_b128 v[224:227], v182 offset:21504
	ds_read_b128 v[228:231], v182 offset:22528
	ds_read_b128 v[232:235], v182 offset:23552
	global_load_lds_dwordx4 v164, s[26:27]
	s_add_i32 m0, s45, 0x2000
	s_add_u32 s46, s26, 0x4000
	s_addc_u32 s47, s27, 0
	s_add_i32 s45, s39, s0
	global_load_lds_dwordx4 v168, s[26:27]
	s_mov_b32 m0, s45
	s_nop 0
	global_load_lds_dwordx4 v164, s[46:47]
	s_add_i32 m0, s45, 0x2000
	s_nop 0
	global_load_lds_dwordx4 v168, s[46:47]
	s_mov_b32 m0, s1
	s_nop 0
	global_load_lds_dwordx4 v162, s[28:29]
	s_mov_b32 m0, s13
	s_nop 0
	global_load_lds_dwordx4 v166, s[28:29]
	s_waitcnt vmcnt(8)
	s_waitcnt lgkmcnt(0)
	s_barrier
	s_setprio 1
	s_waitcnt lgkmcnt(0)
	v_mfma_scale_f32_16x16x128_f8f6f4 v[94:97], v[18:25], v[184:191], v[94:97], v183, v183 op_sel_hi:[0,0,0]
	v_mfma_scale_f32_16x16x128_f8f6f4 v[90:93], v[26:33], v[184:191], v[90:93], v183, v183 op_sel_hi:[0,0,0]
	v_mfma_scale_f32_16x16x128_f8f6f4 v[78:81], v[18:25], v[192:199], v[78:81], v183, v183 op_sel_hi:[0,0,0]
	v_mfma_scale_f32_16x16x128_f8f6f4 v[74:77], v[26:33], v[192:199], v[74:77], v183, v183 op_sel_hi:[0,0,0]
	v_mfma_scale_f32_16x16x128_f8f6f4 v[62:65], v[18:25], v[220:227], v[62:65], v183, v183 op_sel_hi:[0,0,0]
	v_mfma_scale_f32_16x16x128_f8f6f4 v[58:61], v[26:33], v[220:227], v[58:61], v183, v183 op_sel_hi:[0,0,0]
	v_mfma_scale_f32_16x16x128_f8f6f4 v[46:49], v[18:25], v[228:235], v[46:49], v183, v183 op_sel_hi:[0,0,0]
	v_mfma_scale_f32_16x16x128_f8f6f4 v[42:45], v[26:33], v[228:235], v[42:45], v183, v183 op_sel_hi:[0,0,0]
	s_setprio 0
	s_setprio 1
	v_mfma_scale_f32_16x16x128_f8f6f4 v[86:89], v[2:9], v[184:191], v[86:89], v183, v183 op_sel_hi:[0,0,0]
	v_mfma_scale_f32_16x16x128_f8f6f4 v[82:85], v[10:17], v[184:191], v[82:85], v183, v183 op_sel_hi:[0,0,0]
	v_mfma_scale_f32_16x16x128_f8f6f4 v[70:73], v[2:9], v[192:199], v[70:73], v183, v183 op_sel_hi:[0,0,0]
	v_mfma_scale_f32_16x16x128_f8f6f4 v[66:69], v[10:17], v[192:199], v[66:69], v183, v183 op_sel_hi:[0,0,0]
	v_mfma_scale_f32_16x16x128_f8f6f4 v[54:57], v[2:9], v[220:227], v[54:57], v183, v183 op_sel_hi:[0,0,0]
	v_mfma_scale_f32_16x16x128_f8f6f4 v[50:53], v[10:17], v[220:227], v[50:53], v183, v183 op_sel_hi:[0,0,0]
	v_mfma_scale_f32_16x16x128_f8f6f4 v[38:41], v[2:9], v[228:235], v[38:41], v183, v183 op_sel_hi:[0,0,0]
	v_mfma_scale_f32_16x16x128_f8f6f4 v[34:37], v[10:17], v[228:235], v[34:37], v183, v183 op_sel_hi:[0,0,0]
	s_setprio 0
	s_barrier
	s_add_i32 s45, 0, 0x18000
	s_add_i32 s46, 0, 0x1c000
	v_add_u32_e32 v14, s45, v179
	v_add_u32_e32 v30, s46, v179
	ds_read_b128 v[2:5], v14
	ds_read_b128 v[6:9], v14 offset:1024
	ds_read_b128 v[10:13], v14 offset:2048
	ds_read_b128 v[14:17], v14 offset:3072
	ds_read_b128 v[18:21], v30
	ds_read_b128 v[22:25], v30 offset:1024
	ds_read_b128 v[26:29], v30 offset:2048
	ds_read_b128 v[30:33], v30 offset:3072
	s_add_u32 s28, s28, 0x4000
	s_addc_u32 s29, s29, 0
	s_mov_b32 m0, s30
	ds_read_b128 v[184:187], v182 offset:32768
	ds_read_b128 v[188:191], v182 offset:33792
	ds_read_b128 v[192:195], v182 offset:34816
	ds_read_b128 v[196:199], v182 offset:35840
	ds_read_b128 v[220:223], v182 offset:36864
	ds_read_b128 v[224:227], v182 offset:37888
	ds_read_b128 v[228:231], v182 offset:38912
	ds_read_b128 v[232:235], v182 offset:39936
	global_load_lds_dwordx4 v162, s[28:29]
	s_mov_b32 m0, s31
	s_nop 0
	global_load_lds_dwordx4 v166, s[28:29]
	s_waitcnt vmcnt(8)
	s_waitcnt lgkmcnt(0)
	s_barrier
	s_setprio 1
	s_waitcnt lgkmcnt(0)
	v_mfma_scale_f32_16x16x128_f8f6f4 v[158:161], v[2:9], v[184:191], v[158:161], v183, v183 op_sel_hi:[0,0,0]
	v_mfma_scale_f32_16x16x128_f8f6f4 v[154:157], v[10:17], v[184:191], v[154:157], v183, v183 op_sel_hi:[0,0,0]
	v_mfma_scale_f32_16x16x128_f8f6f4 v[142:145], v[2:9], v[192:199], v[142:145], v183, v183 op_sel_hi:[0,0,0]
	v_mfma_scale_f32_16x16x128_f8f6f4 v[138:141], v[10:17], v[192:199], v[138:141], v183, v183 op_sel_hi:[0,0,0]
	v_mfma_scale_f32_16x16x128_f8f6f4 v[126:129], v[2:9], v[220:227], v[126:129], v183, v183 op_sel_hi:[0,0,0]
	v_mfma_scale_f32_16x16x128_f8f6f4 v[122:125], v[10:17], v[220:227], v[122:125], v183, v183 op_sel_hi:[0,0,0]
	v_mfma_scale_f32_16x16x128_f8f6f4 v[110:113], v[2:9], v[228:235], v[110:113], v183, v183 op_sel_hi:[0,0,0]
	v_mfma_scale_f32_16x16x128_f8f6f4 v[106:109], v[10:17], v[228:235], v[106:109], v183, v183 op_sel_hi:[0,0,0]
	s_setprio 0
	s_setprio 1
	v_mfma_scale_f32_16x16x128_f8f6f4 v[150:153], v[18:25], v[184:191], v[150:153], v183, v183 op_sel_hi:[0,0,0]
	v_mfma_scale_f32_16x16x128_f8f6f4 v[146:149], v[26:33], v[184:191], v[146:149], v183, v183 op_sel_hi:[0,0,0]
	v_mfma_scale_f32_16x16x128_f8f6f4 v[134:137], v[18:25], v[192:199], v[134:137], v183, v183 op_sel_hi:[0,0,0]
	v_mfma_scale_f32_16x16x128_f8f6f4 v[130:133], v[26:33], v[192:199], v[130:133], v183, v183 op_sel_hi:[0,0,0]
	v_mfma_scale_f32_16x16x128_f8f6f4 v[118:121], v[18:25], v[220:227], v[118:121], v183, v183 op_sel_hi:[0,0,0]
	v_mfma_scale_f32_16x16x128_f8f6f4 v[114:117], v[26:33], v[220:227], v[114:117], v183, v183 op_sel_hi:[0,0,0]
	v_mfma_scale_f32_16x16x128_f8f6f4 v[102:105], v[18:25], v[228:235], v[102:105], v183, v183 op_sel_hi:[0,0,0]
	v_mfma_scale_f32_16x16x128_f8f6f4 v[98:101], v[26:33], v[228:235], v[98:101], v183, v183 op_sel_hi:[0,0,0]
	s_setprio 0
	s_barrier
	s_add_u32 s28, s26, 0x80000
	s_addc_u32 s29, s27, 0
	s_add_i32 s45, s45, s0
	s_mov_b32 m0, s45
	ds_read_b128 v[184:187], v182 offset:49152
	ds_read_b128 v[188:191], v182 offset:50176
	ds_read_b128 v[192:195], v182 offset:51200
	ds_read_b128 v[196:199], v182 offset:52224
	ds_read_b128 v[220:223], v182 offset:53248
	ds_read_b128 v[224:227], v182 offset:54272
	ds_read_b128 v[228:231], v182 offset:55296
	ds_read_b128 v[232:235], v182 offset:56320
	global_load_lds_dwordx4 v164, s[28:29]
	s_add_i32 m0, s45, 0x2000
	s_add_u32 s26, s26, 0x84000
	s_addc_u32 s27, s27, 0
	global_load_lds_dwordx4 v168, s[28:29]
	s_add_i32 s28, s46, s0
	s_mov_b32 m0, s28
	s_nop 0
	global_load_lds_dwordx4 v164, s[26:27]
	s_add_i32 m0, s28, 0x2000
	s_nop 0
	global_load_lds_dwordx4 v168, s[26:27]
	s_mov_b32 m0, s36
	s_nop 0
	global_load_lds_dwordx4 v162, s[24:25]
	s_mov_b32 m0, s37
	s_nop 0
	global_load_lds_dwordx4 v166, s[24:25]
	s_waitcnt vmcnt(8)
	s_waitcnt lgkmcnt(0)
	s_barrier
	s_setprio 1
	s_waitcnt lgkmcnt(0)
	v_mfma_scale_f32_16x16x128_f8f6f4 v[94:97], v[2:9], v[184:191], v[94:97], v183, v183 op_sel_hi:[0,0,0]
	v_mfma_scale_f32_16x16x128_f8f6f4 v[90:93], v[10:17], v[184:191], v[90:93], v183, v183 op_sel_hi:[0,0,0]
	v_mfma_scale_f32_16x16x128_f8f6f4 v[78:81], v[2:9], v[192:199], v[78:81], v183, v183 op_sel_hi:[0,0,0]
	v_mfma_scale_f32_16x16x128_f8f6f4 v[74:77], v[10:17], v[192:199], v[74:77], v183, v183 op_sel_hi:[0,0,0]
	v_mfma_scale_f32_16x16x128_f8f6f4 v[62:65], v[2:9], v[220:227], v[62:65], v183, v183 op_sel_hi:[0,0,0]
	v_mfma_scale_f32_16x16x128_f8f6f4 v[58:61], v[10:17], v[220:227], v[58:61], v183, v183 op_sel_hi:[0,0,0]
	v_mfma_scale_f32_16x16x128_f8f6f4 v[46:49], v[2:9], v[228:235], v[46:49], v183, v183 op_sel_hi:[0,0,0]
	v_mfma_scale_f32_16x16x128_f8f6f4 v[42:45], v[10:17], v[228:235], v[42:45], v183, v183 op_sel_hi:[0,0,0]
	s_setprio 0
	s_setprio 1
	v_mfma_scale_f32_16x16x128_f8f6f4 v[86:89], v[18:25], v[184:191], v[86:89], v183, v183 op_sel_hi:[0,0,0]
	v_mfma_scale_f32_16x16x128_f8f6f4 v[82:85], v[26:33], v[184:191], v[82:85], v183, v183 op_sel_hi:[0,0,0]
	v_mfma_scale_f32_16x16x128_f8f6f4 v[70:73], v[18:25], v[192:199], v[70:73], v183, v183 op_sel_hi:[0,0,0]
	v_mfma_scale_f32_16x16x128_f8f6f4 v[66:69], v[26:33], v[192:199], v[66:69], v183, v183 op_sel_hi:[0,0,0]
	v_mfma_scale_f32_16x16x128_f8f6f4 v[54:57], v[18:25], v[220:227], v[54:57], v183, v183 op_sel_hi:[0,0,0]
	v_mfma_scale_f32_16x16x128_f8f6f4 v[50:53], v[26:33], v[220:227], v[50:53], v183, v183 op_sel_hi:[0,0,0]
	v_mfma_scale_f32_16x16x128_f8f6f4 v[38:41], v[18:25], v[228:235], v[38:41], v183, v183 op_sel_hi:[0,0,0]
	v_mfma_scale_f32_16x16x128_f8f6f4 v[34:37], v[26:33], v[228:235], v[34:37], v183, v183 op_sel_hi:[0,0,0]
	s_setprio 0
	s_barrier
	s_add_i32 s44, s44, 2
	s_add_u32 s42, s42, 0x100000
	s_addc_u32 s43, s43, 0
	s_add_u32 s22, s22, 0x200000
	s_addc_u32 s23, s23, 0
	s_cmpk_gt_u32 s44, 0x6d
	s_cbranch_scc0 .LBB0_2714
	s_and_b64 vcc, exec, s[10:11]
	s_cbranch_vccz .LBB0_2717
	s_barrier
